# hand-written MoBA (run right after GEMM1, compact K/V/Q/Z layout via custom GEMM1 epilogue, GEMM1 tile order MoBA cols last), hand-written chunk-prep S2 (KK^T/QK^T) and S3 (forward substitution)
# speedup vs baseline: 1.0492x; 1.0201x over previous
.LBB0_212:
	s_or_b64 exec, exec, s[2:3]
	v_mov_b32_e32 v8, v198
	s_cmpk_lt_i32 s96, 0xc00
	s_waitcnt lgkmcnt(0)
	s_barrier
	s_cselect_b64 s[2:3], -1, 0
	s_cmpk_gt_i32 s96, 0xbff
	v_readfirstlane_b32 s4, v8
	s_cbranch_scc1 .LBB0_214
	s_ashr_i32 s0, s96, 31
	s_lshr_b32 s0, s0, 29
	s_add_i32 s0, s96, s0
	s_ashr_i32 s1, s0, 3
	s_and_b32 s0, s0, -8
	s_sub_i32 s0, s96, s0
	s_cmp_lt_i32 s0, 0
	s_movk_i32 s5, 0x181
	s_cselect_b32 s5, s5, 0x180
	s_mul_i32 s0, s5, s0
	s_add_i32 s0, s0, s1
	s_mul_hi_i32 s1, s0, 0x2aaaaaab
	s_lshr_b32 s5, s1, 31
	s_ashr_i32 s1, s1, 5
	s_add_i32 s1, s1, s5
	s_lshl_b32 s5, s1, 2
	s_mulk_i32 s1, 0xc0
	s_sub_i32 s0, s0, s1
	s_sext_i32_i16 s1, s0
	s_bfe_u32 s1, s1, 0x2001d
	s_add_i32 s1, s0, s1
	s_sext_i32_i16 s6, s1
	s_and_b32 s1, s1, 0xfffc
	s_sub_i32 s0, s0, s1
	s_sext_i32_i16 s0, s0
	s_add_i32 s24, s5, s0
	s_ashr_i32 s22, s6, 2
	s_and_b32 s0, s96, 7
	s_lshr_b32 s1, s96, 3
	s_lshr_b32 s5, s1, 7
	s_lshl_b32 s5, s5, 2
	s_lshl_b32 s24, s0, 3
	s_add_u32 s24, s24, s5
	s_and_b32 s5, s1, 3
	s_add_u32 s24, s24, s5
	s_and_b32 s5, s1, 127
	s_lshr_b32 s22, s5, 2
	s_add_u32 s5, s22, 16
	s_cmp_lt_u32 s22, 16
	s_cselect_b32 s22, s22, s5

.LBB0_220:
	s_add_i32 s33, s33, 1
	s_mul_i32 s4, s33, s38
	s_mul_hi_u32 s5, s33, s39
	s_add_i32 s5, s5, s4
	s_mul_i32 s4, s33, s39
	s_add_u32 s18, s4, s96
	s_addc_u32 s19, s5, s56
	v_cmp_gt_i64_e32 vcc, s[18:19], v[156:157]
	v_cmp_lt_i64_e64 s[4:5], s[18:19], v[154:155]
	s_cbranch_vccnz .LBB0_222
	s_ashr_i32 s14, s18, 31
	s_lshr_b32 s14, s14, 29
	s_add_i32 s14, s18, s14
	s_ashr_i32 s15, s14, 3
	s_and_b32 s14, s14, -8
	s_sub_i32 s14, s18, s14
	s_cmp_lt_i32 s14, 0
	s_movk_i32 s16, 0x181
	s_cselect_b32 s16, s16, 0x180
	s_mul_i32 s14, s16, s14
	s_add_i32 s14, s14, s15
	s_mul_hi_i32 s15, s14, 0x2aaaaaab
	s_lshr_b32 s16, s15, 31
	s_ashr_i32 s15, s15, 5
	s_add_i32 s15, s15, s16
	s_lshl_b32 s16, s15, 2
	s_sub_i32 s17, 64, s16
	s_min_i32 s17, s17, 4
	s_abs_i32 s18, s17
	v_cvt_f32_u32_e32 v0, s18
	s_sub_i32 s20, 0, s18
	s_mulk_i32 s15, 0xc0
	s_sub_i32 s15, s14, s15
	v_rcp_iflag_f32_e32 v0, v0
	s_abs_i32 s14, s15
	s_xor_b32 s19, s15, s17
	s_ashr_i32 s19, s19, 31
	v_mul_f32_e32 v0, 0x4f7ffffe, v0
	v_cvt_u32_f32_e32 v0, v0
	s_nop 0
	v_readfirstlane_b32 s21, v0
	s_mul_i32 s20, s20, s21
	s_mul_hi_u32 s20, s21, s20
	s_add_i32 s21, s21, s20
	s_mul_hi_u32 s20, s14, s21
	s_mul_i32 s21, s20, s18
	s_sub_i32 s14, s14, s21
	s_add_i32 s28, s20, 1
	s_sub_i32 s21, s14, s18
	s_cmp_ge_u32 s14, s18
	s_cselect_b32 s20, s28, s20
	s_cselect_b32 s14, s21, s14
	s_add_i32 s21, s20, 1
	s_cmp_ge_u32 s14, s18
	s_cselect_b32 s14, s21, s20
	s_xor_b32 s14, s14, s19
	s_sub_i32 s14, s14, s19
	s_mul_i32 s17, s14, s17
	s_sub_i32 s15, s15, s17
	s_add_i32 s16, s15, s16
	s_and_b32 s15, s96, 7
	s_lshr_b32 s17, s96, 3
	s_cmp_lt_u32 s33, 8
	s_cbranch_scc0 .Lord1_b
	s_lshl_b32 s18, s33, 5
	s_add_u32 s17, s17, s18
	s_lshr_b32 s18, s17, 7
	s_lshl_b32 s18, s18, 2
	s_lshl_b32 s16, s15, 3
	s_add_u32 s16, s16, s18
	s_and_b32 s18, s17, 3
	s_add_u32 s16, s16, s18
	s_and_b32 s18, s17, 127
	s_lshr_b32 s14, s18, 2
	s_add_u32 s18, s14, 16
	s_cmp_lt_u32 s14, 16
	s_cselect_b32 s14, s14, s18
	s_branch .Lord1_d
.Lord1_b:
	s_sub_u32 s18, s33, 8
	s_lshl_b32 s18, s18, 5
	s_add_u32 s17, s17, s18
	s_lshr_b32 s18, s17, 6
	s_lshl_b32 s18, s18, 2
	s_lshl_b32 s16, s15, 3
	s_add_u32 s16, s16, s18
	s_and_b32 s18, s17, 3
	s_add_u32 s16, s16, s18
	s_and_b32 s18, s17, 63
	s_lshr_b32 s14, s18, 2
	s_add_u32 s14, s14, 16
.Lord1_d:
.LBB0_222:
	s_ashr_i32 s17, s16, 31
	s_lshl_b64 s[18:19], s[16:17], 20
	s_add_u32 s18, s64, s18
	s_addc_u32 s19, s65, s19
	s_and_b64 s[20:21], s[4:5], exec
	s_cselect_b32 s17, s19, s7
	s_cselect_b32 s59, s18, s6
	s_ashr_i32 s15, s14, 31
	s_lshl_b64 s[20:21], s[14:15], 20
	s_add_u32 s20, s68, s20
	s_addc_u32 s21, s69, s21
	s_and_b64 s[28:29], s[4:5], exec
	s_cselect_b32 s15, s21, s27
	s_cselect_b32 s90, s20, s26
	s_add_u32 s6, s6, 0x80080
	s_addc_u32 s7, s7, 0
	s_add_u32 s91, s26, 0x100
	v_mov_b32_e32 v0, 0
	s_addc_u32 s94, s27, 0
	s_mov_b32 s95, -2
	v_mov_b32_e32 v1, v0
	v_mov_b32_e32 v2, v0
	v_mov_b32_e32 v3, v0
	v_mov_b32_e32 v8, v0
	v_mov_b32_e32 v9, v0
	v_mov_b32_e32 v10, v0
	v_mov_b32_e32 v11, v0
	v_mov_b32_e32 v16, v0
	v_mov_b32_e32 v17, v0
	v_mov_b32_e32 v18, v0
	v_mov_b32_e32 v19, v0
	v_mov_b32_e32 v24, v0
	v_mov_b32_e32 v25, v0
	v_mov_b32_e32 v26, v0
	v_mov_b32_e32 v27, v0
	v_mov_b32_e32 v32, v0
	v_mov_b32_e32 v33, v0
	v_mov_b32_e32 v34, v0
	v_mov_b32_e32 v35, v0
	v_mov_b32_e32 v40, v0
	v_mov_b32_e32 v41, v0
	v_mov_b32_e32 v42, v0
	v_mov_b32_e32 v43, v0
	v_mov_b32_e32 v48, v0
	v_mov_b32_e32 v49, v0
	v_mov_b32_e32 v50, v0
	v_mov_b32_e32 v51, v0
	v_mov_b32_e32 v56, v0
	v_mov_b32_e32 v57, v0
	v_mov_b32_e32 v58, v0
	v_mov_b32_e32 v59, v0
	v_mov_b32_e32 v4, v0
	v_mov_b32_e32 v5, v0
	v_mov_b32_e32 v6, v0
	v_mov_b32_e32 v7, v0
	v_mov_b32_e32 v12, v0
	v_mov_b32_e32 v13, v0
	v_mov_b32_e32 v14, v0
	v_mov_b32_e32 v15, v0
	v_mov_b32_e32 v20, v0
	v_mov_b32_e32 v21, v0
	v_mov_b32_e32 v22, v0
	v_mov_b32_e32 v23, v0
	v_mov_b32_e32 v28, v0
	v_mov_b32_e32 v29, v0
	v_mov_b32_e32 v30, v0
	v_mov_b32_e32 v31, v0
	v_mov_b32_e32 v36, v0
	v_mov_b32_e32 v37, v0
	v_mov_b32_e32 v38, v0
	v_mov_b32_e32 v39, v0
	v_mov_b32_e32 v44, v0
	v_mov_b32_e32 v45, v0
	v_mov_b32_e32 v46, v0
	v_mov_b32_e32 v47, v0
	v_mov_b32_e32 v52, v0
	v_mov_b32_e32 v53, v0
	v_mov_b32_e32 v54, v0
	v_mov_b32_e32 v55, v0
	v_mov_b32_e32 v60, v0
	v_mov_b32_e32 v61, v0
	v_mov_b32_e32 v62, v0
	v_mov_b32_e32 v63, v0
	v_mov_b32_e32 v64, v0
	v_mov_b32_e32 v65, v0
	v_mov_b32_e32 v66, v0
	v_mov_b32_e32 v67, v0
	v_mov_b32_e32 v72, v0
	v_mov_b32_e32 v73, v0
	v_mov_b32_e32 v74, v0
	v_mov_b32_e32 v75, v0
	v_mov_b32_e32 v80, v0
	v_mov_b32_e32 v81, v0
	v_mov_b32_e32 v82, v0
	v_mov_b32_e32 v83, v0
	v_mov_b32_e32 v88, v0
	v_mov_b32_e32 v89, v0
	v_mov_b32_e32 v90, v0
	v_mov_b32_e32 v91, v0
	v_mov_b32_e32 v96, v0
	v_mov_b32_e32 v97, v0
	v_mov_b32_e32 v98, v0
	v_mov_b32_e32 v99, v0
	v_mov_b32_e32 v104, v0
	v_mov_b32_e32 v105, v0
	v_mov_b32_e32 v106, v0
	v_mov_b32_e32 v107, v0
	v_mov_b32_e32 v112, v0
	v_mov_b32_e32 v113, v0
	v_mov_b32_e32 v114, v0
	v_mov_b32_e32 v115, v0
	v_mov_b32_e32 v120, v0
	v_mov_b32_e32 v121, v0
	v_mov_b32_e32 v122, v0
	v_mov_b32_e32 v123, v0
	v_mov_b32_e32 v68, v0
	v_mov_b32_e32 v69, v0
	v_mov_b32_e32 v70, v0
	v_mov_b32_e32 v71, v0
	v_mov_b32_e32 v76, v0
	v_mov_b32_e32 v77, v0
	v_mov_b32_e32 v78, v0
	v_mov_b32_e32 v79, v0
	v_mov_b32_e32 v84, v0
	v_mov_b32_e32 v85, v0
	v_mov_b32_e32 v86, v0
	v_mov_b32_e32 v87, v0
	v_mov_b32_e32 v92, v0
	v_mov_b32_e32 v93, v0
	v_mov_b32_e32 v94, v0
	v_mov_b32_e32 v95, v0
	v_mov_b32_e32 v100, v0
	v_mov_b32_e32 v101, v0
	v_mov_b32_e32 v102, v0
	v_mov_b32_e32 v103, v0
	v_mov_b32_e32 v108, v0
	v_mov_b32_e32 v109, v0
	v_mov_b32_e32 v110, v0
	v_mov_b32_e32 v111, v0
	v_mov_b32_e32 v116, v0
	v_mov_b32_e32 v117, v0
	v_mov_b32_e32 v118, v0
	v_mov_b32_e32 v119, v0
	v_mov_b32_e32 v124, v0
	v_mov_b32_e32 v125, v0
	v_mov_b32_e32 v126, v0
	v_mov_b32_e32 v127, v0

.LBB0_263:
	s_cmp_gt_i32 s22, 15
	s_cbranch_scc1 .Lep_moba
	s_cmp_eq_u32 s15, 12
	s_cselect_b64 s[6:7], -1, 0
	s_cmp_gt_i32 s22, 27
	s_cselect_b64 s[26:27], -1, 0
	s_or_b64 s[26:27], s[26:27], s[6:7]
	v_cndmask_b32_e64 v128, 0, 1, s[26:27]
	v_cmp_ne_u32_e64 s[6:7], 1, v128
	s_waitcnt lgkmcnt(0)
	v_mov_b64_e32 v[130:131], v[126:127]
	v_mov_b64_e32 v[134:135], v[118:119]
	s_andn2_b64 vcc, exec, s[26:27]
	v_mov_b64_e32 v[128:129], v[124:125]
	v_mov_b64_e32 v[132:133], v[116:117]
	s_cbranch_vccnz .LBB0_265
	v_mul_f32_e32 v129, 0xbfb8aa3b, v116
	v_mul_f32_e32 v130, 0xbfb8aa3b, v125
	v_exp_f32_e32 v129, v129
	v_exp_f32_e32 v130, v130
	v_mul_f32_e32 v131, 0xbfb8aa3b, v126
	v_mul_f32_e32 v133, 0xbfb8aa3b, v118
	v_add_f32_e32 v129, 1.0, v129
	v_rcp_f32_e32 v132, v129
	v_add_f32_e32 v129, 1.0, v130
	v_mul_f32_e32 v130, 0xbfb8aa3b, v117
	v_exp_f32_e32 v130, v130
	v_exp_f32_e32 v131, v131
	v_exp_f32_e32 v133, v133
	v_mul_f32_e32 v128, 0xbfb8aa3b, v124
	v_add_f32_e32 v158, 1.0, v130
	v_add_f32_e32 v130, 1.0, v131
	v_add_f32_e32 v131, 1.0, v133
	v_mul_f32_e32 v133, 0xbfb8aa3b, v127
	v_mul_f32_e32 v134, 0xbfb8aa3b, v119
	v_exp_f32_e32 v128, v128
	v_exp_f32_e32 v133, v133
	v_exp_f32_e32 v135, v134
	v_rcp_f32_e32 v134, v131
	v_add_f32_e32 v128, 1.0, v128
	v_add_f32_e32 v131, 1.0, v133
	v_add_f32_e32 v133, 1.0, v135
	v_rcp_f32_e32 v128, v128
	v_rcp_f32_e32 v129, v129
	v_rcp_f32_e32 v130, v130
	v_rcp_f32_e32 v131, v131
	v_rcp_f32_e32 v135, v133
	v_rcp_f32_e32 v133, v158
	v_pk_mul_f32 v[128:129], v[124:125], v[128:129]
	v_pk_mul_f32 v[130:131], v[126:127], v[130:131]
	v_pk_mul_f32 v[134:135], v[118:119], v[134:135]
	v_pk_mul_f32 v[132:133], v[116:117], v[132:133]

.Lep_moba:
	s_waitcnt lgkmcnt(0)
	s_lshr_b32 s6, s24, 3
	s_and_b32 s7, s24, 7
	s_sub_u32 s15, s22, 16
	s_lshr_b32 s26, s15, 2
	s_and_b32 s15, s15, 3
	s_lshl_b32 s6, s6, 11
	s_lshl_b32 s26, s26, 9
	s_add_u32 s6, s6, s26
	s_lshl_b32 s15, s15, 7
	s_add_u32 s6, s6, s15
	s_lshl_b32 s7, s7, 3
	s_add_u32 s6, s6, s7
	s_lshl_b32 s6, s6, 14
	s_add_u32 s6, s6, 0x2000
	s_add_u32 s6, s66, s6
	s_addc_u32 s7, s67, 0
	v_lshrrev_b32_e32 v158, 6, v137
	v_lshlrev_b32_e32 v158, 15, v158
	v_and_b32_e32 v159, 15, v137
	v_lshl_add_u32 v158, v159, 8, v158
	v_lshl_add_u32 v158, v148, 1, v158
	v_add_u32_e32 v159, 0x1000, v158
	s_cmp_ge_i32 s22, 28
	s_cbranch_scc1 .Lep_moba_act
	v_cvt_pk_bf16_f32 v160, v124, v125
	v_cvt_pk_bf16_f32 v161, v126, v127
	v_cvt_pk_bf16_f32 v162, v116, v117
	v_cvt_pk_bf16_f32 v163, v118, v119
	s_add_u32 s26, s6, 0x0
	s_addc_u32 s27, s7, 0
	global_store_dwordx4 v158, v[160:163], s[26:27]
	v_cvt_pk_bf16_f32 v132, v120, v121
	v_cvt_pk_bf16_f32 v133, v122, v123
	v_cvt_pk_bf16_f32 v134, v112, v113
	v_cvt_pk_bf16_f32 v135, v114, v115
	s_add_u32 s26, s6, 0x100000
	s_addc_u32 s27, s7, 0
	global_store_dwordx4 v158, v[132:135], s[26:27]
	v_cvt_pk_bf16_f32 v160, v108, v109
	v_cvt_pk_bf16_f32 v161, v110, v111
	v_cvt_pk_bf16_f32 v162, v100, v101
	v_cvt_pk_bf16_f32 v163, v102, v103
	s_add_u32 s26, s6, 0x0
	s_addc_u32 s27, s7, 0
	global_store_dwordx4 v159, v[160:163], s[26:27]
	v_cvt_pk_bf16_f32 v132, v104, v105
	v_cvt_pk_bf16_f32 v133, v106, v107
	v_cvt_pk_bf16_f32 v134, v96, v97
	v_cvt_pk_bf16_f32 v135, v98, v99
	s_add_u32 s26, s6, 0x100000
	s_addc_u32 s27, s7, 0
	global_store_dwordx4 v159, v[132:135], s[26:27]
	v_cvt_pk_bf16_f32 v160, v92, v93
	v_cvt_pk_bf16_f32 v161, v94, v95
	v_cvt_pk_bf16_f32 v162, v84, v85
	v_cvt_pk_bf16_f32 v163, v86, v87
	s_add_u32 s26, s6, 0x4000
	s_addc_u32 s27, s7, 0
	global_store_dwordx4 v158, v[160:163], s[26:27]
	v_cvt_pk_bf16_f32 v132, v88, v89
	v_cvt_pk_bf16_f32 v133, v90, v91
	v_cvt_pk_bf16_f32 v134, v80, v81
	v_cvt_pk_bf16_f32 v135, v82, v83
	s_add_u32 s26, s6, 0x104000
	s_addc_u32 s27, s7, 0
	global_store_dwordx4 v158, v[132:135], s[26:27]
	v_cvt_pk_bf16_f32 v160, v76, v77
	v_cvt_pk_bf16_f32 v161, v78, v79
	v_cvt_pk_bf16_f32 v162, v68, v69
	v_cvt_pk_bf16_f32 v163, v70, v71
	s_add_u32 s26, s6, 0x4000
	s_addc_u32 s27, s7, 0
	global_store_dwordx4 v159, v[160:163], s[26:27]
	v_cvt_pk_bf16_f32 v132, v72, v73
	v_cvt_pk_bf16_f32 v133, v74, v75
	v_cvt_pk_bf16_f32 v134, v64, v65
	v_cvt_pk_bf16_f32 v135, v66, v67
	s_add_u32 s26, s6, 0x104000
	s_addc_u32 s27, s7, 0
	global_store_dwordx4 v159, v[132:135], s[26:27]
	v_cvt_pk_bf16_f32 v160, v60, v61
	v_cvt_pk_bf16_f32 v161, v62, v63
	v_cvt_pk_bf16_f32 v162, v52, v53
	v_cvt_pk_bf16_f32 v163, v54, v55
	s_add_u32 s26, s6, 0x10000
	s_addc_u32 s27, s7, 0
	global_store_dwordx4 v158, v[160:163], s[26:27]
	v_cvt_pk_bf16_f32 v132, v56, v57
	v_cvt_pk_bf16_f32 v133, v58, v59
	v_cvt_pk_bf16_f32 v134, v48, v49
	v_cvt_pk_bf16_f32 v135, v50, v51
	s_add_u32 s26, s6, 0x110000
	s_addc_u32 s27, s7, 0
	global_store_dwordx4 v158, v[132:135], s[26:27]
	v_cvt_pk_bf16_f32 v160, v44, v45
	v_cvt_pk_bf16_f32 v161, v46, v47
	v_cvt_pk_bf16_f32 v162, v36, v37
	v_cvt_pk_bf16_f32 v163, v38, v39
	s_add_u32 s26, s6, 0x10000
	s_addc_u32 s27, s7, 0
	global_store_dwordx4 v159, v[160:163], s[26:27]
	v_cvt_pk_bf16_f32 v132, v40, v41
	v_cvt_pk_bf16_f32 v133, v42, v43
	v_cvt_pk_bf16_f32 v134, v32, v33
	v_cvt_pk_bf16_f32 v135, v34, v35
	s_add_u32 s26, s6, 0x110000
	s_addc_u32 s27, s7, 0
	global_store_dwordx4 v159, v[132:135], s[26:27]
	v_cvt_pk_bf16_f32 v160, v28, v29
	v_cvt_pk_bf16_f32 v161, v30, v31
	v_cvt_pk_bf16_f32 v162, v20, v21
	v_cvt_pk_bf16_f32 v163, v22, v23
	s_add_u32 s26, s6, 0x14000
	s_addc_u32 s27, s7, 0
	global_store_dwordx4 v158, v[160:163], s[26:27]
	v_cvt_pk_bf16_f32 v132, v24, v25
	v_cvt_pk_bf16_f32 v133, v26, v27
	v_cvt_pk_bf16_f32 v134, v16, v17
	v_cvt_pk_bf16_f32 v135, v18, v19
	s_add_u32 s26, s6, 0x114000
	s_addc_u32 s27, s7, 0
	global_store_dwordx4 v158, v[132:135], s[26:27]
	v_cvt_pk_bf16_f32 v160, v12, v13
	v_cvt_pk_bf16_f32 v161, v14, v15
	v_cvt_pk_bf16_f32 v162, v4, v5
	v_cvt_pk_bf16_f32 v163, v6, v7
	s_add_u32 s26, s6, 0x14000
	s_addc_u32 s27, s7, 0
	global_store_dwordx4 v159, v[160:163], s[26:27]
	v_cvt_pk_bf16_f32 v132, v8, v9
	v_cvt_pk_bf16_f32 v133, v10, v11
	v_cvt_pk_bf16_f32 v134, v0, v1
	v_cvt_pk_bf16_f32 v135, v2, v3
	s_add_u32 s26, s6, 0x114000
	s_addc_u32 s27, s7, 0
	global_store_dwordx4 v159, v[132:135], s[26:27]
	s_branch .LBB0_228
.Lep_moba_act:
	v_mul_f32_e32 v128, 0xbfb8aa3b, v124
	v_mul_f32_e32 v129, 0xbfb8aa3b, v125
	v_mul_f32_e32 v130, 0xbfb8aa3b, v126
	v_mul_f32_e32 v131, 0xbfb8aa3b, v127
	v_exp_f32_e32 v128, v128
	v_exp_f32_e32 v129, v129
	v_exp_f32_e32 v130, v130
	v_exp_f32_e32 v131, v131
	v_add_f32_e32 v128, 1.0, v128
	v_add_f32_e32 v129, 1.0, v129
	v_add_f32_e32 v130, 1.0, v130
	v_add_f32_e32 v131, 1.0, v131
	v_rcp_f32_e32 v128, v128
	v_rcp_f32_e32 v129, v129
	v_rcp_f32_e32 v130, v130
	v_rcp_f32_e32 v131, v131
	v_mul_f32_e32 v124, v124, v128
	v_mul_f32_e32 v125, v125, v129
	v_mul_f32_e32 v126, v126, v130
	v_mul_f32_e32 v127, v127, v131
	v_mul_f32_e32 v128, 0xbfb8aa3b, v116
	v_mul_f32_e32 v129, 0xbfb8aa3b, v117
	v_mul_f32_e32 v130, 0xbfb8aa3b, v118
	v_mul_f32_e32 v131, 0xbfb8aa3b, v119
	v_exp_f32_e32 v128, v128
	v_exp_f32_e32 v129, v129
	v_exp_f32_e32 v130, v130
	v_exp_f32_e32 v131, v131
	v_add_f32_e32 v128, 1.0, v128
	v_add_f32_e32 v129, 1.0, v129
	v_add_f32_e32 v130, 1.0, v130
	v_add_f32_e32 v131, 1.0, v131
	v_rcp_f32_e32 v128, v128
	v_rcp_f32_e32 v129, v129
	v_rcp_f32_e32 v130, v130
	v_rcp_f32_e32 v131, v131
	v_mul_f32_e32 v116, v116, v128
	v_mul_f32_e32 v117, v117, v129
	v_mul_f32_e32 v118, v118, v130
	v_mul_f32_e32 v119, v119, v131
	v_cvt_pk_bf16_f32 v160, v124, v125
	v_cvt_pk_bf16_f32 v161, v126, v127
	v_cvt_pk_bf16_f32 v162, v116, v117
	v_cvt_pk_bf16_f32 v163, v118, v119
	s_add_u32 s26, s6, 0x0
	s_addc_u32 s27, s7, 0
	global_store_dwordx4 v158, v[160:163], s[26:27]
	v_mul_f32_e32 v128, 0xbfb8aa3b, v120
	v_mul_f32_e32 v129, 0xbfb8aa3b, v121
	v_mul_f32_e32 v130, 0xbfb8aa3b, v122
	v_mul_f32_e32 v131, 0xbfb8aa3b, v123
	v_exp_f32_e32 v128, v128
	v_exp_f32_e32 v129, v129
	v_exp_f32_e32 v130, v130
	v_exp_f32_e32 v131, v131
	v_add_f32_e32 v128, 1.0, v128
	v_add_f32_e32 v129, 1.0, v129
	v_add_f32_e32 v130, 1.0, v130
	v_add_f32_e32 v131, 1.0, v131
	v_rcp_f32_e32 v128, v128
	v_rcp_f32_e32 v129, v129
	v_rcp_f32_e32 v130, v130
	v_rcp_f32_e32 v131, v131
	v_mul_f32_e32 v120, v120, v128
	v_mul_f32_e32 v121, v121, v129
	v_mul_f32_e32 v122, v122, v130
	v_mul_f32_e32 v123, v123, v131
	v_mul_f32_e32 v128, 0xbfb8aa3b, v112
	v_mul_f32_e32 v129, 0xbfb8aa3b, v113
	v_mul_f32_e32 v130, 0xbfb8aa3b, v114
	v_mul_f32_e32 v131, 0xbfb8aa3b, v115
	v_exp_f32_e32 v128, v128
	v_exp_f32_e32 v129, v129
	v_exp_f32_e32 v130, v130
	v_exp_f32_e32 v131, v131
	v_add_f32_e32 v128, 1.0, v128
	v_add_f32_e32 v129, 1.0, v129
	v_add_f32_e32 v130, 1.0, v130
	v_add_f32_e32 v131, 1.0, v131
	v_rcp_f32_e32 v128, v128
	v_rcp_f32_e32 v129, v129
	v_rcp_f32_e32 v130, v130
	v_rcp_f32_e32 v131, v131
	v_mul_f32_e32 v112, v112, v128
	v_mul_f32_e32 v113, v113, v129
	v_mul_f32_e32 v114, v114, v130
	v_mul_f32_e32 v115, v115, v131
	v_cvt_pk_bf16_f32 v132, v120, v121
	v_cvt_pk_bf16_f32 v133, v122, v123
	v_cvt_pk_bf16_f32 v134, v112, v113
	v_cvt_pk_bf16_f32 v135, v114, v115
	s_add_u32 s26, s6, 0x100000
	s_addc_u32 s27, s7, 0
	global_store_dwordx4 v158, v[132:135], s[26:27]
	v_mul_f32_e32 v128, 0xbfb8aa3b, v108
	v_mul_f32_e32 v129, 0xbfb8aa3b, v109
	v_mul_f32_e32 v130, 0xbfb8aa3b, v110
	v_mul_f32_e32 v131, 0xbfb8aa3b, v111
	v_exp_f32_e32 v128, v128
	v_exp_f32_e32 v129, v129
	v_exp_f32_e32 v130, v130
	v_exp_f32_e32 v131, v131
	v_add_f32_e32 v128, 1.0, v128
	v_add_f32_e32 v129, 1.0, v129
	v_add_f32_e32 v130, 1.0, v130
	v_add_f32_e32 v131, 1.0, v131
	v_rcp_f32_e32 v128, v128
	v_rcp_f32_e32 v129, v129
	v_rcp_f32_e32 v130, v130
	v_rcp_f32_e32 v131, v131
	v_mul_f32_e32 v108, v108, v128
	v_mul_f32_e32 v109, v109, v129
	v_mul_f32_e32 v110, v110, v130
	v_mul_f32_e32 v111, v111, v131
	v_mul_f32_e32 v128, 0xbfb8aa3b, v100
	v_mul_f32_e32 v129, 0xbfb8aa3b, v101
	v_mul_f32_e32 v130, 0xbfb8aa3b, v102
	v_mul_f32_e32 v131, 0xbfb8aa3b, v103
	v_exp_f32_e32 v128, v128
	v_exp_f32_e32 v129, v129
	v_exp_f32_e32 v130, v130
	v_exp_f32_e32 v131, v131
	v_add_f32_e32 v128, 1.0, v128
	v_add_f32_e32 v129, 1.0, v129
	v_add_f32_e32 v130, 1.0, v130
	v_add_f32_e32 v131, 1.0, v131
	v_rcp_f32_e32 v128, v128
	v_rcp_f32_e32 v129, v129
	v_rcp_f32_e32 v130, v130
	v_rcp_f32_e32 v131, v131
	v_mul_f32_e32 v100, v100, v128
	v_mul_f32_e32 v101, v101, v129
	v_mul_f32_e32 v102, v102, v130
	v_mul_f32_e32 v103, v103, v131
	v_cvt_pk_bf16_f32 v160, v108, v109
	v_cvt_pk_bf16_f32 v161, v110, v111
	v_cvt_pk_bf16_f32 v162, v100, v101
	v_cvt_pk_bf16_f32 v163, v102, v103
	s_add_u32 s26, s6, 0x0
	s_addc_u32 s27, s7, 0
	global_store_dwordx4 v159, v[160:163], s[26:27]
	v_mul_f32_e32 v128, 0xbfb8aa3b, v104
	v_mul_f32_e32 v129, 0xbfb8aa3b, v105
	v_mul_f32_e32 v130, 0xbfb8aa3b, v106
	v_mul_f32_e32 v131, 0xbfb8aa3b, v107
	v_exp_f32_e32 v128, v128
	v_exp_f32_e32 v129, v129
	v_exp_f32_e32 v130, v130
	v_exp_f32_e32 v131, v131
	v_add_f32_e32 v128, 1.0, v128
	v_add_f32_e32 v129, 1.0, v129
	v_add_f32_e32 v130, 1.0, v130
	v_add_f32_e32 v131, 1.0, v131
	v_rcp_f32_e32 v128, v128
	v_rcp_f32_e32 v129, v129
	v_rcp_f32_e32 v130, v130
	v_rcp_f32_e32 v131, v131
	v_mul_f32_e32 v104, v104, v128
	v_mul_f32_e32 v105, v105, v129
	v_mul_f32_e32 v106, v106, v130
	v_mul_f32_e32 v107, v107, v131
	v_mul_f32_e32 v128, 0xbfb8aa3b, v96
	v_mul_f32_e32 v129, 0xbfb8aa3b, v97
	v_mul_f32_e32 v130, 0xbfb8aa3b, v98
	v_mul_f32_e32 v131, 0xbfb8aa3b, v99
	v_exp_f32_e32 v128, v128
	v_exp_f32_e32 v129, v129
	v_exp_f32_e32 v130, v130
	v_exp_f32_e32 v131, v131
	v_add_f32_e32 v128, 1.0, v128
	v_add_f32_e32 v129, 1.0, v129
	v_add_f32_e32 v130, 1.0, v130
	v_add_f32_e32 v131, 1.0, v131
	v_rcp_f32_e32 v128, v128
	v_rcp_f32_e32 v129, v129
	v_rcp_f32_e32 v130, v130
	v_rcp_f32_e32 v131, v131
	v_mul_f32_e32 v96, v96, v128
	v_mul_f32_e32 v97, v97, v129
	v_mul_f32_e32 v98, v98, v130
	v_mul_f32_e32 v99, v99, v131
	v_cvt_pk_bf16_f32 v132, v104, v105
	v_cvt_pk_bf16_f32 v133, v106, v107
	v_cvt_pk_bf16_f32 v134, v96, v97
	v_cvt_pk_bf16_f32 v135, v98, v99
	s_add_u32 s26, s6, 0x100000
	s_addc_u32 s27, s7, 0
	global_store_dwordx4 v159, v[132:135], s[26:27]
	v_mul_f32_e32 v128, 0xbfb8aa3b, v92
	v_mul_f32_e32 v129, 0xbfb8aa3b, v93
	v_mul_f32_e32 v130, 0xbfb8aa3b, v94
	v_mul_f32_e32 v131, 0xbfb8aa3b, v95
	v_exp_f32_e32 v128, v128
	v_exp_f32_e32 v129, v129
	v_exp_f32_e32 v130, v130
	v_exp_f32_e32 v131, v131
	v_add_f32_e32 v128, 1.0, v128
	v_add_f32_e32 v129, 1.0, v129
	v_add_f32_e32 v130, 1.0, v130
	v_add_f32_e32 v131, 1.0, v131
	v_rcp_f32_e32 v128, v128
	v_rcp_f32_e32 v129, v129
	v_rcp_f32_e32 v130, v130
	v_rcp_f32_e32 v131, v131
	v_mul_f32_e32 v92, v92, v128
	v_mul_f32_e32 v93, v93, v129
	v_mul_f32_e32 v94, v94, v130
	v_mul_f32_e32 v95, v95, v131
	v_mul_f32_e32 v128, 0xbfb8aa3b, v84
	v_mul_f32_e32 v129, 0xbfb8aa3b, v85
	v_mul_f32_e32 v130, 0xbfb8aa3b, v86
	v_mul_f32_e32 v131, 0xbfb8aa3b, v87
	v_exp_f32_e32 v128, v128
	v_exp_f32_e32 v129, v129
	v_exp_f32_e32 v130, v130
	v_exp_f32_e32 v131, v131
	v_add_f32_e32 v128, 1.0, v128
	v_add_f32_e32 v129, 1.0, v129
	v_add_f32_e32 v130, 1.0, v130
	v_add_f32_e32 v131, 1.0, v131
	v_rcp_f32_e32 v128, v128
	v_rcp_f32_e32 v129, v129
	v_rcp_f32_e32 v130, v130
	v_rcp_f32_e32 v131, v131
	v_mul_f32_e32 v84, v84, v128
	v_mul_f32_e32 v85, v85, v129
	v_mul_f32_e32 v86, v86, v130
	v_mul_f32_e32 v87, v87, v131
	v_cvt_pk_bf16_f32 v160, v92, v93
	v_cvt_pk_bf16_f32 v161, v94, v95
	v_cvt_pk_bf16_f32 v162, v84, v85
	v_cvt_pk_bf16_f32 v163, v86, v87
	s_add_u32 s26, s6, 0x4000
	s_addc_u32 s27, s7, 0
	global_store_dwordx4 v158, v[160:163], s[26:27]
	v_mul_f32_e32 v128, 0xbfb8aa3b, v88
	v_mul_f32_e32 v129, 0xbfb8aa3b, v89
	v_mul_f32_e32 v130, 0xbfb8aa3b, v90
	v_mul_f32_e32 v131, 0xbfb8aa3b, v91
	v_exp_f32_e32 v128, v128
	v_exp_f32_e32 v129, v129
	v_exp_f32_e32 v130, v130
	v_exp_f32_e32 v131, v131
	v_add_f32_e32 v128, 1.0, v128
	v_add_f32_e32 v129, 1.0, v129
	v_add_f32_e32 v130, 1.0, v130
	v_add_f32_e32 v131, 1.0, v131
	v_rcp_f32_e32 v128, v128
	v_rcp_f32_e32 v129, v129
	v_rcp_f32_e32 v130, v130
	v_rcp_f32_e32 v131, v131
	v_mul_f32_e32 v88, v88, v128
	v_mul_f32_e32 v89, v89, v129
	v_mul_f32_e32 v90, v90, v130
	v_mul_f32_e32 v91, v91, v131
	v_mul_f32_e32 v128, 0xbfb8aa3b, v80
	v_mul_f32_e32 v129, 0xbfb8aa3b, v81
	v_mul_f32_e32 v130, 0xbfb8aa3b, v82
	v_mul_f32_e32 v131, 0xbfb8aa3b, v83
	v_exp_f32_e32 v128, v128
	v_exp_f32_e32 v129, v129
	v_exp_f32_e32 v130, v130
	v_exp_f32_e32 v131, v131
	v_add_f32_e32 v128, 1.0, v128
	v_add_f32_e32 v129, 1.0, v129
	v_add_f32_e32 v130, 1.0, v130
	v_add_f32_e32 v131, 1.0, v131
	v_rcp_f32_e32 v128, v128
	v_rcp_f32_e32 v129, v129
	v_rcp_f32_e32 v130, v130
	v_rcp_f32_e32 v131, v131
	v_mul_f32_e32 v80, v80, v128
	v_mul_f32_e32 v81, v81, v129
	v_mul_f32_e32 v82, v82, v130
	v_mul_f32_e32 v83, v83, v131
	v_cvt_pk_bf16_f32 v132, v88, v89
	v_cvt_pk_bf16_f32 v133, v90, v91
	v_cvt_pk_bf16_f32 v134, v80, v81
	v_cvt_pk_bf16_f32 v135, v82, v83
	s_add_u32 s26, s6, 0x104000
	s_addc_u32 s27, s7, 0
	global_store_dwordx4 v158, v[132:135], s[26:27]
	v_mul_f32_e32 v128, 0xbfb8aa3b, v76
	v_mul_f32_e32 v129, 0xbfb8aa3b, v77
	v_mul_f32_e32 v130, 0xbfb8aa3b, v78
	v_mul_f32_e32 v131, 0xbfb8aa3b, v79
	v_exp_f32_e32 v128, v128
	v_exp_f32_e32 v129, v129
	v_exp_f32_e32 v130, v130
	v_exp_f32_e32 v131, v131
	v_add_f32_e32 v128, 1.0, v128
	v_add_f32_e32 v129, 1.0, v129
	v_add_f32_e32 v130, 1.0, v130
	v_add_f32_e32 v131, 1.0, v131
	v_rcp_f32_e32 v128, v128
	v_rcp_f32_e32 v129, v129
	v_rcp_f32_e32 v130, v130
	v_rcp_f32_e32 v131, v131
	v_mul_f32_e32 v76, v76, v128
	v_mul_f32_e32 v77, v77, v129
	v_mul_f32_e32 v78, v78, v130
	v_mul_f32_e32 v79, v79, v131
	v_mul_f32_e32 v128, 0xbfb8aa3b, v68
	v_mul_f32_e32 v129, 0xbfb8aa3b, v69
	v_mul_f32_e32 v130, 0xbfb8aa3b, v70
	v_mul_f32_e32 v131, 0xbfb8aa3b, v71
	v_exp_f32_e32 v128, v128
	v_exp_f32_e32 v129, v129
	v_exp_f32_e32 v130, v130
	v_exp_f32_e32 v131, v131
	v_add_f32_e32 v128, 1.0, v128
	v_add_f32_e32 v129, 1.0, v129
	v_add_f32_e32 v130, 1.0, v130
	v_add_f32_e32 v131, 1.0, v131
	v_rcp_f32_e32 v128, v128
	v_rcp_f32_e32 v129, v129
	v_rcp_f32_e32 v130, v130
	v_rcp_f32_e32 v131, v131
	v_mul_f32_e32 v68, v68, v128
	v_mul_f32_e32 v69, v69, v129
	v_mul_f32_e32 v70, v70, v130
	v_mul_f32_e32 v71, v71, v131
	v_cvt_pk_bf16_f32 v160, v76, v77
	v_cvt_pk_bf16_f32 v161, v78, v79
	v_cvt_pk_bf16_f32 v162, v68, v69
	v_cvt_pk_bf16_f32 v163, v70, v71
	s_add_u32 s26, s6, 0x4000
	s_addc_u32 s27, s7, 0
	global_store_dwordx4 v159, v[160:163], s[26:27]
	v_mul_f32_e32 v128, 0xbfb8aa3b, v72
	v_mul_f32_e32 v129, 0xbfb8aa3b, v73
	v_mul_f32_e32 v130, 0xbfb8aa3b, v74
	v_mul_f32_e32 v131, 0xbfb8aa3b, v75
	v_exp_f32_e32 v128, v128
	v_exp_f32_e32 v129, v129
	v_exp_f32_e32 v130, v130
	v_exp_f32_e32 v131, v131
	v_add_f32_e32 v128, 1.0, v128
	v_add_f32_e32 v129, 1.0, v129
	v_add_f32_e32 v130, 1.0, v130
	v_add_f32_e32 v131, 1.0, v131
	v_rcp_f32_e32 v128, v128
	v_rcp_f32_e32 v129, v129
	v_rcp_f32_e32 v130, v130
	v_rcp_f32_e32 v131, v131
	v_mul_f32_e32 v72, v72, v128
	v_mul_f32_e32 v73, v73, v129
	v_mul_f32_e32 v74, v74, v130
	v_mul_f32_e32 v75, v75, v131
	v_mul_f32_e32 v128, 0xbfb8aa3b, v64
	v_mul_f32_e32 v129, 0xbfb8aa3b, v65
	v_mul_f32_e32 v130, 0xbfb8aa3b, v66
	v_mul_f32_e32 v131, 0xbfb8aa3b, v67
	v_exp_f32_e32 v128, v128
	v_exp_f32_e32 v129, v129
	v_exp_f32_e32 v130, v130
	v_exp_f32_e32 v131, v131
	v_add_f32_e32 v128, 1.0, v128
	v_add_f32_e32 v129, 1.0, v129
	v_add_f32_e32 v130, 1.0, v130
	v_add_f32_e32 v131, 1.0, v131
	v_rcp_f32_e32 v128, v128
	v_rcp_f32_e32 v129, v129
	v_rcp_f32_e32 v130, v130
	v_rcp_f32_e32 v131, v131
	v_mul_f32_e32 v64, v64, v128
	v_mul_f32_e32 v65, v65, v129
	v_mul_f32_e32 v66, v66, v130
	v_mul_f32_e32 v67, v67, v131
	v_cvt_pk_bf16_f32 v132, v72, v73
	v_cvt_pk_bf16_f32 v133, v74, v75
	v_cvt_pk_bf16_f32 v134, v64, v65
	v_cvt_pk_bf16_f32 v135, v66, v67
	s_add_u32 s26, s6, 0x104000
	s_addc_u32 s27, s7, 0
	global_store_dwordx4 v159, v[132:135], s[26:27]
	v_mul_f32_e32 v128, 0xbfb8aa3b, v60
	v_mul_f32_e32 v129, 0xbfb8aa3b, v61
	v_mul_f32_e32 v130, 0xbfb8aa3b, v62
	v_mul_f32_e32 v131, 0xbfb8aa3b, v63
	v_exp_f32_e32 v128, v128
	v_exp_f32_e32 v129, v129
	v_exp_f32_e32 v130, v130
	v_exp_f32_e32 v131, v131
	v_add_f32_e32 v128, 1.0, v128
	v_add_f32_e32 v129, 1.0, v129
	v_add_f32_e32 v130, 1.0, v130
	v_add_f32_e32 v131, 1.0, v131
	v_rcp_f32_e32 v128, v128
	v_rcp_f32_e32 v129, v129
	v_rcp_f32_e32 v130, v130
	v_rcp_f32_e32 v131, v131
	v_mul_f32_e32 v60, v60, v128
	v_mul_f32_e32 v61, v61, v129
	v_mul_f32_e32 v62, v62, v130
	v_mul_f32_e32 v63, v63, v131
	v_mul_f32_e32 v128, 0xbfb8aa3b, v52
	v_mul_f32_e32 v129, 0xbfb8aa3b, v53
	v_mul_f32_e32 v130, 0xbfb8aa3b, v54
	v_mul_f32_e32 v131, 0xbfb8aa3b, v55
	v_exp_f32_e32 v128, v128
	v_exp_f32_e32 v129, v129
	v_exp_f32_e32 v130, v130
	v_exp_f32_e32 v131, v131
	v_add_f32_e32 v128, 1.0, v128
	v_add_f32_e32 v129, 1.0, v129
	v_add_f32_e32 v130, 1.0, v130
	v_add_f32_e32 v131, 1.0, v131
	v_rcp_f32_e32 v128, v128
	v_rcp_f32_e32 v129, v129
	v_rcp_f32_e32 v130, v130
	v_rcp_f32_e32 v131, v131
	v_mul_f32_e32 v52, v52, v128
	v_mul_f32_e32 v53, v53, v129
	v_mul_f32_e32 v54, v54, v130
	v_mul_f32_e32 v55, v55, v131
	v_cvt_pk_bf16_f32 v160, v60, v61
	v_cvt_pk_bf16_f32 v161, v62, v63
	v_cvt_pk_bf16_f32 v162, v52, v53
	v_cvt_pk_bf16_f32 v163, v54, v55
	s_add_u32 s26, s6, 0x10000
	s_addc_u32 s27, s7, 0
	global_store_dwordx4 v158, v[160:163], s[26:27]
	v_mul_f32_e32 v128, 0xbfb8aa3b, v56
	v_mul_f32_e32 v129, 0xbfb8aa3b, v57
	v_mul_f32_e32 v130, 0xbfb8aa3b, v58
	v_mul_f32_e32 v131, 0xbfb8aa3b, v59
	v_exp_f32_e32 v128, v128
	v_exp_f32_e32 v129, v129
	v_exp_f32_e32 v130, v130
	v_exp_f32_e32 v131, v131
	v_add_f32_e32 v128, 1.0, v128
	v_add_f32_e32 v129, 1.0, v129
	v_add_f32_e32 v130, 1.0, v130
	v_add_f32_e32 v131, 1.0, v131
	v_rcp_f32_e32 v128, v128
	v_rcp_f32_e32 v129, v129
	v_rcp_f32_e32 v130, v130
	v_rcp_f32_e32 v131, v131
	v_mul_f32_e32 v56, v56, v128
	v_mul_f32_e32 v57, v57, v129
	v_mul_f32_e32 v58, v58, v130
	v_mul_f32_e32 v59, v59, v131
	v_mul_f32_e32 v128, 0xbfb8aa3b, v48
	v_mul_f32_e32 v129, 0xbfb8aa3b, v49
	v_mul_f32_e32 v130, 0xbfb8aa3b, v50
	v_mul_f32_e32 v131, 0xbfb8aa3b, v51
	v_exp_f32_e32 v128, v128
	v_exp_f32_e32 v129, v129
	v_exp_f32_e32 v130, v130
	v_exp_f32_e32 v131, v131
	v_add_f32_e32 v128, 1.0, v128
	v_add_f32_e32 v129, 1.0, v129
	v_add_f32_e32 v130, 1.0, v130
	v_add_f32_e32 v131, 1.0, v131
	v_rcp_f32_e32 v128, v128
	v_rcp_f32_e32 v129, v129
	v_rcp_f32_e32 v130, v130
	v_rcp_f32_e32 v131, v131
	v_mul_f32_e32 v48, v48, v128
	v_mul_f32_e32 v49, v49, v129
	v_mul_f32_e32 v50, v50, v130
	v_mul_f32_e32 v51, v51, v131
	v_cvt_pk_bf16_f32 v132, v56, v57
	v_cvt_pk_bf16_f32 v133, v58, v59
	v_cvt_pk_bf16_f32 v134, v48, v49
	v_cvt_pk_bf16_f32 v135, v50, v51
	s_add_u32 s26, s6, 0x110000
	s_addc_u32 s27, s7, 0
	global_store_dwordx4 v158, v[132:135], s[26:27]
	v_mul_f32_e32 v128, 0xbfb8aa3b, v44
	v_mul_f32_e32 v129, 0xbfb8aa3b, v45
	v_mul_f32_e32 v130, 0xbfb8aa3b, v46
	v_mul_f32_e32 v131, 0xbfb8aa3b, v47
	v_exp_f32_e32 v128, v128
	v_exp_f32_e32 v129, v129
	v_exp_f32_e32 v130, v130
	v_exp_f32_e32 v131, v131
	v_add_f32_e32 v128, 1.0, v128
	v_add_f32_e32 v129, 1.0, v129
	v_add_f32_e32 v130, 1.0, v130
	v_add_f32_e32 v131, 1.0, v131
	v_rcp_f32_e32 v128, v128
	v_rcp_f32_e32 v129, v129
	v_rcp_f32_e32 v130, v130
	v_rcp_f32_e32 v131, v131
	v_mul_f32_e32 v44, v44, v128
	v_mul_f32_e32 v45, v45, v129
	v_mul_f32_e32 v46, v46, v130
	v_mul_f32_e32 v47, v47, v131
	v_mul_f32_e32 v128, 0xbfb8aa3b, v36
	v_mul_f32_e32 v129, 0xbfb8aa3b, v37
	v_mul_f32_e32 v130, 0xbfb8aa3b, v38
	v_mul_f32_e32 v131, 0xbfb8aa3b, v39
	v_exp_f32_e32 v128, v128
	v_exp_f32_e32 v129, v129
	v_exp_f32_e32 v130, v130
	v_exp_f32_e32 v131, v131
	v_add_f32_e32 v128, 1.0, v128
	v_add_f32_e32 v129, 1.0, v129
	v_add_f32_e32 v130, 1.0, v130
	v_add_f32_e32 v131, 1.0, v131
	v_rcp_f32_e32 v128, v128
	v_rcp_f32_e32 v129, v129
	v_rcp_f32_e32 v130, v130
	v_rcp_f32_e32 v131, v131
	v_mul_f32_e32 v36, v36, v128
	v_mul_f32_e32 v37, v37, v129
	v_mul_f32_e32 v38, v38, v130
	v_mul_f32_e32 v39, v39, v131
	v_cvt_pk_bf16_f32 v160, v44, v45
	v_cvt_pk_bf16_f32 v161, v46, v47
	v_cvt_pk_bf16_f32 v162, v36, v37
	v_cvt_pk_bf16_f32 v163, v38, v39
	s_add_u32 s26, s6, 0x10000
	s_addc_u32 s27, s7, 0
	global_store_dwordx4 v159, v[160:163], s[26:27]
	v_mul_f32_e32 v128, 0xbfb8aa3b, v40
	v_mul_f32_e32 v129, 0xbfb8aa3b, v41
	v_mul_f32_e32 v130, 0xbfb8aa3b, v42
	v_mul_f32_e32 v131, 0xbfb8aa3b, v43
	v_exp_f32_e32 v128, v128
	v_exp_f32_e32 v129, v129
	v_exp_f32_e32 v130, v130
	v_exp_f32_e32 v131, v131
	v_add_f32_e32 v128, 1.0, v128
	v_add_f32_e32 v129, 1.0, v129
	v_add_f32_e32 v130, 1.0, v130
	v_add_f32_e32 v131, 1.0, v131
	v_rcp_f32_e32 v128, v128
	v_rcp_f32_e32 v129, v129
	v_rcp_f32_e32 v130, v130
	v_rcp_f32_e32 v131, v131
	v_mul_f32_e32 v40, v40, v128
	v_mul_f32_e32 v41, v41, v129
	v_mul_f32_e32 v42, v42, v130
	v_mul_f32_e32 v43, v43, v131
	v_mul_f32_e32 v128, 0xbfb8aa3b, v32
	v_mul_f32_e32 v129, 0xbfb8aa3b, v33
	v_mul_f32_e32 v130, 0xbfb8aa3b, v34
	v_mul_f32_e32 v131, 0xbfb8aa3b, v35
	v_exp_f32_e32 v128, v128
	v_exp_f32_e32 v129, v129
	v_exp_f32_e32 v130, v130
	v_exp_f32_e32 v131, v131
	v_add_f32_e32 v128, 1.0, v128
	v_add_f32_e32 v129, 1.0, v129
	v_add_f32_e32 v130, 1.0, v130
	v_add_f32_e32 v131, 1.0, v131
	v_rcp_f32_e32 v128, v128
	v_rcp_f32_e32 v129, v129
	v_rcp_f32_e32 v130, v130
	v_rcp_f32_e32 v131, v131
	v_mul_f32_e32 v32, v32, v128
	v_mul_f32_e32 v33, v33, v129
	v_mul_f32_e32 v34, v34, v130
	v_mul_f32_e32 v35, v35, v131
	v_cvt_pk_bf16_f32 v132, v40, v41
	v_cvt_pk_bf16_f32 v133, v42, v43
	v_cvt_pk_bf16_f32 v134, v32, v33
	v_cvt_pk_bf16_f32 v135, v34, v35
	s_add_u32 s26, s6, 0x110000
	s_addc_u32 s27, s7, 0
	global_store_dwordx4 v159, v[132:135], s[26:27]
	v_mul_f32_e32 v128, 0xbfb8aa3b, v28
	v_mul_f32_e32 v129, 0xbfb8aa3b, v29
	v_mul_f32_e32 v130, 0xbfb8aa3b, v30
	v_mul_f32_e32 v131, 0xbfb8aa3b, v31
	v_exp_f32_e32 v128, v128
	v_exp_f32_e32 v129, v129
	v_exp_f32_e32 v130, v130
	v_exp_f32_e32 v131, v131
	v_add_f32_e32 v128, 1.0, v128
	v_add_f32_e32 v129, 1.0, v129
	v_add_f32_e32 v130, 1.0, v130
	v_add_f32_e32 v131, 1.0, v131
	v_rcp_f32_e32 v128, v128
	v_rcp_f32_e32 v129, v129
	v_rcp_f32_e32 v130, v130
	v_rcp_f32_e32 v131, v131
	v_mul_f32_e32 v28, v28, v128
	v_mul_f32_e32 v29, v29, v129
	v_mul_f32_e32 v30, v30, v130
	v_mul_f32_e32 v31, v31, v131
	v_mul_f32_e32 v128, 0xbfb8aa3b, v20
	v_mul_f32_e32 v129, 0xbfb8aa3b, v21
	v_mul_f32_e32 v130, 0xbfb8aa3b, v22
	v_mul_f32_e32 v131, 0xbfb8aa3b, v23
	v_exp_f32_e32 v128, v128
	v_exp_f32_e32 v129, v129
	v_exp_f32_e32 v130, v130
	v_exp_f32_e32 v131, v131
	v_add_f32_e32 v128, 1.0, v128
	v_add_f32_e32 v129, 1.0, v129
	v_add_f32_e32 v130, 1.0, v130
	v_add_f32_e32 v131, 1.0, v131
	v_rcp_f32_e32 v128, v128
	v_rcp_f32_e32 v129, v129
	v_rcp_f32_e32 v130, v130
	v_rcp_f32_e32 v131, v131
	v_mul_f32_e32 v20, v20, v128
	v_mul_f32_e32 v21, v21, v129
	v_mul_f32_e32 v22, v22, v130
	v_mul_f32_e32 v23, v23, v131
	v_cvt_pk_bf16_f32 v160, v28, v29
	v_cvt_pk_bf16_f32 v161, v30, v31
	v_cvt_pk_bf16_f32 v162, v20, v21
	v_cvt_pk_bf16_f32 v163, v22, v23
	s_add_u32 s26, s6, 0x14000
	s_addc_u32 s27, s7, 0
	global_store_dwordx4 v158, v[160:163], s[26:27]
	v_mul_f32_e32 v128, 0xbfb8aa3b, v24
	v_mul_f32_e32 v129, 0xbfb8aa3b, v25
	v_mul_f32_e32 v130, 0xbfb8aa3b, v26
	v_mul_f32_e32 v131, 0xbfb8aa3b, v27
	v_exp_f32_e32 v128, v128
	v_exp_f32_e32 v129, v129
	v_exp_f32_e32 v130, v130
	v_exp_f32_e32 v131, v131
	v_add_f32_e32 v128, 1.0, v128
	v_add_f32_e32 v129, 1.0, v129
	v_add_f32_e32 v130, 1.0, v130
	v_add_f32_e32 v131, 1.0, v131
	v_rcp_f32_e32 v128, v128
	v_rcp_f32_e32 v129, v129
	v_rcp_f32_e32 v130, v130
	v_rcp_f32_e32 v131, v131
	v_mul_f32_e32 v24, v24, v128
	v_mul_f32_e32 v25, v25, v129
	v_mul_f32_e32 v26, v26, v130
	v_mul_f32_e32 v27, v27, v131
	v_mul_f32_e32 v128, 0xbfb8aa3b, v16
	v_mul_f32_e32 v129, 0xbfb8aa3b, v17
	v_mul_f32_e32 v130, 0xbfb8aa3b, v18
	v_mul_f32_e32 v131, 0xbfb8aa3b, v19
	v_exp_f32_e32 v128, v128
	v_exp_f32_e32 v129, v129
	v_exp_f32_e32 v130, v130
	v_exp_f32_e32 v131, v131
	v_add_f32_e32 v128, 1.0, v128
	v_add_f32_e32 v129, 1.0, v129
	v_add_f32_e32 v130, 1.0, v130
	v_add_f32_e32 v131, 1.0, v131
	v_rcp_f32_e32 v128, v128
	v_rcp_f32_e32 v129, v129
	v_rcp_f32_e32 v130, v130
	v_rcp_f32_e32 v131, v131
	v_mul_f32_e32 v16, v16, v128
	v_mul_f32_e32 v17, v17, v129
	v_mul_f32_e32 v18, v18, v130
	v_mul_f32_e32 v19, v19, v131
	v_cvt_pk_bf16_f32 v132, v24, v25
	v_cvt_pk_bf16_f32 v133, v26, v27
	v_cvt_pk_bf16_f32 v134, v16, v17
	v_cvt_pk_bf16_f32 v135, v18, v19
	s_add_u32 s26, s6, 0x114000
	s_addc_u32 s27, s7, 0
	global_store_dwordx4 v158, v[132:135], s[26:27]
	v_mul_f32_e32 v128, 0xbfb8aa3b, v12
	v_mul_f32_e32 v129, 0xbfb8aa3b, v13
	v_mul_f32_e32 v130, 0xbfb8aa3b, v14
	v_mul_f32_e32 v131, 0xbfb8aa3b, v15
	v_exp_f32_e32 v128, v128
	v_exp_f32_e32 v129, v129
	v_exp_f32_e32 v130, v130
	v_exp_f32_e32 v131, v131
	v_add_f32_e32 v128, 1.0, v128
	v_add_f32_e32 v129, 1.0, v129
	v_add_f32_e32 v130, 1.0, v130
	v_add_f32_e32 v131, 1.0, v131
	v_rcp_f32_e32 v128, v128
	v_rcp_f32_e32 v129, v129
	v_rcp_f32_e32 v130, v130
	v_rcp_f32_e32 v131, v131
	v_mul_f32_e32 v12, v12, v128
	v_mul_f32_e32 v13, v13, v129
	v_mul_f32_e32 v14, v14, v130
	v_mul_f32_e32 v15, v15, v131
	v_mul_f32_e32 v128, 0xbfb8aa3b, v4
	v_mul_f32_e32 v129, 0xbfb8aa3b, v5
	v_mul_f32_e32 v130, 0xbfb8aa3b, v6
	v_mul_f32_e32 v131, 0xbfb8aa3b, v7
	v_exp_f32_e32 v128, v128
	v_exp_f32_e32 v129, v129
	v_exp_f32_e32 v130, v130
	v_exp_f32_e32 v131, v131
	v_add_f32_e32 v128, 1.0, v128
	v_add_f32_e32 v129, 1.0, v129
	v_add_f32_e32 v130, 1.0, v130
	v_add_f32_e32 v131, 1.0, v131
	v_rcp_f32_e32 v128, v128
	v_rcp_f32_e32 v129, v129
	v_rcp_f32_e32 v130, v130
	v_rcp_f32_e32 v131, v131
	v_mul_f32_e32 v4, v4, v128
	v_mul_f32_e32 v5, v5, v129
	v_mul_f32_e32 v6, v6, v130
	v_mul_f32_e32 v7, v7, v131
	v_cvt_pk_bf16_f32 v160, v12, v13
	v_cvt_pk_bf16_f32 v161, v14, v15
	v_cvt_pk_bf16_f32 v162, v4, v5
	v_cvt_pk_bf16_f32 v163, v6, v7
	s_add_u32 s26, s6, 0x14000
	s_addc_u32 s27, s7, 0
	global_store_dwordx4 v159, v[160:163], s[26:27]
	v_mul_f32_e32 v128, 0xbfb8aa3b, v8
	v_mul_f32_e32 v129, 0xbfb8aa3b, v9
	v_mul_f32_e32 v130, 0xbfb8aa3b, v10
	v_mul_f32_e32 v131, 0xbfb8aa3b, v11
	v_exp_f32_e32 v128, v128
	v_exp_f32_e32 v129, v129
	v_exp_f32_e32 v130, v130
	v_exp_f32_e32 v131, v131
	v_add_f32_e32 v128, 1.0, v128
	v_add_f32_e32 v129, 1.0, v129
	v_add_f32_e32 v130, 1.0, v130
	v_add_f32_e32 v131, 1.0, v131
	v_rcp_f32_e32 v128, v128
	v_rcp_f32_e32 v129, v129
	v_rcp_f32_e32 v130, v130
	v_rcp_f32_e32 v131, v131
	v_mul_f32_e32 v8, v8, v128
	v_mul_f32_e32 v9, v9, v129
	v_mul_f32_e32 v10, v10, v130
	v_mul_f32_e32 v11, v11, v131
	v_mul_f32_e32 v128, 0xbfb8aa3b, v0
	v_mul_f32_e32 v129, 0xbfb8aa3b, v1
	v_mul_f32_e32 v130, 0xbfb8aa3b, v2
	v_mul_f32_e32 v131, 0xbfb8aa3b, v3
	v_exp_f32_e32 v128, v128
	v_exp_f32_e32 v129, v129
	v_exp_f32_e32 v130, v130
	v_exp_f32_e32 v131, v131
	v_add_f32_e32 v128, 1.0, v128
	v_add_f32_e32 v129, 1.0, v129
	v_add_f32_e32 v130, 1.0, v130
	v_add_f32_e32 v131, 1.0, v131
	v_rcp_f32_e32 v128, v128
	v_rcp_f32_e32 v129, v129
	v_rcp_f32_e32 v130, v130
	v_rcp_f32_e32 v131, v131
	v_mul_f32_e32 v0, v0, v128
	v_mul_f32_e32 v1, v1, v129
	v_mul_f32_e32 v2, v2, v130
	v_mul_f32_e32 v3, v3, v131
	v_cvt_pk_bf16_f32 v132, v8, v9
	v_cvt_pk_bf16_f32 v133, v10, v11
	v_cvt_pk_bf16_f32 v134, v0, v1
	v_cvt_pk_bf16_f32 v135, v2, v3
	s_add_u32 s26, s6, 0x114000
	s_addc_u32 s27, s7, 0
	global_store_dwordx4 v159, v[132:135], s[26:27]
	s_branch .LBB0_228

.Lmb_entry:
	s_waitcnt lgkmcnt(0)
	s_barrier
	s_lshr_b32 s39, s96, 5
	s_and_b32 s39, s39, 7
	s_and_b32 s4, s96, 7
	s_lshl_b32 s5, s4, 3
	s_add_u32 s5, s5, s39
	s_bfe_u32 s6, s96, 0x20003
	v_mbcnt_lo_u32_b32 v230, -1, 0
	v_mbcnt_hi_u32_b32 v230, -1, v230
	v_xor_b32_e32 v228, 16, v230
	v_lshlrev_b32_e32 v228, 2, v228
	v_xor_b32_e32 v229, 32, v230
	v_lshlrev_b32_e32 v229, 2, v229
	s_mov_b32 s35, 0x40c00000
	s_mov_b32 s36, 0xc61c4000
	s_mov_b32 s37, 0xefa18f08
	s_mov_b32 s38, 0x3e0293ee
	v_mov_b32_e32 v134, 0xff61b1e6
	v_mov_b32_e32 v135, 0x7f61b1e6
	v_lshrrev_b32_e32 v140, 6, v198
	s_nop 0
	v_readfirstlane_b32 s7, v140
	s_lshl_b32 s30, s39, 20
	s_lshl_b32 s31, s4, 25
	s_add_u32 s8, s66, s31
	s_addc_u32 s9, s67, 0
	s_add_u32 s8, s8, s30
	s_addc_u32 s9, s9, 0
	s_lshl_b32 s30, s39, 8
	s_add_u32 s8, s8, 0x2000
	s_addc_u32 s9, s9, 0
	s_lshl_b32 s31, s4, 23
	s_add_u32 s10, s50, s31
	s_addc_u32 s11, s51, 0
	s_add_u32 s10, s10, s30
	s_addc_u32 s11, s11, 0
	s_add_u32 s10, s10, 0x800
	s_addc_u32 s11, s11, 0
	s_lshl_b32 s31, s5, 12
	v_readlane_b32 s12, v236, 26
	v_readlane_b32 s13, v236, 27
	s_nop 3
	s_add_u32 s12, s12, s31
	s_addc_u32 s13, s13, 0
	v_lshrrev_b32_e32 v140, 4, v198
	v_and_b32_e32 v141, 15, v198
	v_lshlrev_b32_e32 v141, 4, v141
	v_lshlrev_b32_e32 v132, 4, v198
	v_add_u32_e32 v133, 0x4000, v132
	v_and_b32_e32 v142, 0x7f, v198
	v_lshrrev_b32_e32 v143, 1, v142
	v_and_b32_e32 v142, 1, v142
	v_lshlrev_b32_e32 v142, 7, v142
	v_lshl_add_u32 v227, v143, 14, v142
	v_bfe_u32 v142, v198, 7, 1
	v_lshl_add_u32 v227, v142, 11, v227
	s_movk_i32 s30, 272
	v_mad_u32_u24 v130, v140, s30, v141
	v_xor_b32_e32 v130, 65536, v130
	s_movk_i32 s30, 288
	v_mad_u32_u24 v131, v140, s30, v141
	v_add_u32_e32 v131, 82944, v131
	v_and_b32_e32 v140, 15, v230
	v_lshrrev_b32_e32 v141, 4, v230
	s_movk_i32 s30, 272
	v_lshlrev_b32_e32 v142, 4, v141
	v_mad_u32_u24 v128, v140, s30, v142
	v_lshrrev_b32_e32 v142, 2, v140
	v_lshl_add_u32 v142, v141, 2, v142
	v_and_b32_e32 v143, 3, v140
	v_lshlrev_b32_e32 v143, 3, v143
	s_movk_i32 s30, 288
	v_mad_u32_u24 v129, v142, s30, v143
	v_add_u32_e32 v129, 17408, v129
	s_lshl_b32 s30, s7, 5
	v_lshlrev_b32_e32 v142, 2, v141
	v_sub_u32_e32 v137, v140, v142
	v_add_u32_e32 v137, s30, v137
	s_cmp_ge_u32 s7, 4
	s_cbranch_scc0 .Lmb_noprio
	s_setprio 1
.Lmb_noprio:
	s_mov_b32 s14, 0
.Lmb_task:
	s_sub_u32 s15, 7, s6
	s_cmp_eq_u32 s14, 0
	s_cselect_b32 s15, s15, s6
	s_lshl_b32 s22, s15, 2
	s_add_u32 s22, s22, 4
	s_lshl_b32 s30, s15, 17
	s_add_u32 s24, s8, s30
	s_addc_u32 s25, s9, 0
	s_mov_b32 s30, 0
	s_lshl_b32 s33, s15, 2
	s_add_u32 s33, s33, s30
	s_sub_u32 s31, s30, 4
	s_cmp_lt_u32 s30, 4
	s_cselect_b32 s31, s33, s31
	s_lshl_b32 s33, s31, 15
	s_add_u32 s33, s33, 0x800000
	s_add_u32 s26, s8, s33
	s_addc_u32 s27, s9, 0
	global_load_dwordx4 v[168:171], v132, s[26:27]
	global_load_dwordx4 v[172:175], v133, s[26:27]
	s_add_u32 s26, s26, 0x800000
	s_addc_u32 s27, s27, 0
	global_load_dwordx4 v[176:179], v132, s[26:27]
	global_load_dwordx4 v[180:183], v133, s[26:27]
	v_and_b32_e32 v140, 15, v230
	s_lshl_b32 s30, s7, 5
	v_lshlrev_b32_e32 v140, 8, v140
	s_lshl_b32 s30, s7, 14
	v_add_u32_e32 v140, s30, v140
	v_lshrrev_b32_e32 v141, 4, v230
	s_cmp_lt_u32 s15, 4
	s_cbranch_scc1 .Lmb_sel_small
	v_lshl_add_u32 v142, v141, 6, v140
	v_and_b32_e32 v143, 7, v230
	v_lshlrev_b32_e32 v143, 9, v143
	v_lshl_add_u32 v143, v141, 7, v143
	global_load_dwordx4 v[0:3], v143, s[12:13] offset:0
	global_load_dwordx4 v[4:7], v143, s[12:13] offset:16
	global_load_dwordx4 v[8:11], v143, s[12:13] offset:32
	global_load_dwordx4 v[12:15], v143, s[12:13] offset:48
	global_load_dwordx4 v[16:19], v143, s[12:13] offset:64
	global_load_dwordx4 v[20:23], v143, s[12:13] offset:80
	global_load_dwordx4 v[24:27], v143, s[12:13] offset:96
	global_load_dwordx4 v[28:31], v143, s[12:13] offset:112
	s_add_u32 s28, s24, 0
	s_addc_u32 s29, s25, 0
	global_load_dwordx4 v[96:99], v142, s[28:29] offset:0
	global_load_dwordx4 v[100:103], v142, s[28:29] offset:16
	global_load_dwordx4 v[104:107], v142, s[28:29] offset:32
	global_load_dwordx4 v[108:111], v142, s[28:29] offset:48
	s_waitcnt vmcnt(0)
	v_lshlrev_b32_e32 v32, 16, v96
	v_and_b32_e32 v33, 0xffff0000, v96
	v_lshlrev_b32_e32 v34, 16, v97
	v_and_b32_e32 v35, 0xffff0000, v97
	v_lshlrev_b32_e32 v36, 16, v98
	v_and_b32_e32 v37, 0xffff0000, v98
	v_lshlrev_b32_e32 v38, 16, v99
	v_and_b32_e32 v39, 0xffff0000, v99
	v_lshlrev_b32_e32 v40, 16, v100
	v_and_b32_e32 v41, 0xffff0000, v100
	v_lshlrev_b32_e32 v42, 16, v101
	v_and_b32_e32 v43, 0xffff0000, v101
	v_lshlrev_b32_e32 v44, 16, v102
	v_and_b32_e32 v45, 0xffff0000, v102
	v_lshlrev_b32_e32 v46, 16, v103
	v_and_b32_e32 v47, 0xffff0000, v103
	v_lshlrev_b32_e32 v48, 16, v104
	v_and_b32_e32 v49, 0xffff0000, v104
	v_lshlrev_b32_e32 v50, 16, v105
	v_and_b32_e32 v51, 0xffff0000, v105
	v_lshlrev_b32_e32 v52, 16, v106
	v_and_b32_e32 v53, 0xffff0000, v106
	v_lshlrev_b32_e32 v54, 16, v107
	v_and_b32_e32 v55, 0xffff0000, v107
	v_lshlrev_b32_e32 v56, 16, v108
	v_and_b32_e32 v57, 0xffff0000, v108
	v_lshlrev_b32_e32 v58, 16, v109
	v_and_b32_e32 v59, 0xffff0000, v109
	v_lshlrev_b32_e32 v60, 16, v110
	v_and_b32_e32 v61, 0xffff0000, v110
	v_lshlrev_b32_e32 v62, 16, v111
	v_and_b32_e32 v63, 0xffff0000, v111
	s_nop 1
	v_mfma_f32_16x16x4_f32 v[112:115], v0, v32, 0
	v_mfma_f32_16x16x4_f32 v[112:115], v1, v33, v[112:115]
	v_mfma_f32_16x16x4_f32 v[112:115], v2, v34, v[112:115]
	v_mfma_f32_16x16x4_f32 v[112:115], v3, v35, v[112:115]
	v_mfma_f32_16x16x4_f32 v[112:115], v4, v36, v[112:115]
	v_mfma_f32_16x16x4_f32 v[112:115], v5, v37, v[112:115]
	v_mfma_f32_16x16x4_f32 v[112:115], v6, v38, v[112:115]
	v_mfma_f32_16x16x4_f32 v[112:115], v7, v39, v[112:115]
	v_mfma_f32_16x16x4_f32 v[112:115], v8, v40, v[112:115]
	v_mfma_f32_16x16x4_f32 v[112:115], v9, v41, v[112:115]
	v_mfma_f32_16x16x4_f32 v[112:115], v10, v42, v[112:115]
	v_mfma_f32_16x16x4_f32 v[112:115], v11, v43, v[112:115]
	v_mfma_f32_16x16x4_f32 v[112:115], v12, v44, v[112:115]
	v_mfma_f32_16x16x4_f32 v[112:115], v13, v45, v[112:115]
	v_mfma_f32_16x16x4_f32 v[112:115], v14, v46, v[112:115]
	v_mfma_f32_16x16x4_f32 v[112:115], v15, v47, v[112:115]
	v_mfma_f32_16x16x4_f32 v[112:115], v16, v48, v[112:115]
	v_mfma_f32_16x16x4_f32 v[112:115], v17, v49, v[112:115]
	v_mfma_f32_16x16x4_f32 v[112:115], v18, v50, v[112:115]
	v_mfma_f32_16x16x4_f32 v[112:115], v19, v51, v[112:115]
	v_mfma_f32_16x16x4_f32 v[112:115], v20, v52, v[112:115]
	v_mfma_f32_16x16x4_f32 v[112:115], v21, v53, v[112:115]
	v_mfma_f32_16x16x4_f32 v[112:115], v22, v54, v[112:115]
	v_mfma_f32_16x16x4_f32 v[112:115], v23, v55, v[112:115]
	v_mfma_f32_16x16x4_f32 v[112:115], v24, v56, v[112:115]
	v_mfma_f32_16x16x4_f32 v[112:115], v25, v57, v[112:115]
	v_mfma_f32_16x16x4_f32 v[112:115], v26, v58, v[112:115]
	v_mfma_f32_16x16x4_f32 v[112:115], v27, v59, v[112:115]
	v_mfma_f32_16x16x4_f32 v[112:115], v28, v60, v[112:115]
	v_mfma_f32_16x16x4_f32 v[112:115], v29, v61, v[112:115]
	v_mfma_f32_16x16x4_f32 v[112:115], v30, v62, v[112:115]
	v_mfma_f32_16x16x4_f32 v[112:115], v31, v63, v[112:115]
	s_nop 10
	ds_bpermute_b32 v116, v228, v112
	ds_bpermute_b32 v117, v228, v113
	ds_bpermute_b32 v118, v228, v114
	ds_bpermute_b32 v119, v228, v115
	s_waitcnt lgkmcnt(0)
	s_cmp_gt_u32 s15, 0
	s_cselect_b64 s[56:57], -1, 0
	v_cndmask_b32_e64 v112, v134, v112, s[56:57]
	s_cmp_gt_u32 s15, 1
	s_cselect_b64 s[58:59], -1, 0
	v_cndmask_b32_e64 v113, v134, v113, s[58:59]
	s_cmp_gt_u32 s15, 2
	s_cselect_b64 s[64:65], -1, 0
	v_cndmask_b32_e64 v114, v134, v114, s[64:65]
	s_cmp_gt_u32 s15, 3
	s_cselect_b64 s[68:69], -1, 0
	v_cndmask_b32_e64 v115, v134, v115, s[68:69]
	s_cmp_gt_u32 s15, 4
	s_cselect_b64 s[56:57], -1, 0
	v_cndmask_b32_e64 v116, v134, v116, s[56:57]
	s_cmp_gt_u32 s15, 5
	s_cselect_b64 s[58:59], -1, 0
	v_cndmask_b32_e64 v117, v134, v117, s[58:59]
	s_cmp_gt_u32 s15, 6
	s_cselect_b64 s[64:65], -1, 0
	v_cndmask_b32_e64 v118, v134, v118, s[64:65]
	v_mov_b32_e32 v160, 0
	v_mov_b32_e32 v158, v134
	v_mov_b32_e32 v159, 0
	v_cmp_gt_f32_e32 vcc, v112, v158
	s_nop 1
	v_cndmask_b32_e32 v158, v158, v112, vcc
	v_cndmask_b32_e64 v159, v159, 0, vcc
	v_cmp_gt_f32_e32 vcc, v113, v158
	s_nop 1
	v_cndmask_b32_e32 v158, v158, v113, vcc
	v_cndmask_b32_e64 v159, v159, 1, vcc
	v_cmp_gt_f32_e32 vcc, v114, v158
	s_nop 1
	v_cndmask_b32_e32 v158, v158, v114, vcc
	v_cndmask_b32_e64 v159, v159, 2, vcc
	v_cmp_gt_f32_e32 vcc, v115, v158
	s_nop 1
	v_cndmask_b32_e32 v158, v158, v115, vcc
	v_cndmask_b32_e64 v159, v159, 3, vcc
	v_cmp_gt_f32_e32 vcc, v116, v158
	s_nop 1
	v_cndmask_b32_e32 v158, v158, v116, vcc
	v_cndmask_b32_e64 v159, v159, 4, vcc
	v_cmp_gt_f32_e32 vcc, v117, v158
	s_nop 1
	v_cndmask_b32_e32 v158, v158, v117, vcc
	v_cndmask_b32_e64 v159, v159, 5, vcc
	v_cmp_gt_f32_e32 vcc, v118, v158
	s_nop 1
	v_cndmask_b32_e32 v158, v158, v118, vcc
	v_cndmask_b32_e64 v159, v159, 6, vcc
	v_lshlrev_b32_e64 v161, v159, 1
	v_or_b32_e32 v160, v160, v161
	v_cmp_eq_u32_e64 s[56:57], 0, v159
	v_cmp_eq_u32_e64 s[58:59], 1, v159
	v_cmp_eq_u32_e64 s[64:65], 2, v159
	v_cmp_eq_u32_e64 s[68:69], 3, v159
	s_nop 1
	v_cndmask_b32_e64 v112, v112, v134, s[56:57]
	v_cndmask_b32_e64 v113, v113, v134, s[58:59]
	v_cndmask_b32_e64 v114, v114, v134, s[64:65]
	v_cndmask_b32_e64 v115, v115, v134, s[68:69]
	v_cmp_eq_u32_e64 s[56:57], 4, v159
	v_cmp_eq_u32_e64 s[58:59], 5, v159
	v_cmp_eq_u32_e64 s[64:65], 6, v159
	s_nop 1
	v_cndmask_b32_e64 v116, v116, v134, s[56:57]
	v_cndmask_b32_e64 v117, v117, v134, s[58:59]
	v_cndmask_b32_e64 v118, v118, v134, s[64:65]
	v_mov_b32_e32 v158, v134
	v_mov_b32_e32 v159, 0
	v_cmp_gt_f32_e32 vcc, v112, v158
	s_nop 1
	v_cndmask_b32_e32 v158, v158, v112, vcc
	v_cndmask_b32_e64 v159, v159, 0, vcc
	v_cmp_gt_f32_e32 vcc, v113, v158
	s_nop 1
	v_cndmask_b32_e32 v158, v158, v113, vcc
	v_cndmask_b32_e64 v159, v159, 1, vcc
	v_cmp_gt_f32_e32 vcc, v114, v158
	s_nop 1
	v_cndmask_b32_e32 v158, v158, v114, vcc
	v_cndmask_b32_e64 v159, v159, 2, vcc
	v_cmp_gt_f32_e32 vcc, v115, v158
	s_nop 1
	v_cndmask_b32_e32 v158, v158, v115, vcc
	v_cndmask_b32_e64 v159, v159, 3, vcc
	v_cmp_gt_f32_e32 vcc, v116, v158
	s_nop 1
	v_cndmask_b32_e32 v158, v158, v116, vcc
	v_cndmask_b32_e64 v159, v159, 4, vcc
	v_cmp_gt_f32_e32 vcc, v117, v158
	s_nop 1
	v_cndmask_b32_e32 v158, v158, v117, vcc
	v_cndmask_b32_e64 v159, v159, 5, vcc
	v_cmp_gt_f32_e32 vcc, v118, v158
	s_nop 1
	v_cndmask_b32_e32 v158, v158, v118, vcc
	v_cndmask_b32_e64 v159, v159, 6, vcc
	v_lshlrev_b32_e64 v161, v159, 1
	v_or_b32_e32 v160, v160, v161
	v_cmp_eq_u32_e64 s[56:57], 0, v159
	v_cmp_eq_u32_e64 s[58:59], 1, v159
	v_cmp_eq_u32_e64 s[64:65], 2, v159
	v_cmp_eq_u32_e64 s[68:69], 3, v159
	s_nop 1
	v_cndmask_b32_e64 v112, v112, v134, s[56:57]
	v_cndmask_b32_e64 v113, v113, v134, s[58:59]
	v_cndmask_b32_e64 v114, v114, v134, s[64:65]
	v_cndmask_b32_e64 v115, v115, v134, s[68:69]
	v_cmp_eq_u32_e64 s[56:57], 4, v159
	v_cmp_eq_u32_e64 s[58:59], 5, v159
	v_cmp_eq_u32_e64 s[64:65], 6, v159
	s_nop 1
	v_cndmask_b32_e64 v116, v116, v134, s[56:57]
	v_cndmask_b32_e64 v117, v117, v134, s[58:59]
	v_cndmask_b32_e64 v118, v118, v134, s[64:65]
	v_mov_b32_e32 v158, v134
	v_mov_b32_e32 v159, 0
	v_cmp_gt_f32_e32 vcc, v112, v158
	s_nop 1
	v_cndmask_b32_e32 v158, v158, v112, vcc
	v_cndmask_b32_e64 v159, v159, 0, vcc
	v_cmp_gt_f32_e32 vcc, v113, v158
	s_nop 1
	v_cndmask_b32_e32 v158, v158, v113, vcc
	v_cndmask_b32_e64 v159, v159, 1, vcc
	v_cmp_gt_f32_e32 vcc, v114, v158
	s_nop 1
	v_cndmask_b32_e32 v158, v158, v114, vcc
	v_cndmask_b32_e64 v159, v159, 2, vcc
	v_cmp_gt_f32_e32 vcc, v115, v158
	s_nop 1
	v_cndmask_b32_e32 v158, v158, v115, vcc
	v_cndmask_b32_e64 v159, v159, 3, vcc
	v_cmp_gt_f32_e32 vcc, v116, v158
	s_nop 1
	v_cndmask_b32_e32 v158, v158, v116, vcc
	v_cndmask_b32_e64 v159, v159, 4, vcc
	v_cmp_gt_f32_e32 vcc, v117, v158
	s_nop 1
	v_cndmask_b32_e32 v158, v158, v117, vcc
	v_cndmask_b32_e64 v159, v159, 5, vcc
	v_cmp_gt_f32_e32 vcc, v118, v158
	s_nop 1
	v_cndmask_b32_e32 v158, v158, v118, vcc
	v_cndmask_b32_e64 v159, v159, 6, vcc
	v_lshlrev_b32_e64 v161, v159, 1
	v_or_b32_e32 v160, v160, v161
	v_and_b32_e32 v161, 15, v230
	v_lshlrev_b32_e32 v161, 2, v161
	ds_bpermute_b32 v152, v161, v160
	s_waitcnt lgkmcnt(0)
	s_add_u32 s28, s24, 4096
	s_addc_u32 s29, s25, 0
	global_load_dwordx4 v[96:99], v142, s[28:29] offset:0
	global_load_dwordx4 v[100:103], v142, s[28:29] offset:16
	global_load_dwordx4 v[104:107], v142, s[28:29] offset:32
	global_load_dwordx4 v[108:111], v142, s[28:29] offset:48
	s_waitcnt vmcnt(0)
	v_lshlrev_b32_e32 v32, 16, v96
	v_and_b32_e32 v33, 0xffff0000, v96
	v_lshlrev_b32_e32 v34, 16, v97
	v_and_b32_e32 v35, 0xffff0000, v97
	v_lshlrev_b32_e32 v36, 16, v98
	v_and_b32_e32 v37, 0xffff0000, v98
	v_lshlrev_b32_e32 v38, 16, v99
	v_and_b32_e32 v39, 0xffff0000, v99
	v_lshlrev_b32_e32 v40, 16, v100
	v_and_b32_e32 v41, 0xffff0000, v100
	v_lshlrev_b32_e32 v42, 16, v101
	v_and_b32_e32 v43, 0xffff0000, v101
	v_lshlrev_b32_e32 v44, 16, v102
	v_and_b32_e32 v45, 0xffff0000, v102
	v_lshlrev_b32_e32 v46, 16, v103
	v_and_b32_e32 v47, 0xffff0000, v103
	v_lshlrev_b32_e32 v48, 16, v104
	v_and_b32_e32 v49, 0xffff0000, v104
	v_lshlrev_b32_e32 v50, 16, v105
	v_and_b32_e32 v51, 0xffff0000, v105
	v_lshlrev_b32_e32 v52, 16, v106
	v_and_b32_e32 v53, 0xffff0000, v106
	v_lshlrev_b32_e32 v54, 16, v107
	v_and_b32_e32 v55, 0xffff0000, v107
	v_lshlrev_b32_e32 v56, 16, v108
	v_and_b32_e32 v57, 0xffff0000, v108
	v_lshlrev_b32_e32 v58, 16, v109
	v_and_b32_e32 v59, 0xffff0000, v109
	v_lshlrev_b32_e32 v60, 16, v110
	v_and_b32_e32 v61, 0xffff0000, v110
	v_lshlrev_b32_e32 v62, 16, v111
	v_and_b32_e32 v63, 0xffff0000, v111
	s_nop 1
	v_mfma_f32_16x16x4_f32 v[112:115], v0, v32, 0
	v_mfma_f32_16x16x4_f32 v[112:115], v1, v33, v[112:115]
	v_mfma_f32_16x16x4_f32 v[112:115], v2, v34, v[112:115]
	v_mfma_f32_16x16x4_f32 v[112:115], v3, v35, v[112:115]
	v_mfma_f32_16x16x4_f32 v[112:115], v4, v36, v[112:115]
	v_mfma_f32_16x16x4_f32 v[112:115], v5, v37, v[112:115]
	v_mfma_f32_16x16x4_f32 v[112:115], v6, v38, v[112:115]
	v_mfma_f32_16x16x4_f32 v[112:115], v7, v39, v[112:115]
	v_mfma_f32_16x16x4_f32 v[112:115], v8, v40, v[112:115]
	v_mfma_f32_16x16x4_f32 v[112:115], v9, v41, v[112:115]
	v_mfma_f32_16x16x4_f32 v[112:115], v10, v42, v[112:115]
	v_mfma_f32_16x16x4_f32 v[112:115], v11, v43, v[112:115]
	v_mfma_f32_16x16x4_f32 v[112:115], v12, v44, v[112:115]
	v_mfma_f32_16x16x4_f32 v[112:115], v13, v45, v[112:115]
	v_mfma_f32_16x16x4_f32 v[112:115], v14, v46, v[112:115]
	v_mfma_f32_16x16x4_f32 v[112:115], v15, v47, v[112:115]
	v_mfma_f32_16x16x4_f32 v[112:115], v16, v48, v[112:115]
	v_mfma_f32_16x16x4_f32 v[112:115], v17, v49, v[112:115]
	v_mfma_f32_16x16x4_f32 v[112:115], v18, v50, v[112:115]
	v_mfma_f32_16x16x4_f32 v[112:115], v19, v51, v[112:115]
	v_mfma_f32_16x16x4_f32 v[112:115], v20, v52, v[112:115]
	v_mfma_f32_16x16x4_f32 v[112:115], v21, v53, v[112:115]
	v_mfma_f32_16x16x4_f32 v[112:115], v22, v54, v[112:115]
	v_mfma_f32_16x16x4_f32 v[112:115], v23, v55, v[112:115]
	v_mfma_f32_16x16x4_f32 v[112:115], v24, v56, v[112:115]
	v_mfma_f32_16x16x4_f32 v[112:115], v25, v57, v[112:115]
	v_mfma_f32_16x16x4_f32 v[112:115], v26, v58, v[112:115]
	v_mfma_f32_16x16x4_f32 v[112:115], v27, v59, v[112:115]
	v_mfma_f32_16x16x4_f32 v[112:115], v28, v60, v[112:115]
	v_mfma_f32_16x16x4_f32 v[112:115], v29, v61, v[112:115]
	v_mfma_f32_16x16x4_f32 v[112:115], v30, v62, v[112:115]
	v_mfma_f32_16x16x4_f32 v[112:115], v31, v63, v[112:115]
	s_nop 10
	ds_bpermute_b32 v116, v228, v112
	ds_bpermute_b32 v117, v228, v113
	ds_bpermute_b32 v118, v228, v114
	ds_bpermute_b32 v119, v228, v115
	s_waitcnt lgkmcnt(0)
	s_cmp_gt_u32 s15, 0
	s_cselect_b64 s[56:57], -1, 0
	v_cndmask_b32_e64 v112, v134, v112, s[56:57]
	s_cmp_gt_u32 s15, 1
	s_cselect_b64 s[58:59], -1, 0
	v_cndmask_b32_e64 v113, v134, v113, s[58:59]
	s_cmp_gt_u32 s15, 2
	s_cselect_b64 s[64:65], -1, 0
	v_cndmask_b32_e64 v114, v134, v114, s[64:65]
	s_cmp_gt_u32 s15, 3
	s_cselect_b64 s[68:69], -1, 0
	v_cndmask_b32_e64 v115, v134, v115, s[68:69]
	s_cmp_gt_u32 s15, 4
	s_cselect_b64 s[56:57], -1, 0
	v_cndmask_b32_e64 v116, v134, v116, s[56:57]
	s_cmp_gt_u32 s15, 5
	s_cselect_b64 s[58:59], -1, 0
	v_cndmask_b32_e64 v117, v134, v117, s[58:59]
	s_cmp_gt_u32 s15, 6
	s_cselect_b64 s[64:65], -1, 0
	v_cndmask_b32_e64 v118, v134, v118, s[64:65]
	v_mov_b32_e32 v160, 0
	v_mov_b32_e32 v158, v134
	v_mov_b32_e32 v159, 0
	v_cmp_gt_f32_e32 vcc, v112, v158
	s_nop 1
	v_cndmask_b32_e32 v158, v158, v112, vcc
	v_cndmask_b32_e64 v159, v159, 0, vcc
	v_cmp_gt_f32_e32 vcc, v113, v158
	s_nop 1
	v_cndmask_b32_e32 v158, v158, v113, vcc
	v_cndmask_b32_e64 v159, v159, 1, vcc
	v_cmp_gt_f32_e32 vcc, v114, v158
	s_nop 1
	v_cndmask_b32_e32 v158, v158, v114, vcc
	v_cndmask_b32_e64 v159, v159, 2, vcc
	v_cmp_gt_f32_e32 vcc, v115, v158
	s_nop 1
	v_cndmask_b32_e32 v158, v158, v115, vcc
	v_cndmask_b32_e64 v159, v159, 3, vcc
	v_cmp_gt_f32_e32 vcc, v116, v158
	s_nop 1
	v_cndmask_b32_e32 v158, v158, v116, vcc
	v_cndmask_b32_e64 v159, v159, 4, vcc
	v_cmp_gt_f32_e32 vcc, v117, v158
	s_nop 1
	v_cndmask_b32_e32 v158, v158, v117, vcc
	v_cndmask_b32_e64 v159, v159, 5, vcc
	v_cmp_gt_f32_e32 vcc, v118, v158
	s_nop 1
	v_cndmask_b32_e32 v158, v158, v118, vcc
	v_cndmask_b32_e64 v159, v159, 6, vcc
	v_lshlrev_b32_e64 v161, v159, 1
	v_or_b32_e32 v160, v160, v161
	v_cmp_eq_u32_e64 s[56:57], 0, v159
	v_cmp_eq_u32_e64 s[58:59], 1, v159
	v_cmp_eq_u32_e64 s[64:65], 2, v159
	v_cmp_eq_u32_e64 s[68:69], 3, v159
	s_nop 1
	v_cndmask_b32_e64 v112, v112, v134, s[56:57]
	v_cndmask_b32_e64 v113, v113, v134, s[58:59]
	v_cndmask_b32_e64 v114, v114, v134, s[64:65]
	v_cndmask_b32_e64 v115, v115, v134, s[68:69]
	v_cmp_eq_u32_e64 s[56:57], 4, v159
	v_cmp_eq_u32_e64 s[58:59], 5, v159
	v_cmp_eq_u32_e64 s[64:65], 6, v159
	s_nop 1
	v_cndmask_b32_e64 v116, v116, v134, s[56:57]
	v_cndmask_b32_e64 v117, v117, v134, s[58:59]
	v_cndmask_b32_e64 v118, v118, v134, s[64:65]
	v_mov_b32_e32 v158, v134
	v_mov_b32_e32 v159, 0
	v_cmp_gt_f32_e32 vcc, v112, v158
	s_nop 1
	v_cndmask_b32_e32 v158, v158, v112, vcc
	v_cndmask_b32_e64 v159, v159, 0, vcc
	v_cmp_gt_f32_e32 vcc, v113, v158
	s_nop 1
	v_cndmask_b32_e32 v158, v158, v113, vcc
	v_cndmask_b32_e64 v159, v159, 1, vcc
	v_cmp_gt_f32_e32 vcc, v114, v158
	s_nop 1
	v_cndmask_b32_e32 v158, v158, v114, vcc
	v_cndmask_b32_e64 v159, v159, 2, vcc
	v_cmp_gt_f32_e32 vcc, v115, v158
	s_nop 1
	v_cndmask_b32_e32 v158, v158, v115, vcc
	v_cndmask_b32_e64 v159, v159, 3, vcc
	v_cmp_gt_f32_e32 vcc, v116, v158
	s_nop 1
	v_cndmask_b32_e32 v158, v158, v116, vcc
	v_cndmask_b32_e64 v159, v159, 4, vcc
	v_cmp_gt_f32_e32 vcc, v117, v158
	s_nop 1
	v_cndmask_b32_e32 v158, v158, v117, vcc
	v_cndmask_b32_e64 v159, v159, 5, vcc
	v_cmp_gt_f32_e32 vcc, v118, v158
	s_nop 1
	v_cndmask_b32_e32 v158, v158, v118, vcc
	v_cndmask_b32_e64 v159, v159, 6, vcc
	v_lshlrev_b32_e64 v161, v159, 1
	v_or_b32_e32 v160, v160, v161
	v_cmp_eq_u32_e64 s[56:57], 0, v159
	v_cmp_eq_u32_e64 s[58:59], 1, v159
	v_cmp_eq_u32_e64 s[64:65], 2, v159
	v_cmp_eq_u32_e64 s[68:69], 3, v159
	s_nop 1
	v_cndmask_b32_e64 v112, v112, v134, s[56:57]
	v_cndmask_b32_e64 v113, v113, v134, s[58:59]
	v_cndmask_b32_e64 v114, v114, v134, s[64:65]
	v_cndmask_b32_e64 v115, v115, v134, s[68:69]
	v_cmp_eq_u32_e64 s[56:57], 4, v159
	v_cmp_eq_u32_e64 s[58:59], 5, v159
	v_cmp_eq_u32_e64 s[64:65], 6, v159
	s_nop 1
	v_cndmask_b32_e64 v116, v116, v134, s[56:57]
	v_cndmask_b32_e64 v117, v117, v134, s[58:59]
	v_cndmask_b32_e64 v118, v118, v134, s[64:65]
	v_mov_b32_e32 v158, v134
	v_mov_b32_e32 v159, 0
	v_cmp_gt_f32_e32 vcc, v112, v158
	s_nop 1
	v_cndmask_b32_e32 v158, v158, v112, vcc
	v_cndmask_b32_e64 v159, v159, 0, vcc
	v_cmp_gt_f32_e32 vcc, v113, v158
	s_nop 1
	v_cndmask_b32_e32 v158, v158, v113, vcc
	v_cndmask_b32_e64 v159, v159, 1, vcc
	v_cmp_gt_f32_e32 vcc, v114, v158
	s_nop 1
	v_cndmask_b32_e32 v158, v158, v114, vcc
	v_cndmask_b32_e64 v159, v159, 2, vcc
	v_cmp_gt_f32_e32 vcc, v115, v158
	s_nop 1
	v_cndmask_b32_e32 v158, v158, v115, vcc
	v_cndmask_b32_e64 v159, v159, 3, vcc
	v_cmp_gt_f32_e32 vcc, v116, v158
	s_nop 1
	v_cndmask_b32_e32 v158, v158, v116, vcc
	v_cndmask_b32_e64 v159, v159, 4, vcc
	v_cmp_gt_f32_e32 vcc, v117, v158
	s_nop 1
	v_cndmask_b32_e32 v158, v158, v117, vcc
	v_cndmask_b32_e64 v159, v159, 5, vcc
	v_cmp_gt_f32_e32 vcc, v118, v158
	s_nop 1
	v_cndmask_b32_e32 v158, v158, v118, vcc
	v_cndmask_b32_e64 v159, v159, 6, vcc
	v_lshlrev_b32_e64 v161, v159, 1
	v_or_b32_e32 v160, v160, v161
	v_and_b32_e32 v161, 15, v230
	v_lshlrev_b32_e32 v161, 2, v161
	ds_bpermute_b32 v153, v161, v160
	s_waitcnt lgkmcnt(0)
	s_branch .Lmb_sel_done
.Lmb_sel_small:
	s_lshl_b32 s30, 1, s15
	s_sub_u32 s30, s30, 1
	v_mov_b32_e32 v152, s30
	v_mov_b32_e32 v153, s30
.Lmb_sel_done:
	v_lshl_add_u32 v142, v141, 4, v140
	s_add_u32 s28, s24, 0
	s_addc_u32 s29, s25, 0
	global_load_dwordx4 v[64:67], v142, s[28:29] offset:0
	global_load_dwordx4 v[68:71], v142, s[28:29] offset:64
	global_load_dwordx4 v[72:75], v142, s[28:29] offset:128
	global_load_dwordx4 v[76:79], v142, s[28:29] offset:192
	s_add_u32 s28, s24, 4096
	s_addc_u32 s29, s25, 0
	global_load_dwordx4 v[80:83], v142, s[28:29] offset:0
	global_load_dwordx4 v[84:87], v142, s[28:29] offset:64
	global_load_dwordx4 v[88:91], v142, s[28:29] offset:128
	global_load_dwordx4 v[92:95], v142, s[28:29] offset:192
	s_waitcnt vmcnt(0)
	v_lshlrev_b32_e32 v143, 16, v64
	v_and_b32_e32 v157, 0xffff0000, v64
	v_mul_f32_e32 v143, s38, v143
	v_mul_f32_e32 v157, s38, v157
	v_cvt_pk_bf16_f32 v64, v143, v157
	v_lshlrev_b32_e32 v143, 16, v65
	v_and_b32_e32 v157, 0xffff0000, v65
	v_mul_f32_e32 v143, s38, v143
	v_mul_f32_e32 v157, s38, v157
	v_cvt_pk_bf16_f32 v65, v143, v157
	v_lshlrev_b32_e32 v143, 16, v66
	v_and_b32_e32 v157, 0xffff0000, v66
	v_mul_f32_e32 v143, s38, v143
	v_mul_f32_e32 v157, s38, v157
	v_cvt_pk_bf16_f32 v66, v143, v157
	v_lshlrev_b32_e32 v143, 16, v67
	v_and_b32_e32 v157, 0xffff0000, v67
	v_mul_f32_e32 v143, s38, v143
	v_mul_f32_e32 v157, s38, v157
	v_cvt_pk_bf16_f32 v67, v143, v157
	v_lshlrev_b32_e32 v143, 16, v68
	v_and_b32_e32 v157, 0xffff0000, v68
	v_mul_f32_e32 v143, s38, v143
	v_mul_f32_e32 v157, s38, v157
	v_cvt_pk_bf16_f32 v68, v143, v157
	v_lshlrev_b32_e32 v143, 16, v69
	v_and_b32_e32 v157, 0xffff0000, v69
	v_mul_f32_e32 v143, s38, v143
	v_mul_f32_e32 v157, s38, v157
	v_cvt_pk_bf16_f32 v69, v143, v157
	v_lshlrev_b32_e32 v143, 16, v70
	v_and_b32_e32 v157, 0xffff0000, v70
	v_mul_f32_e32 v143, s38, v143
	v_mul_f32_e32 v157, s38, v157
	v_cvt_pk_bf16_f32 v70, v143, v157
	v_lshlrev_b32_e32 v143, 16, v71
	v_and_b32_e32 v157, 0xffff0000, v71
	v_mul_f32_e32 v143, s38, v143
	v_mul_f32_e32 v157, s38, v157
	v_cvt_pk_bf16_f32 v71, v143, v157
	v_lshlrev_b32_e32 v143, 16, v72
	v_and_b32_e32 v157, 0xffff0000, v72
	v_mul_f32_e32 v143, s38, v143
	v_mul_f32_e32 v157, s38, v157
	v_cvt_pk_bf16_f32 v72, v143, v157
	v_lshlrev_b32_e32 v143, 16, v73
	v_and_b32_e32 v157, 0xffff0000, v73
	v_mul_f32_e32 v143, s38, v143
	v_mul_f32_e32 v157, s38, v157
	v_cvt_pk_bf16_f32 v73, v143, v157
	v_lshlrev_b32_e32 v143, 16, v74
	v_and_b32_e32 v157, 0xffff0000, v74
	v_mul_f32_e32 v143, s38, v143
	v_mul_f32_e32 v157, s38, v157
	v_cvt_pk_bf16_f32 v74, v143, v157
	v_lshlrev_b32_e32 v143, 16, v75
	v_and_b32_e32 v157, 0xffff0000, v75
	v_mul_f32_e32 v143, s38, v143
	v_mul_f32_e32 v157, s38, v157
	v_cvt_pk_bf16_f32 v75, v143, v157
	v_lshlrev_b32_e32 v143, 16, v76
	v_and_b32_e32 v157, 0xffff0000, v76
	v_mul_f32_e32 v143, s38, v143
	v_mul_f32_e32 v157, s38, v157
	v_cvt_pk_bf16_f32 v76, v143, v157
	v_lshlrev_b32_e32 v143, 16, v77
	v_and_b32_e32 v157, 0xffff0000, v77
	v_mul_f32_e32 v143, s38, v143
	v_mul_f32_e32 v157, s38, v157
	v_cvt_pk_bf16_f32 v77, v143, v157
	v_lshlrev_b32_e32 v143, 16, v78
	v_and_b32_e32 v157, 0xffff0000, v78
	v_mul_f32_e32 v143, s38, v143
	v_mul_f32_e32 v157, s38, v157
	v_cvt_pk_bf16_f32 v78, v143, v157
	v_lshlrev_b32_e32 v143, 16, v79
	v_and_b32_e32 v157, 0xffff0000, v79
	v_mul_f32_e32 v143, s38, v143
	v_mul_f32_e32 v157, s38, v157
	v_cvt_pk_bf16_f32 v79, v143, v157
	v_lshlrev_b32_e32 v143, 16, v80
	v_and_b32_e32 v157, 0xffff0000, v80
	v_mul_f32_e32 v143, s38, v143
	v_mul_f32_e32 v157, s38, v157
	v_cvt_pk_bf16_f32 v80, v143, v157
	v_lshlrev_b32_e32 v143, 16, v81
	v_and_b32_e32 v157, 0xffff0000, v81
	v_mul_f32_e32 v143, s38, v143
	v_mul_f32_e32 v157, s38, v157
	v_cvt_pk_bf16_f32 v81, v143, v157
	v_lshlrev_b32_e32 v143, 16, v82
	v_and_b32_e32 v157, 0xffff0000, v82
	v_mul_f32_e32 v143, s38, v143
	v_mul_f32_e32 v157, s38, v157
	v_cvt_pk_bf16_f32 v82, v143, v157
	v_lshlrev_b32_e32 v143, 16, v83
	v_and_b32_e32 v157, 0xffff0000, v83
	v_mul_f32_e32 v143, s38, v143
	v_mul_f32_e32 v157, s38, v157
	v_cvt_pk_bf16_f32 v83, v143, v157
	v_lshlrev_b32_e32 v143, 16, v84
	v_and_b32_e32 v157, 0xffff0000, v84
	v_mul_f32_e32 v143, s38, v143
	v_mul_f32_e32 v157, s38, v157
	v_cvt_pk_bf16_f32 v84, v143, v157
	v_lshlrev_b32_e32 v143, 16, v85
	v_and_b32_e32 v157, 0xffff0000, v85
	v_mul_f32_e32 v143, s38, v143
	v_mul_f32_e32 v157, s38, v157
	v_cvt_pk_bf16_f32 v85, v143, v157
	v_lshlrev_b32_e32 v143, 16, v86
	v_and_b32_e32 v157, 0xffff0000, v86
	v_mul_f32_e32 v143, s38, v143
	v_mul_f32_e32 v157, s38, v157
	v_cvt_pk_bf16_f32 v86, v143, v157
	v_lshlrev_b32_e32 v143, 16, v87
	v_and_b32_e32 v157, 0xffff0000, v87
	v_mul_f32_e32 v143, s38, v143
	v_mul_f32_e32 v157, s38, v157
	v_cvt_pk_bf16_f32 v87, v143, v157
	v_lshlrev_b32_e32 v143, 16, v88
	v_and_b32_e32 v157, 0xffff0000, v88
	v_mul_f32_e32 v143, s38, v143
	v_mul_f32_e32 v157, s38, v157
	v_cvt_pk_bf16_f32 v88, v143, v157
	v_lshlrev_b32_e32 v143, 16, v89
	v_and_b32_e32 v157, 0xffff0000, v89
	v_mul_f32_e32 v143, s38, v143
	v_mul_f32_e32 v157, s38, v157
	v_cvt_pk_bf16_f32 v89, v143, v157
	v_lshlrev_b32_e32 v143, 16, v90
	v_and_b32_e32 v157, 0xffff0000, v90
	v_mul_f32_e32 v143, s38, v143
	v_mul_f32_e32 v157, s38, v157
	v_cvt_pk_bf16_f32 v90, v143, v157
	v_lshlrev_b32_e32 v143, 16, v91
	v_and_b32_e32 v157, 0xffff0000, v91
	v_mul_f32_e32 v143, s38, v143
	v_mul_f32_e32 v157, s38, v157
	v_cvt_pk_bf16_f32 v91, v143, v157
	v_lshlrev_b32_e32 v143, 16, v92
	v_and_b32_e32 v157, 0xffff0000, v92
	v_mul_f32_e32 v143, s38, v143
	v_mul_f32_e32 v157, s38, v157
	v_cvt_pk_bf16_f32 v92, v143, v157
	v_lshlrev_b32_e32 v143, 16, v93
	v_and_b32_e32 v157, 0xffff0000, v93
	v_mul_f32_e32 v143, s38, v143
	v_mul_f32_e32 v157, s38, v157
	v_cvt_pk_bf16_f32 v93, v143, v157
	v_lshlrev_b32_e32 v143, 16, v94
	v_and_b32_e32 v157, 0xffff0000, v94
	v_mul_f32_e32 v143, s38, v143
	v_mul_f32_e32 v157, s38, v157
	v_cvt_pk_bf16_f32 v94, v143, v157
	v_lshlrev_b32_e32 v143, 16, v95
	v_and_b32_e32 v157, 0xffff0000, v95
	v_mul_f32_e32 v143, s38, v143
	v_mul_f32_e32 v157, s38, v157
	v_cvt_pk_bf16_f32 v95, v143, v157
	v_mov_b32_e32 v0, 0
	v_mov_b32_e32 v1, 0
	v_mov_b32_e32 v2, 0
	v_mov_b32_e32 v3, 0
	v_mov_b32_e32 v4, 0
	v_mov_b32_e32 v5, 0
	v_mov_b32_e32 v6, 0
	v_mov_b32_e32 v7, 0
	v_mov_b32_e32 v8, 0
	v_mov_b32_e32 v9, 0
	v_mov_b32_e32 v10, 0
	v_mov_b32_e32 v11, 0
	v_mov_b32_e32 v12, 0
	v_mov_b32_e32 v13, 0
	v_mov_b32_e32 v14, 0
	v_mov_b32_e32 v15, 0
	v_mov_b32_e32 v16, 0
	v_mov_b32_e32 v17, 0
	v_mov_b32_e32 v18, 0
	v_mov_b32_e32 v19, 0
	v_mov_b32_e32 v20, 0
	v_mov_b32_e32 v21, 0
	v_mov_b32_e32 v22, 0
	v_mov_b32_e32 v23, 0
	v_mov_b32_e32 v24, 0
	v_mov_b32_e32 v25, 0
	v_mov_b32_e32 v26, 0
	v_mov_b32_e32 v27, 0
	v_mov_b32_e32 v28, 0
	v_mov_b32_e32 v29, 0
	v_mov_b32_e32 v30, 0
	v_mov_b32_e32 v31, 0
	v_mov_b32_e32 v32, 0
	v_mov_b32_e32 v33, 0
	v_mov_b32_e32 v34, 0
	v_mov_b32_e32 v35, 0
	v_mov_b32_e32 v36, 0
	v_mov_b32_e32 v37, 0
	v_mov_b32_e32 v38, 0
	v_mov_b32_e32 v39, 0
	v_mov_b32_e32 v40, 0
	v_mov_b32_e32 v41, 0
	v_mov_b32_e32 v42, 0
	v_mov_b32_e32 v43, 0
	v_mov_b32_e32 v44, 0
	v_mov_b32_e32 v45, 0
	v_mov_b32_e32 v46, 0
	v_mov_b32_e32 v47, 0
	v_mov_b32_e32 v48, 0
	v_mov_b32_e32 v49, 0
	v_mov_b32_e32 v50, 0
	v_mov_b32_e32 v51, 0
	v_mov_b32_e32 v52, 0
	v_mov_b32_e32 v53, 0
	v_mov_b32_e32 v54, 0
	v_mov_b32_e32 v55, 0
	v_mov_b32_e32 v56, 0
	v_mov_b32_e32 v57, 0
	v_mov_b32_e32 v58, 0
	v_mov_b32_e32 v59, 0
	v_mov_b32_e32 v60, 0
	v_mov_b32_e32 v61, 0
	v_mov_b32_e32 v62, 0
	v_mov_b32_e32 v63, 0
	v_mov_b32_e32 v148, 0xf149f2ca
	v_mov_b32_e32 v150, 0
	v_mov_b32_e32 v149, 0xf149f2ca
	v_mov_b32_e32 v151, 0
	v_xor_b32_e32 v130, 65536, v130
	v_xor_b32_e32 v131, 65536, v131
	s_waitcnt vmcnt(0)
	ds_write_b128 v130, v[168:171]
	ds_write_b128 v130, v[172:175] offset:8704
	ds_write_b128 v131, v[176:179]
	ds_write_b128 v131, v[180:183] offset:9216
	v_xor_b32_e32 v130, 65536, v130
	v_xor_b32_e32 v131, 65536, v131
	s_mov_b32 s30, 1
	s_lshl_b32 s33, s15, 2
	s_add_u32 s33, s33, s30
	s_sub_u32 s31, s30, 4
	s_cmp_lt_u32 s30, 4
	s_cselect_b32 s31, s33, s31
	s_lshl_b32 s33, s31, 15
	s_add_u32 s33, s33, 0x800000
	s_add_u32 s26, s8, s33
	s_addc_u32 s27, s9, 0
	global_load_dwordx4 v[168:171], v132, s[26:27]
	global_load_dwordx4 v[172:175], v133, s[26:27]
	s_add_u32 s26, s26, 0x800000
	s_addc_u32 s27, s27, 0
	global_load_dwordx4 v[176:179], v132, s[26:27]
	global_load_dwordx4 v[180:183], v133, s[26:27]
	s_mov_b32 s23, 0
	s_waitcnt lgkmcnt(0)
	s_barrier
.Lmb_loop:
	s_add_u32 s30, s23, 1
	s_cmp_ge_u32 s30, s22
	s_cbranch_scc1 .Lmb_nostage
	s_waitcnt vmcnt(0)
	ds_write_b128 v130, v[168:171]
	ds_write_b128 v130, v[172:175] offset:8704
	ds_write_b128 v131, v[176:179]
	ds_write_b128 v131, v[180:183] offset:9216
	s_add_u32 s30, s23, 2
	s_cmp_ge_u32 s30, s22
	s_cbranch_scc1 .Lmb_nostage
	s_lshl_b32 s33, s15, 2
	s_add_u32 s33, s33, s30
	s_sub_u32 s31, s30, 4
	s_cmp_lt_u32 s30, 4
	s_cselect_b32 s31, s33, s31
	s_lshl_b32 s33, s31, 15
	s_add_u32 s33, s33, 0x800000
	s_add_u32 s26, s8, s33
	s_addc_u32 s27, s9, 0
	global_load_dwordx4 v[168:171], v132, s[26:27]
	global_load_dwordx4 v[172:175], v133, s[26:27]
	s_add_u32 s26, s26, 0x800000
	s_addc_u32 s27, s27, 0
	global_load_dwordx4 v[176:179], v132, s[26:27]
	global_load_dwordx4 v[180:183], v133, s[26:27]
.Lmb_nostage:
	s_cmp_ge_u32 s23, 4
	s_cbranch_scc1 .Lmb_past
	s_lshl_b32 s30, s23, 6
	s_lshl_b32 s31, s7, 5
	s_add_u32 s31, s31, 31
	s_cmp_gt_u32 s30, s31
	s_cbranch_scc1 .Lmb_iter_end
	v_max_f32_e32 v146, s36, v148
	v_max_f32_e32 v147, s36, v149
	v_subrev_u32_e32 v138, s30, v137
	v_add_u32_e32 v139, 16, v138
	s_branch .Lmb_S
.Lmb_past:
	s_sub_u32 s30, s23, 4
	s_lshr_b32 s30, s30, 2
	v_lshrrev_b32_e32 v158, s30, v152
	v_lshrrev_b32_e32 v159, s30, v153
	v_and_b32_e32 v158, 1, v158
	v_and_b32_e32 v159, 1, v159
	v_cmp_eq_u32_e64 s[56:57], 1, v158
	v_cmp_eq_u32_e64 s[58:59], 1, v159
	v_max_f32_e32 v160, s36, v148
	v_max_f32_e32 v161, s36, v149
	v_cndmask_b32_e64 v146, v135, v160, s[56:57]
	v_cndmask_b32_e64 v147, v135, v161, s[58:59]
.Lmb_S:
	v_xor_b32_e32 v184, 0x80000000, v146
	v_xor_b32_e32 v185, 0x80000000, v146
	v_xor_b32_e32 v186, 0x80000000, v146
	v_xor_b32_e32 v187, 0x80000000, v146
	v_xor_b32_e32 v188, 0x80000000, v147
	v_xor_b32_e32 v189, 0x80000000, v147
	v_xor_b32_e32 v190, 0x80000000, v147
	v_xor_b32_e32 v191, 0x80000000, v147
	ds_read_b128 v[204:207], v128 offset:0
	ds_read_b128 v[208:211], v128 offset:64
	ds_read_b128 v[212:215], v128 offset:128
	ds_read_b128 v[216:219], v128 offset:192
	ds_read_b128 v[240:243], v128 offset:4352
	ds_read_b128 v[244:247], v128 offset:4416
	ds_read_b128 v[248:251], v128 offset:4480
	ds_read_b128 v[252:255], v128 offset:4544
	s_waitcnt lgkmcnt(7)
	v_mfma_f32_16x16x32_bf16 v[96:99], v[204:207], v[64:67], v[184:187]
	v_mfma_f32_16x16x32_bf16 v[112:115], v[204:207], v[80:83], v[188:191]
	ds_read_b128 v[204:207], v128 offset:8704
	s_waitcnt lgkmcnt(7)
	v_mfma_f32_16x16x32_bf16 v[96:99], v[208:211], v[68:71], v[96:99]
	v_mfma_f32_16x16x32_bf16 v[112:115], v[208:211], v[84:87], v[112:115]
	ds_read_b128 v[208:211], v128 offset:8768
	s_waitcnt lgkmcnt(7)
	v_mfma_f32_16x16x32_bf16 v[96:99], v[212:215], v[72:75], v[96:99]
	v_mfma_f32_16x16x32_bf16 v[112:115], v[212:215], v[88:91], v[112:115]
	ds_read_b128 v[212:215], v128 offset:8832
	s_waitcnt lgkmcnt(7)
	v_mfma_f32_16x16x32_bf16 v[96:99], v[216:219], v[76:79], v[96:99]
	v_mfma_f32_16x16x32_bf16 v[112:115], v[216:219], v[92:95], v[112:115]
	ds_read_b128 v[216:219], v128 offset:8896
	s_waitcnt lgkmcnt(7)
	v_mfma_f32_16x16x32_bf16 v[100:103], v[240:243], v[64:67], v[184:187]
	v_mfma_f32_16x16x32_bf16 v[116:119], v[240:243], v[80:83], v[188:191]
	ds_read_b128 v[240:243], v128 offset:13056
	s_waitcnt lgkmcnt(7)
	v_mfma_f32_16x16x32_bf16 v[100:103], v[244:247], v[68:71], v[100:103]
	v_mfma_f32_16x16x32_bf16 v[116:119], v[244:247], v[84:87], v[116:119]
	ds_read_b128 v[244:247], v128 offset:13120
	s_waitcnt lgkmcnt(7)
	v_mfma_f32_16x16x32_bf16 v[100:103], v[248:251], v[72:75], v[100:103]
	v_mfma_f32_16x16x32_bf16 v[116:119], v[248:251], v[88:91], v[116:119]
	ds_read_b128 v[248:251], v128 offset:13184
	s_waitcnt lgkmcnt(7)
	v_mfma_f32_16x16x32_bf16 v[100:103], v[252:255], v[76:79], v[100:103]
	v_mfma_f32_16x16x32_bf16 v[116:119], v[252:255], v[92:95], v[116:119]
	ds_read_b128 v[252:255], v128 offset:13248
	s_waitcnt lgkmcnt(7)
	v_mfma_f32_16x16x32_bf16 v[104:107], v[204:207], v[64:67], v[184:187]
	v_mfma_f32_16x16x32_bf16 v[120:123], v[204:207], v[80:83], v[188:191]
	s_waitcnt lgkmcnt(6)
	v_mfma_f32_16x16x32_bf16 v[104:107], v[208:211], v[68:71], v[104:107]
	v_mfma_f32_16x16x32_bf16 v[120:123], v[208:211], v[84:87], v[120:123]
	s_waitcnt lgkmcnt(5)
	v_mfma_f32_16x16x32_bf16 v[104:107], v[212:215], v[72:75], v[104:107]
	v_mfma_f32_16x16x32_bf16 v[120:123], v[212:215], v[88:91], v[120:123]
	s_waitcnt lgkmcnt(4)
	v_mfma_f32_16x16x32_bf16 v[104:107], v[216:219], v[76:79], v[104:107]
	v_mfma_f32_16x16x32_bf16 v[120:123], v[216:219], v[92:95], v[120:123]
	s_waitcnt lgkmcnt(3)
	v_mfma_f32_16x16x32_bf16 v[108:111], v[240:243], v[64:67], v[184:187]
	v_mfma_f32_16x16x32_bf16 v[124:127], v[240:243], v[80:83], v[188:191]
	s_waitcnt lgkmcnt(2)
	v_mfma_f32_16x16x32_bf16 v[108:111], v[244:247], v[68:71], v[108:111]
	v_mfma_f32_16x16x32_bf16 v[124:127], v[244:247], v[84:87], v[124:127]
	s_waitcnt lgkmcnt(1)
	v_mfma_f32_16x16x32_bf16 v[108:111], v[248:251], v[72:75], v[108:111]
	v_mfma_f32_16x16x32_bf16 v[124:127], v[248:251], v[88:91], v[124:127]
	s_waitcnt lgkmcnt(0)
	v_mfma_f32_16x16x32_bf16 v[108:111], v[252:255], v[76:79], v[108:111]
	v_mfma_f32_16x16x32_bf16 v[124:127], v[252:255], v[92:95], v[124:127]
	ds_read_b64_tr_b16 v[204:205], v129 offset:0
	ds_read_b64_tr_b16 v[206:207], v129 offset:4608
	ds_read_b64_tr_b16 v[208:209], v129 offset:32
	ds_read_b64_tr_b16 v[210:211], v129 offset:4640
	ds_read_b64_tr_b16 v[212:213], v129 offset:64
	ds_read_b64_tr_b16 v[214:215], v129 offset:4672
	ds_read_b64_tr_b16 v[216:217], v129 offset:96
	ds_read_b64_tr_b16 v[218:219], v129 offset:4704
	ds_read_b64_tr_b16 v[240:241], v129 offset:128
	ds_read_b64_tr_b16 v[242:243], v129 offset:4736
	ds_read_b64_tr_b16 v[244:245], v129 offset:160
	ds_read_b64_tr_b16 v[246:247], v129 offset:4768
	s_cmp_ge_u32 s23, 4
	s_cbranch_scc1 .Lmb_nomask
	v_cmp_le_i32_e64 s[56:57], 0, v138
	v_cmp_le_i32_e64 s[58:59], 1, v138
	v_cmp_le_i32_e64 s[64:65], 2, v138
	v_cmp_le_i32_e64 s[68:69], 3, v138
	v_cndmask_b32_e64 v96, v134, v96, s[56:57]
	v_cndmask_b32_e64 v97, v134, v97, s[58:59]
	v_cndmask_b32_e64 v98, v134, v98, s[64:65]
	v_cndmask_b32_e64 v99, v134, v99, s[68:69]
	v_cmp_le_i32_e64 s[56:57], 16, v138
	v_cmp_le_i32_e64 s[58:59], 17, v138
	v_cmp_le_i32_e64 s[64:65], 18, v138
	v_cmp_le_i32_e64 s[68:69], 19, v138
	v_cndmask_b32_e64 v100, v134, v100, s[56:57]
	v_cndmask_b32_e64 v101, v134, v101, s[58:59]
	v_cndmask_b32_e64 v102, v134, v102, s[64:65]
	v_cndmask_b32_e64 v103, v134, v103, s[68:69]
	v_cmp_le_i32_e64 s[56:57], 32, v138
	v_cmp_le_i32_e64 s[58:59], 33, v138
	v_cmp_le_i32_e64 s[64:65], 34, v138
	v_cmp_le_i32_e64 s[68:69], 35, v138
	v_cndmask_b32_e64 v104, v134, v104, s[56:57]
	v_cndmask_b32_e64 v105, v134, v105, s[58:59]
	v_cndmask_b32_e64 v106, v134, v106, s[64:65]
	v_cndmask_b32_e64 v107, v134, v107, s[68:69]
	v_cmp_le_i32_e64 s[56:57], 48, v138
	v_cmp_le_i32_e64 s[58:59], 49, v138
	v_cmp_le_i32_e64 s[64:65], 50, v138
	v_cmp_le_i32_e64 s[68:69], 51, v138
	v_cndmask_b32_e64 v108, v134, v108, s[56:57]
	v_cndmask_b32_e64 v109, v134, v109, s[58:59]
	v_cndmask_b32_e64 v110, v134, v110, s[64:65]
	v_cndmask_b32_e64 v111, v134, v111, s[68:69]
	v_cmp_le_i32_e64 s[56:57], 0, v139
	v_cmp_le_i32_e64 s[58:59], 1, v139
	v_cmp_le_i32_e64 s[64:65], 2, v139
	v_cmp_le_i32_e64 s[68:69], 3, v139
	v_cndmask_b32_e64 v112, v134, v112, s[56:57]
	v_cndmask_b32_e64 v113, v134, v113, s[58:59]
	v_cndmask_b32_e64 v114, v134, v114, s[64:65]
	v_cndmask_b32_e64 v115, v134, v115, s[68:69]
	v_cmp_le_i32_e64 s[56:57], 16, v139
	v_cmp_le_i32_e64 s[58:59], 17, v139
	v_cmp_le_i32_e64 s[64:65], 18, v139
	v_cmp_le_i32_e64 s[68:69], 19, v139
	v_cndmask_b32_e64 v116, v134, v116, s[56:57]
	v_cndmask_b32_e64 v117, v134, v117, s[58:59]
	v_cndmask_b32_e64 v118, v134, v118, s[64:65]
	v_cndmask_b32_e64 v119, v134, v119, s[68:69]
	v_cmp_le_i32_e64 s[56:57], 32, v139
	v_cmp_le_i32_e64 s[58:59], 33, v139
	v_cmp_le_i32_e64 s[64:65], 34, v139
	v_cmp_le_i32_e64 s[68:69], 35, v139
	v_cndmask_b32_e64 v120, v134, v120, s[56:57]
	v_cndmask_b32_e64 v121, v134, v121, s[58:59]
	v_cndmask_b32_e64 v122, v134, v122, s[64:65]
	v_cndmask_b32_e64 v123, v134, v123, s[68:69]
	v_cmp_le_i32_e64 s[56:57], 48, v139
	v_cmp_le_i32_e64 s[58:59], 49, v139
	v_cmp_le_i32_e64 s[64:65], 50, v139
	v_cmp_le_i32_e64 s[68:69], 51, v139
	v_cndmask_b32_e64 v124, v134, v124, s[56:57]
	v_cndmask_b32_e64 v125, v134, v125, s[58:59]
	v_cndmask_b32_e64 v126, v134, v126, s[64:65]
	v_cndmask_b32_e64 v127, v134, v127, s[68:69]
.Lmb_nomask:
	v_max3_f32 v154, v96, v97, v98
	v_max3_f32 v154, v154, v99, v100
	v_max3_f32 v154, v154, v101, v102
	v_max3_f32 v154, v154, v103, v104
	v_max3_f32 v154, v154, v105, v106
	v_max3_f32 v154, v154, v107, v108
	v_max3_f32 v154, v154, v109, v110
	v_max_f32_e32 v154, v154, v111
	v_max3_f32 v155, v112, v113, v114
	v_max3_f32 v155, v155, v115, v116
	v_max3_f32 v155, v155, v117, v118
	v_max3_f32 v155, v155, v119, v120
	v_max3_f32 v155, v155, v121, v122
	v_max3_f32 v155, v155, v123, v124
	v_max3_f32 v155, v155, v125, v126
	v_max_f32_e32 v155, v155, v127
	ds_bpermute_b32 v158, v228, v154
	ds_bpermute_b32 v159, v228, v155
	s_waitcnt lgkmcnt(0)
	v_max_f32_e32 v154, v154, v158
	v_max_f32_e32 v155, v155, v159
	ds_bpermute_b32 v158, v229, v154
	ds_bpermute_b32 v159, v229, v155
	s_waitcnt lgkmcnt(0)
	v_max_f32_e32 v154, v154, v158
	v_max_f32_e32 v155, v155, v159
	v_cmp_ge_f32_e32 vcc, s35, v154
	s_cmp_eq_u64 vcc, exec
	s_cbranch_scc1 .Lmb_norescale_1
	v_max_f32_e32 v160, 0, v154
	v_cmp_gt_f32_e32 vcc, s37, v148
	v_add_f32_e32 v161, v146, v160
	v_add_f32_e32 v162, v148, v160
	s_nop 0
	v_cndmask_b32_e32 v161, v162, v161, vcc
	v_sub_f32_e32 v162, v148, v161
	v_exp_f32_e32 v162, v162
	v_mov_b32_e32 v148, v161
	v_mul_f32_e32 v150, v150, v162
	v_mul_f32_e32 v0, v0, v162
	v_mul_f32_e32 v1, v1, v162
	v_mul_f32_e32 v2, v2, v162
	v_mul_f32_e32 v3, v3, v162
	v_mul_f32_e32 v4, v4, v162
	v_mul_f32_e32 v5, v5, v162
	v_mul_f32_e32 v6, v6, v162
	v_mul_f32_e32 v7, v7, v162
	v_mul_f32_e32 v8, v8, v162
	v_mul_f32_e32 v9, v9, v162
	v_mul_f32_e32 v10, v10, v162
	v_mul_f32_e32 v11, v11, v162
	v_mul_f32_e32 v12, v12, v162
	v_mul_f32_e32 v13, v13, v162
	v_mul_f32_e32 v14, v14, v162
	v_mul_f32_e32 v15, v15, v162
	v_mul_f32_e32 v16, v16, v162
	v_mul_f32_e32 v17, v17, v162
	v_mul_f32_e32 v18, v18, v162
	v_mul_f32_e32 v19, v19, v162
	v_mul_f32_e32 v20, v20, v162
	v_mul_f32_e32 v21, v21, v162
	v_mul_f32_e32 v22, v22, v162
	v_mul_f32_e32 v23, v23, v162
	v_mul_f32_e32 v24, v24, v162
	v_mul_f32_e32 v25, v25, v162
	v_mul_f32_e32 v26, v26, v162
	v_mul_f32_e32 v27, v27, v162
	v_mul_f32_e32 v28, v28, v162
	v_mul_f32_e32 v29, v29, v162
	v_mul_f32_e32 v30, v30, v162
	v_mul_f32_e32 v31, v31, v162
	v_sub_f32_e32 v96, v96, v160
	v_sub_f32_e32 v97, v97, v160
	v_sub_f32_e32 v98, v98, v160
	v_sub_f32_e32 v99, v99, v160
	v_sub_f32_e32 v100, v100, v160
	v_sub_f32_e32 v101, v101, v160
	v_sub_f32_e32 v102, v102, v160
	v_sub_f32_e32 v103, v103, v160
	v_sub_f32_e32 v104, v104, v160
	v_sub_f32_e32 v105, v105, v160
	v_sub_f32_e32 v106, v106, v160
	v_sub_f32_e32 v107, v107, v160
	v_sub_f32_e32 v108, v108, v160
	v_sub_f32_e32 v109, v109, v160
	v_sub_f32_e32 v110, v110, v160
	v_sub_f32_e32 v111, v111, v160
.Lmb_norescale_1:
	v_cmp_ge_f32_e32 vcc, s35, v155
	s_cmp_eq_u64 vcc, exec
	s_cbranch_scc1 .Lmb_norescale_2
	v_max_f32_e32 v160, 0, v155
	v_cmp_gt_f32_e32 vcc, s37, v149
	v_add_f32_e32 v161, v147, v160
	v_add_f32_e32 v162, v149, v160
	s_nop 0
	v_cndmask_b32_e32 v161, v162, v161, vcc
	v_sub_f32_e32 v162, v149, v161
	v_exp_f32_e32 v162, v162
	v_mov_b32_e32 v149, v161
	v_mul_f32_e32 v151, v151, v162
	v_mul_f32_e32 v32, v32, v162
	v_mul_f32_e32 v33, v33, v162
	v_mul_f32_e32 v34, v34, v162
	v_mul_f32_e32 v35, v35, v162
	v_mul_f32_e32 v36, v36, v162
	v_mul_f32_e32 v37, v37, v162
	v_mul_f32_e32 v38, v38, v162
	v_mul_f32_e32 v39, v39, v162
	v_mul_f32_e32 v40, v40, v162
	v_mul_f32_e32 v41, v41, v162
	v_mul_f32_e32 v42, v42, v162
	v_mul_f32_e32 v43, v43, v162
	v_mul_f32_e32 v44, v44, v162
	v_mul_f32_e32 v45, v45, v162
	v_mul_f32_e32 v46, v46, v162
	v_mul_f32_e32 v47, v47, v162
	v_mul_f32_e32 v48, v48, v162
	v_mul_f32_e32 v49, v49, v162
	v_mul_f32_e32 v50, v50, v162
	v_mul_f32_e32 v51, v51, v162
	v_mul_f32_e32 v52, v52, v162
	v_mul_f32_e32 v53, v53, v162
	v_mul_f32_e32 v54, v54, v162
	v_mul_f32_e32 v55, v55, v162
	v_mul_f32_e32 v56, v56, v162
	v_mul_f32_e32 v57, v57, v162
	v_mul_f32_e32 v58, v58, v162
	v_mul_f32_e32 v59, v59, v162
	v_mul_f32_e32 v60, v60, v162
	v_mul_f32_e32 v61, v61, v162
	v_mul_f32_e32 v62, v62, v162
	v_mul_f32_e32 v63, v63, v162
	v_sub_f32_e32 v112, v112, v160
	v_sub_f32_e32 v113, v113, v160
	v_sub_f32_e32 v114, v114, v160
	v_sub_f32_e32 v115, v115, v160
	v_sub_f32_e32 v116, v116, v160
	v_sub_f32_e32 v117, v117, v160
	v_sub_f32_e32 v118, v118, v160
	v_sub_f32_e32 v119, v119, v160
	v_sub_f32_e32 v120, v120, v160
	v_sub_f32_e32 v121, v121, v160
	v_sub_f32_e32 v122, v122, v160
	v_sub_f32_e32 v123, v123, v160
	v_sub_f32_e32 v124, v124, v160
	v_sub_f32_e32 v125, v125, v160
	v_sub_f32_e32 v126, v126, v160
	v_sub_f32_e32 v127, v127, v160
.Lmb_norescale_2:
	v_exp_f32_e32 v96, v96
	v_exp_f32_e32 v97, v97
	v_mov_b32_e32 v160, v96
	v_exp_f32_e32 v98, v98
	v_add_f32_e32 v160, v160, v97
	v_exp_f32_e32 v99, v99
	v_add_f32_e32 v160, v160, v98
	v_exp_f32_e32 v100, v100
	v_add_f32_e32 v160, v160, v99
	v_exp_f32_e32 v101, v101
	v_add_f32_e32 v160, v160, v100
	v_exp_f32_e32 v102, v102
	v_add_f32_e32 v160, v160, v101
	v_exp_f32_e32 v103, v103
	v_add_f32_e32 v160, v160, v102
	v_exp_f32_e32 v104, v104
	v_add_f32_e32 v160, v160, v103
	v_exp_f32_e32 v105, v105
	v_add_f32_e32 v160, v160, v104
	v_exp_f32_e32 v106, v106
	v_add_f32_e32 v160, v160, v105
	v_exp_f32_e32 v107, v107
	v_add_f32_e32 v160, v160, v106
	v_exp_f32_e32 v108, v108
	v_add_f32_e32 v160, v160, v107
	v_exp_f32_e32 v109, v109
	v_add_f32_e32 v160, v160, v108
	v_exp_f32_e32 v110, v110
	v_add_f32_e32 v160, v160, v109
	v_exp_f32_e32 v111, v111
	v_add_f32_e32 v160, v160, v110
	s_nop 0
	v_add_f32_e32 v160, v160, v111
	v_add_f32_e32 v150, v150, v160
	v_cvt_pk_bf16_f32 v96, v96, v97
	v_cvt_pk_bf16_f32 v97, v98, v99
	v_cvt_pk_bf16_f32 v98, v100, v101
	v_cvt_pk_bf16_f32 v99, v102, v103
	v_cvt_pk_bf16_f32 v104, v104, v105
	v_cvt_pk_bf16_f32 v105, v106, v107
	v_cvt_pk_bf16_f32 v106, v108, v109
	v_cvt_pk_bf16_f32 v107, v110, v111
	v_exp_f32_e32 v112, v112
	v_exp_f32_e32 v113, v113
	v_mov_b32_e32 v160, v112
	v_exp_f32_e32 v114, v114
	v_add_f32_e32 v160, v160, v113
	v_exp_f32_e32 v115, v115
	v_add_f32_e32 v160, v160, v114
	v_exp_f32_e32 v116, v116
	v_add_f32_e32 v160, v160, v115
	v_exp_f32_e32 v117, v117
	v_add_f32_e32 v160, v160, v116
	v_exp_f32_e32 v118, v118
	v_add_f32_e32 v160, v160, v117
	v_exp_f32_e32 v119, v119
	v_add_f32_e32 v160, v160, v118
	v_exp_f32_e32 v120, v120
	v_add_f32_e32 v160, v160, v119
	v_exp_f32_e32 v121, v121
	v_add_f32_e32 v160, v160, v120
	v_exp_f32_e32 v122, v122
	v_add_f32_e32 v160, v160, v121
	v_exp_f32_e32 v123, v123
	v_add_f32_e32 v160, v160, v122
	v_exp_f32_e32 v124, v124
	v_add_f32_e32 v160, v160, v123
	v_exp_f32_e32 v125, v125
	v_add_f32_e32 v160, v160, v124
	v_exp_f32_e32 v126, v126
	v_add_f32_e32 v160, v160, v125
	v_exp_f32_e32 v127, v127
	v_add_f32_e32 v160, v160, v126
	s_nop 0
	v_add_f32_e32 v160, v160, v127
	v_add_f32_e32 v151, v151, v160
	v_cvt_pk_bf16_f32 v112, v112, v113
	v_cvt_pk_bf16_f32 v113, v114, v115
	v_cvt_pk_bf16_f32 v114, v116, v117
	v_cvt_pk_bf16_f32 v115, v118, v119
	v_cvt_pk_bf16_f32 v120, v120, v121
	v_cvt_pk_bf16_f32 v121, v122, v123
	v_cvt_pk_bf16_f32 v122, v124, v125
	v_cvt_pk_bf16_f32 v123, v126, v127
	ds_read_b64_tr_b16 v[248:249], v129 offset:192
	ds_read_b64_tr_b16 v[250:251], v129 offset:4800
	s_nop 1
	s_waitcnt lgkmcnt(12)
	v_mfma_f32_16x16x32_bf16 v[0:3], v[204:207], v[96:99], v[0:3]
	v_mfma_f32_16x16x32_bf16 v[32:35], v[204:207], v[112:115], v[32:35]
	ds_read_b64_tr_b16 v[252:253], v129 offset:224
	ds_read_b64_tr_b16 v[254:255], v129 offset:4832
	s_waitcnt lgkmcnt(12)
	v_mfma_f32_16x16x32_bf16 v[4:7], v[208:211], v[96:99], v[4:7]
	v_mfma_f32_16x16x32_bf16 v[36:39], v[208:211], v[112:115], v[36:39]
	ds_read_b64_tr_b16 v[204:205], v129 offset:9216
	ds_read_b64_tr_b16 v[206:207], v129 offset:13824
	s_waitcnt lgkmcnt(12)
	v_mfma_f32_16x16x32_bf16 v[8:11], v[212:215], v[96:99], v[8:11]
	v_mfma_f32_16x16x32_bf16 v[40:43], v[212:215], v[112:115], v[40:43]
	ds_read_b64_tr_b16 v[208:209], v129 offset:9248
	ds_read_b64_tr_b16 v[210:211], v129 offset:13856
	s_waitcnt lgkmcnt(12)
	v_mfma_f32_16x16x32_bf16 v[12:15], v[216:219], v[96:99], v[12:15]
	v_mfma_f32_16x16x32_bf16 v[44:47], v[216:219], v[112:115], v[44:47]
	ds_read_b64_tr_b16 v[212:213], v129 offset:9280
	ds_read_b64_tr_b16 v[214:215], v129 offset:13888
	s_waitcnt lgkmcnt(12)
	v_mfma_f32_16x16x32_bf16 v[16:19], v[240:243], v[96:99], v[16:19]
	v_mfma_f32_16x16x32_bf16 v[48:51], v[240:243], v[112:115], v[48:51]
	ds_read_b64_tr_b16 v[216:217], v129 offset:9312
	ds_read_b64_tr_b16 v[218:219], v129 offset:13920
	s_waitcnt lgkmcnt(12)
	v_mfma_f32_16x16x32_bf16 v[20:23], v[244:247], v[96:99], v[20:23]
	v_mfma_f32_16x16x32_bf16 v[52:55], v[244:247], v[112:115], v[52:55]
	ds_read_b64_tr_b16 v[240:241], v129 offset:9344
	ds_read_b64_tr_b16 v[242:243], v129 offset:13952
	s_waitcnt lgkmcnt(12)
	v_mfma_f32_16x16x32_bf16 v[24:27], v[248:251], v[96:99], v[24:27]
	v_mfma_f32_16x16x32_bf16 v[56:59], v[248:251], v[112:115], v[56:59]
	ds_read_b64_tr_b16 v[244:245], v129 offset:9376
	ds_read_b64_tr_b16 v[246:247], v129 offset:13984
	s_waitcnt lgkmcnt(12)
	v_mfma_f32_16x16x32_bf16 v[28:31], v[252:255], v[96:99], v[28:31]
	v_mfma_f32_16x16x32_bf16 v[60:63], v[252:255], v[112:115], v[60:63]
	ds_read_b64_tr_b16 v[248:249], v129 offset:9408
	ds_read_b64_tr_b16 v[250:251], v129 offset:14016
	s_waitcnt lgkmcnt(12)
	v_mfma_f32_16x16x32_bf16 v[0:3], v[204:207], v[104:107], v[0:3]
	v_mfma_f32_16x16x32_bf16 v[32:35], v[204:207], v[120:123], v[32:35]
	ds_read_b64_tr_b16 v[252:253], v129 offset:9440
	ds_read_b64_tr_b16 v[254:255], v129 offset:14048
	s_waitcnt lgkmcnt(12)
	v_mfma_f32_16x16x32_bf16 v[4:7], v[208:211], v[104:107], v[4:7]
	v_mfma_f32_16x16x32_bf16 v[36:39], v[208:211], v[120:123], v[36:39]
	s_waitcnt lgkmcnt(10)
	v_mfma_f32_16x16x32_bf16 v[8:11], v[212:215], v[104:107], v[8:11]
	v_mfma_f32_16x16x32_bf16 v[40:43], v[212:215], v[120:123], v[40:43]
	s_waitcnt lgkmcnt(8)
	v_mfma_f32_16x16x32_bf16 v[12:15], v[216:219], v[104:107], v[12:15]
	v_mfma_f32_16x16x32_bf16 v[44:47], v[216:219], v[120:123], v[44:47]
	s_waitcnt lgkmcnt(6)
	v_mfma_f32_16x16x32_bf16 v[16:19], v[240:243], v[104:107], v[16:19]
	v_mfma_f32_16x16x32_bf16 v[48:51], v[240:243], v[120:123], v[48:51]
	s_waitcnt lgkmcnt(4)
	v_mfma_f32_16x16x32_bf16 v[20:23], v[244:247], v[104:107], v[20:23]
	v_mfma_f32_16x16x32_bf16 v[52:55], v[244:247], v[120:123], v[52:55]
	s_waitcnt lgkmcnt(2)
	v_mfma_f32_16x16x32_bf16 v[24:27], v[248:251], v[104:107], v[24:27]
	v_mfma_f32_16x16x32_bf16 v[56:59], v[248:251], v[120:123], v[56:59]
	s_waitcnt lgkmcnt(0)
	v_mfma_f32_16x16x32_bf16 v[28:31], v[252:255], v[104:107], v[28:31]
	v_mfma_f32_16x16x32_bf16 v[60:63], v[252:255], v[120:123], v[60:63]
.Lmb_iter_end:
	v_xor_b32_e32 v128, 65536, v128
	v_xor_b32_e32 v129, 65536, v129
	v_xor_b32_e32 v130, 65536, v130
	v_xor_b32_e32 v131, 65536, v131
	s_add_u32 s23, s23, 1
	s_waitcnt lgkmcnt(0)
	s_barrier
	s_cmp_lt_u32 s23, s22
	s_cbranch_scc1 .Lmb_loop
	s_nop 7
	ds_bpermute_b32 v158, v228, v150
	ds_bpermute_b32 v159, v228, v151
	s_waitcnt lgkmcnt(0)
	v_add_f32_e32 v150, v150, v158
	v_add_f32_e32 v151, v151, v159
	ds_bpermute_b32 v158, v229, v150
	ds_bpermute_b32 v159, v229, v151
	s_waitcnt lgkmcnt(0)
	v_add_f32_e32 v150, v150, v158
	v_add_f32_e32 v151, v151, v159
	v_div_scale_f32 v162, s[78:79], v150, v150, 1.0
	v_rcp_f32_e32 v163, v162
	v_div_scale_f32 v192, vcc, 1.0, v150, 1.0
	v_fma_f32 v193, -v162, v163, 1.0
	v_fmac_f32_e32 v163, v193, v163
	v_mul_f32_e32 v193, v192, v163
	v_fma_f32 v195, -v162, v193, v192
	v_fmac_f32_e32 v193, v195, v163
	v_fma_f32 v162, -v162, v193, v192
	v_div_fmas_f32 v162, v162, v163, v193
	v_div_fixup_f32 v160, v162, v150, 1.0
	v_div_scale_f32 v162, s[78:79], v151, v151, 1.0
	v_rcp_f32_e32 v163, v162
	v_div_scale_f32 v192, vcc, 1.0, v151, 1.0
	v_fma_f32 v193, -v162, v163, 1.0
	v_fmac_f32_e32 v163, v193, v163
	v_mul_f32_e32 v193, v192, v163
	v_fma_f32 v195, -v162, v193, v192
	v_fmac_f32_e32 v193, v195, v163
	v_fma_f32 v162, -v162, v193, v192
	v_div_fmas_f32 v162, v162, v163, v193
	v_div_fixup_f32 v161, v162, v151, 1.0
	v_and_b32_e32 v140, 15, v230
	s_lshl_b32 s30, s7, 5
	v_add_u32_e32 v140, s30, v140
	v_lshrrev_b32_e32 v141, 4, v230
	v_lshlrev_b32_e32 v141, 3, v141
	v_and_b32_e32 v142, 15, v230
	v_lshl_add_u32 v142, v142, 8, v141
	s_lshl_b32 s31, s7, 14
	v_add_u32_e32 v142, s31, v142
	v_lshl_add_u32 v143, v140, 12, v141
	s_add_u32 s28, s24, 25165824
	s_addc_u32 s29, s25, 0
	global_load_dwordx2 v[96:97], v142, s[28:29] offset:0
	global_load_dwordx2 v[98:99], v142, s[28:29] offset:32
	global_load_dwordx2 v[100:101], v142, s[28:29] offset:64
	global_load_dwordx2 v[102:103], v142, s[28:29] offset:96
	global_load_dwordx2 v[104:105], v142, s[28:29] offset:128
	global_load_dwordx2 v[106:107], v142, s[28:29] offset:160
	global_load_dwordx2 v[108:109], v142, s[28:29] offset:192
	global_load_dwordx2 v[110:111], v142, s[28:29] offset:224
	s_add_u32 s28, s24, 25169920
	s_addc_u32 s29, s25, 0
	global_load_dwordx2 v[112:113], v142, s[28:29] offset:0
	global_load_dwordx2 v[114:115], v142, s[28:29] offset:32
	global_load_dwordx2 v[116:117], v142, s[28:29] offset:64
	global_load_dwordx2 v[118:119], v142, s[28:29] offset:96
	global_load_dwordx2 v[120:121], v142, s[28:29] offset:128
	global_load_dwordx2 v[122:123], v142, s[28:29] offset:160
	global_load_dwordx2 v[124:125], v142, s[28:29] offset:192
	global_load_dwordx2 v[126:127], v142, s[28:29] offset:224
	s_lshl_b32 s30, s15, 20
	s_add_u32 s26, s10, s30
	s_addc_u32 s27, s11, 0
	s_waitcnt vmcnt(15)
	v_mul_f32_e32 v162, v0, v160
	v_mul_f32_e32 v163, v1, v160
	v_mul_f32_e32 v192, v2, v160
	v_mul_f32_e32 v193, v3, v160
	v_lshlrev_b32_e32 v195, 16, v96
	v_and_b32_e32 v203, 0xffff0000, v96
	v_mul_f32_e32 v162, v162, v195
	v_mul_f32_e32 v163, v163, v203
	v_lshlrev_b32_e32 v195, 16, v97
	v_and_b32_e32 v203, 0xffff0000, v97
	v_mul_f32_e32 v192, v192, v195
	v_mul_f32_e32 v193, v193, v203
	v_cvt_pk_bf16_f32 v96, v162, v163
	v_cvt_pk_bf16_f32 v97, v192, v193
	global_store_dwordx2 v143, v[96:97], s[26:27] offset:0
	s_waitcnt vmcnt(15)
	v_mul_f32_e32 v162, v4, v160
	v_mul_f32_e32 v163, v5, v160
	v_mul_f32_e32 v192, v6, v160
	v_mul_f32_e32 v193, v7, v160
	v_lshlrev_b32_e32 v195, 16, v98
	v_and_b32_e32 v203, 0xffff0000, v98
	v_mul_f32_e32 v162, v162, v195
	v_mul_f32_e32 v163, v163, v203
	v_lshlrev_b32_e32 v195, 16, v99
	v_and_b32_e32 v203, 0xffff0000, v99
	v_mul_f32_e32 v192, v192, v195
	v_mul_f32_e32 v193, v193, v203
	v_cvt_pk_bf16_f32 v98, v162, v163
	v_cvt_pk_bf16_f32 v99, v192, v193
	global_store_dwordx2 v143, v[98:99], s[26:27] offset:32
	s_waitcnt vmcnt(15)
	v_mul_f32_e32 v162, v8, v160
	v_mul_f32_e32 v163, v9, v160
	v_mul_f32_e32 v192, v10, v160
	v_mul_f32_e32 v193, v11, v160
	v_lshlrev_b32_e32 v195, 16, v100
	v_and_b32_e32 v203, 0xffff0000, v100
	v_mul_f32_e32 v162, v162, v195
	v_mul_f32_e32 v163, v163, v203
	v_lshlrev_b32_e32 v195, 16, v101
	v_and_b32_e32 v203, 0xffff0000, v101
	v_mul_f32_e32 v192, v192, v195
	v_mul_f32_e32 v193, v193, v203
	v_cvt_pk_bf16_f32 v100, v162, v163
	v_cvt_pk_bf16_f32 v101, v192, v193
	global_store_dwordx2 v143, v[100:101], s[26:27] offset:64
	s_waitcnt vmcnt(15)
	v_mul_f32_e32 v162, v12, v160
	v_mul_f32_e32 v163, v13, v160
	v_mul_f32_e32 v192, v14, v160
	v_mul_f32_e32 v193, v15, v160
	v_lshlrev_b32_e32 v195, 16, v102
	v_and_b32_e32 v203, 0xffff0000, v102
	v_mul_f32_e32 v162, v162, v195
	v_mul_f32_e32 v163, v163, v203
	v_lshlrev_b32_e32 v195, 16, v103
	v_and_b32_e32 v203, 0xffff0000, v103
	v_mul_f32_e32 v192, v192, v195
	v_mul_f32_e32 v193, v193, v203
	v_cvt_pk_bf16_f32 v102, v162, v163
	v_cvt_pk_bf16_f32 v103, v192, v193
	global_store_dwordx2 v143, v[102:103], s[26:27] offset:96
	s_waitcnt vmcnt(15)
	v_mul_f32_e32 v162, v16, v160
	v_mul_f32_e32 v163, v17, v160
	v_mul_f32_e32 v192, v18, v160
	v_mul_f32_e32 v193, v19, v160
	v_lshlrev_b32_e32 v195, 16, v104
	v_and_b32_e32 v203, 0xffff0000, v104
	v_mul_f32_e32 v162, v162, v195
	v_mul_f32_e32 v163, v163, v203
	v_lshlrev_b32_e32 v195, 16, v105
	v_and_b32_e32 v203, 0xffff0000, v105
	v_mul_f32_e32 v192, v192, v195
	v_mul_f32_e32 v193, v193, v203
	v_cvt_pk_bf16_f32 v104, v162, v163
	v_cvt_pk_bf16_f32 v105, v192, v193
	global_store_dwordx2 v143, v[104:105], s[26:27] offset:128
	s_waitcnt vmcnt(15)
	v_mul_f32_e32 v162, v20, v160
	v_mul_f32_e32 v163, v21, v160
	v_mul_f32_e32 v192, v22, v160
	v_mul_f32_e32 v193, v23, v160
	v_lshlrev_b32_e32 v195, 16, v106
	v_and_b32_e32 v203, 0xffff0000, v106
	v_mul_f32_e32 v162, v162, v195
	v_mul_f32_e32 v163, v163, v203
	v_lshlrev_b32_e32 v195, 16, v107
	v_and_b32_e32 v203, 0xffff0000, v107
	v_mul_f32_e32 v192, v192, v195
	v_mul_f32_e32 v193, v193, v203
	v_cvt_pk_bf16_f32 v106, v162, v163
	v_cvt_pk_bf16_f32 v107, v192, v193
	global_store_dwordx2 v143, v[106:107], s[26:27] offset:160
	s_waitcnt vmcnt(15)
	v_mul_f32_e32 v162, v24, v160
	v_mul_f32_e32 v163, v25, v160
	v_mul_f32_e32 v192, v26, v160
	v_mul_f32_e32 v193, v27, v160
	v_lshlrev_b32_e32 v195, 16, v108
	v_and_b32_e32 v203, 0xffff0000, v108
	v_mul_f32_e32 v162, v162, v195
	v_mul_f32_e32 v163, v163, v203
	v_lshlrev_b32_e32 v195, 16, v109
	v_and_b32_e32 v203, 0xffff0000, v109
	v_mul_f32_e32 v192, v192, v195
	v_mul_f32_e32 v193, v193, v203
	v_cvt_pk_bf16_f32 v108, v162, v163
	v_cvt_pk_bf16_f32 v109, v192, v193
	global_store_dwordx2 v143, v[108:109], s[26:27] offset:192
	s_waitcnt vmcnt(15)
	v_mul_f32_e32 v162, v28, v160
	v_mul_f32_e32 v163, v29, v160
	v_mul_f32_e32 v192, v30, v160
	v_mul_f32_e32 v193, v31, v160
	v_lshlrev_b32_e32 v195, 16, v110
	v_and_b32_e32 v203, 0xffff0000, v110
	v_mul_f32_e32 v162, v162, v195
	v_mul_f32_e32 v163, v163, v203
	v_lshlrev_b32_e32 v195, 16, v111
	v_and_b32_e32 v203, 0xffff0000, v111
	v_mul_f32_e32 v192, v192, v195
	v_mul_f32_e32 v193, v193, v203
	v_cvt_pk_bf16_f32 v110, v162, v163
	v_cvt_pk_bf16_f32 v111, v192, v193
	global_store_dwordx2 v143, v[110:111], s[26:27] offset:224
	s_add_u32 s26, s26, 0x10000
	s_addc_u32 s27, s27, 0
	s_waitcnt vmcnt(15)
	v_mul_f32_e32 v162, v32, v161
	v_mul_f32_e32 v163, v33, v161
	v_mul_f32_e32 v192, v34, v161
	v_mul_f32_e32 v193, v35, v161
	v_lshlrev_b32_e32 v195, 16, v112
	v_and_b32_e32 v203, 0xffff0000, v112
	v_mul_f32_e32 v162, v162, v195
	v_mul_f32_e32 v163, v163, v203
	v_lshlrev_b32_e32 v195, 16, v113
	v_and_b32_e32 v203, 0xffff0000, v113
	v_mul_f32_e32 v192, v192, v195
	v_mul_f32_e32 v193, v193, v203
	v_cvt_pk_bf16_f32 v112, v162, v163
	v_cvt_pk_bf16_f32 v113, v192, v193
	global_store_dwordx2 v143, v[112:113], s[26:27] offset:0
	s_waitcnt vmcnt(15)
	v_mul_f32_e32 v162, v36, v161
	v_mul_f32_e32 v163, v37, v161
	v_mul_f32_e32 v192, v38, v161
	v_mul_f32_e32 v193, v39, v161
	v_lshlrev_b32_e32 v195, 16, v114
	v_and_b32_e32 v203, 0xffff0000, v114
	v_mul_f32_e32 v162, v162, v195
	v_mul_f32_e32 v163, v163, v203
	v_lshlrev_b32_e32 v195, 16, v115
	v_and_b32_e32 v203, 0xffff0000, v115
	v_mul_f32_e32 v192, v192, v195
	v_mul_f32_e32 v193, v193, v203
	v_cvt_pk_bf16_f32 v114, v162, v163
	v_cvt_pk_bf16_f32 v115, v192, v193
	global_store_dwordx2 v143, v[114:115], s[26:27] offset:32
	s_waitcnt vmcnt(15)
	v_mul_f32_e32 v162, v40, v161
	v_mul_f32_e32 v163, v41, v161
	v_mul_f32_e32 v192, v42, v161
	v_mul_f32_e32 v193, v43, v161
	v_lshlrev_b32_e32 v195, 16, v116
	v_and_b32_e32 v203, 0xffff0000, v116
	v_mul_f32_e32 v162, v162, v195
	v_mul_f32_e32 v163, v163, v203
	v_lshlrev_b32_e32 v195, 16, v117
	v_and_b32_e32 v203, 0xffff0000, v117
	v_mul_f32_e32 v192, v192, v195
	v_mul_f32_e32 v193, v193, v203
	v_cvt_pk_bf16_f32 v116, v162, v163
	v_cvt_pk_bf16_f32 v117, v192, v193
	global_store_dwordx2 v143, v[116:117], s[26:27] offset:64
	s_waitcnt vmcnt(15)
	v_mul_f32_e32 v162, v44, v161
	v_mul_f32_e32 v163, v45, v161
	v_mul_f32_e32 v192, v46, v161
	v_mul_f32_e32 v193, v47, v161
	v_lshlrev_b32_e32 v195, 16, v118
	v_and_b32_e32 v203, 0xffff0000, v118
	v_mul_f32_e32 v162, v162, v195
	v_mul_f32_e32 v163, v163, v203
	v_lshlrev_b32_e32 v195, 16, v119
	v_and_b32_e32 v203, 0xffff0000, v119
	v_mul_f32_e32 v192, v192, v195
	v_mul_f32_e32 v193, v193, v203
	v_cvt_pk_bf16_f32 v118, v162, v163
	v_cvt_pk_bf16_f32 v119, v192, v193
	global_store_dwordx2 v143, v[118:119], s[26:27] offset:96
	s_waitcnt vmcnt(15)
	v_mul_f32_e32 v162, v48, v161
	v_mul_f32_e32 v163, v49, v161
	v_mul_f32_e32 v192, v50, v161
	v_mul_f32_e32 v193, v51, v161
	v_lshlrev_b32_e32 v195, 16, v120
	v_and_b32_e32 v203, 0xffff0000, v120
	v_mul_f32_e32 v162, v162, v195
	v_mul_f32_e32 v163, v163, v203
	v_lshlrev_b32_e32 v195, 16, v121
	v_and_b32_e32 v203, 0xffff0000, v121
	v_mul_f32_e32 v192, v192, v195
	v_mul_f32_e32 v193, v193, v203
	v_cvt_pk_bf16_f32 v120, v162, v163
	v_cvt_pk_bf16_f32 v121, v192, v193
	global_store_dwordx2 v143, v[120:121], s[26:27] offset:128
	s_waitcnt vmcnt(15)
	v_mul_f32_e32 v162, v52, v161
	v_mul_f32_e32 v163, v53, v161
	v_mul_f32_e32 v192, v54, v161
	v_mul_f32_e32 v193, v55, v161
	v_lshlrev_b32_e32 v195, 16, v122
	v_and_b32_e32 v203, 0xffff0000, v122
	v_mul_f32_e32 v162, v162, v195
	v_mul_f32_e32 v163, v163, v203
	v_lshlrev_b32_e32 v195, 16, v123
	v_and_b32_e32 v203, 0xffff0000, v123
	v_mul_f32_e32 v192, v192, v195
	v_mul_f32_e32 v193, v193, v203
	v_cvt_pk_bf16_f32 v122, v162, v163
	v_cvt_pk_bf16_f32 v123, v192, v193
	global_store_dwordx2 v143, v[122:123], s[26:27] offset:160
	s_waitcnt vmcnt(15)
	v_mul_f32_e32 v162, v56, v161
	v_mul_f32_e32 v163, v57, v161
	v_mul_f32_e32 v192, v58, v161
	v_mul_f32_e32 v193, v59, v161
	v_lshlrev_b32_e32 v195, 16, v124
	v_and_b32_e32 v203, 0xffff0000, v124
	v_mul_f32_e32 v162, v162, v195
	v_mul_f32_e32 v163, v163, v203
	v_lshlrev_b32_e32 v195, 16, v125
	v_and_b32_e32 v203, 0xffff0000, v125
	v_mul_f32_e32 v192, v192, v195
	v_mul_f32_e32 v193, v193, v203
	v_cvt_pk_bf16_f32 v124, v162, v163
	v_cvt_pk_bf16_f32 v125, v192, v193
	global_store_dwordx2 v143, v[124:125], s[26:27] offset:192
	s_waitcnt vmcnt(15)
	v_mul_f32_e32 v162, v60, v161
	v_mul_f32_e32 v163, v61, v161
	v_mul_f32_e32 v192, v62, v161
	v_mul_f32_e32 v193, v63, v161
	v_lshlrev_b32_e32 v195, 16, v126
	v_and_b32_e32 v203, 0xffff0000, v126
	v_mul_f32_e32 v162, v162, v195
	v_mul_f32_e32 v163, v163, v203
	v_lshlrev_b32_e32 v195, 16, v127
	v_and_b32_e32 v203, 0xffff0000, v127
	v_mul_f32_e32 v192, v192, v195
	v_mul_f32_e32 v193, v193, v203
	v_cvt_pk_bf16_f32 v126, v162, v163
	v_cvt_pk_bf16_f32 v127, v192, v193
	global_store_dwordx2 v143, v[126:127], s[26:27] offset:224
	s_add_u32 s14, s14, 1
	s_cmp_lt_u32 s14, 2
	s_cbranch_scc1 .Lmb_task
	s_setprio 0
	s_cmpk_lt_i32 s96, 0x800
	s_cselect_b64 s[10:11], -1, 0
	s_cmpk_gt_i32 s96, 0x7ff
	v_lshlrev_b32_e32 v156, 4, v198
	v_cmp_gt_u32_e64 s[8:9], 64, v198
	s_waitcnt lgkmcnt(0)
	s_barrier
	s_cbranch_scc1 .LBB0_356
	s_ashr_i32 s2, s96, 8
	s_lshl_b32 s0, s96, 6
	s_ashr_i32 s3, s2, 31
	s_and_b32 s0, s0, 0x7c0
	s_lshl_b64 s[2:3], s[2:3], 11
	s_ashr_i32 s12, s96, 5
	s_or_b32 s1, s2, s0
	s_add_u32 s4, s1, -3
	v_mov_b32_e32 v129, 0
	s_addc_u32 s5, s3, 0x3ffff
	v_or_b32_e32 v6, s0, v136
	v_mov_b32_e32 v137, v129
	v_lshl_add_u64 v[2:3], s[4:5], 0, v[136:137]
	v_mov_b32_e32 v7, s3
	v_cmp_lt_u32_e64 s[2:3], 2, v6
	v_mov_b32_e32 v8, s1
	v_add_u32_e32 v0, 0x200, v198
	v_cndmask_b32_e64 v5, v7, v3, s[2:3]
	v_cndmask_b32_e64 v4, v8, v2, s[2:3]
	v_lshlrev_b64 v[4:5], 14, v[4:5]
	s_lshl_b32 s1, s12, 8
	v_lshrrev_b32_e32 v128, 4, v0
	s_mov_b32 s15, 0
	v_lshl_add_u64 v[4:5], s[66:67], 0, v[4:5]
	s_and_b32 s14, s1, 0x700
	v_lshl_add_u64 v[0:1], s[4:5], 0, v[128:129]
	v_lshl_add_u64 v[4:5], v[4:5], 0, s[14:15]
	v_and_b32_e32 v128, 0xf0, v156
	v_lshl_add_u64 v[16:17], v[4:5], 0, v[128:129]
	v_lshl_add_u64 v[4:5], v[2:3], 0, 1
	v_cmp_lt_u32_e64 s[4:5], 1, v6
	v_cmp_eq_u32_e64 s[6:7], 0, v6
	s_mov_b32 s1, 0xc000
	v_cndmask_b32_e64 v5, v7, v5, s[4:5]
	v_cndmask_b32_e64 v4, v8, v4, s[4:5]
	v_lshlrev_b64 v[4:5], 14, v[4:5]
	v_lshl_add_u64 v[4:5], s[66:67], 0, v[4:5]
	v_lshl_add_u64 v[4:5], v[4:5], 0, s[14:15]
	v_lshl_add_u64 v[18:19], v[4:5], 0, v[128:129]
	v_lshl_add_u64 v[4:5], v[2:3], 0, 2
	v_cndmask_b32_e64 v5, v5, v7, s[6:7]
	v_cndmask_b32_e64 v4, v4, v8, s[6:7]
	v_lshlrev_b64 v[2:3], 14, v[2:3]
	v_lshlrev_b64 v[4:5], 14, v[4:5]
	v_lshl_add_u64 v[2:3], s[66:67], 0, v[2:3]
	v_lshl_add_u64 v[4:5], s[66:67], 0, v[4:5]
	v_lshl_add_u64 v[2:3], v[2:3], 0, s[14:15]
	v_lshl_add_u64 v[4:5], v[4:5], 0, s[14:15]
	v_lshl_add_u64 v[2:3], v[2:3], 0, v[128:129]
	v_lshl_add_u64 v[44:45], v[4:5], 0, v[128:129]
	v_add_co_u32_e32 v4, vcc, s1, v2
	v_lshlrev_b64 v[0:1], 14, v[0:1]
	s_nop 0
	v_addc_co_u32_e32 v5, vcc, 0, v3, vcc
	s_mov_b32 s13, 0xd000
	v_lshl_add_u64 v[0:1], s[66:67], 0, v[0:1]
	v_add_co_u32_e32 v46, vcc, s13, v2
	v_lshl_add_u64 v[0:1], v[0:1], 0, s[14:15]
	s_nop 0
	v_addc_co_u32_e32 v47, vcc, 0, v3, vcc
	v_lshl_add_u64 v[48:49], v[0:1], 0, v[128:129]
	s_movk_i32 s13, 0x4000
	v_add_co_u32_e32 v12, vcc, s13, v48
	s_mov_b32 s13, 0x8000
	s_nop 0
	v_addc_co_u32_e32 v13, vcc, 0, v49, vcc
	v_add_co_u32_e32 v32, vcc, s13, v48
	v_mov_b32_e32 v135, v129
	s_nop 0
	v_addc_co_u32_e32 v33, vcc, 0, v49, vcc
	v_add_co_u32_e32 v36, vcc, s1, v48
	s_movk_i32 s1, 0x1000
	s_nop 0
	v_addc_co_u32_e32 v37, vcc, 0, v49, vcc
	global_load_dwordx4 v[40:43], v[16:17], off
	global_load_dwordx4 v[80:83], v[16:17], off offset:2048
	global_load_dwordx4 v[94:97], v[18:19], off
	global_load_dwordx4 v[76:79], v[18:19], off offset:2048
	global_load_dwordx4 v[62:65], v[44:45], off
	global_load_dwordx4 v[86:89], v[44:45], off offset:2048
	global_load_dwordx4 v[0:3], v[48:49], off
	global_load_dwordx4 v[20:23], v[4:5], off offset:2048
	s_nop 0
	global_load_dwordx4 v[4:7], v[12:13], off
	global_load_dwordx4 v[24:27], v[48:49], off offset:2048
	global_load_dwordx4 v[8:11], v[32:33], off
	global_load_dwordx4 v[28:31], v[12:13], off offset:2048
	s_nop 0
	global_load_dwordx4 v[12:15], v[36:37], off
	s_nop 0
	global_load_dwordx4 v[32:35], v[32:33], off offset:2048
	v_add_co_u32_e32 v16, vcc, s1, v16
	s_nop 1
	v_addc_co_u32_e32 v17, vcc, 0, v17, vcc
	global_load_dwordx4 v[36:39], v[36:37], off offset:2048
	s_nop 0
	global_load_dwordx4 v[90:93], v[16:17], off
	v_add_co_u32_e32 v16, vcc, s1, v18
	s_nop 1
	v_addc_co_u32_e32 v17, vcc, 0, v19, vcc
	v_add_co_u32_e32 v18, vcc, s1, v44
	s_nop 1
	v_addc_co_u32_e32 v19, vcc, 0, v45, vcc
	v_add_co_u32_e32 v50, vcc, s1, v48
	global_load_dwordx4 v[102:105], v[16:17], off
	global_load_dwordx4 v[98:101], v[18:19], off
	s_nop 0
	global_load_dwordx4 v[16:19], v[46:47], off offset:-4096
	s_nop 0
	global_load_dwordx4 v[44:47], v[46:47], off
	v_addc_co_u32_e32 v51, vcc, 0, v49, vcc
	v_add_co_u32_e32 v56, vcc, 0x5000, v48
	s_nop 1
	v_addc_co_u32_e32 v57, vcc, 0, v49, vcc
	global_load_dwordx4 v[52:55], v[50:51], off
	global_load_dwordx4 v[58:61], v[56:57], off
	v_add_co_u32_e32 v50, vcc, 0x9000, v48
	s_nop 1
	v_addc_co_u32_e32 v51, vcc, 0, v49, vcc
	v_add_co_u32_e32 v48, vcc, 0xd000, v48
	s_nop 1
	v_addc_co_u32_e32 v49, vcc, 0, v49, vcc
	global_load_dwordx4 v[66:69], v[50:51], off
	global_load_dwordx4 v[72:75], v[48:49], off
	s_and_saveexec_b64 s[14:15], s[8:9]
	s_cbranch_execz .LBB0_355
	s_ashr_i32 s13, s12, 31
	v_or_b32_e32 v48, s0, v198
	v_mov_b32_e32 v49, 0
	v_lshlrev_b64 v[48:49], 2, v[48:49]
	s_lshl_b64 s[0:1], s[12:13], 13
	v_or_b32_e32 v49, s1, v49
	v_or_b32_e32 v48, s0, v48
	v_lshl_add_u64 v[50:51], s[72:73], 0, v[48:49]
	v_lshl_add_u64 v[48:49], s[74:75], 0, v[48:49]
	global_load_dword v129, v[48:49], off
	global_load_dword v135, v[50:51], off

.LBB0_374:
	v_bfe_u32 v127, v132, 6, 2
	s_movk_i32 s4, 0x100
	v_lshlrev_b32_e32 v116, 4, v127
	v_mov_b32_e32 v96, s38
	v_cmp_gt_u32_e32 vcc, s4, v132
	v_or_b32_e32 v97, v116, v142
	v_and_b32_e32 v120, 48, v132
	v_cndmask_b32_e32 v96, 0, v96, vcc
	v_mul_u32_u24_e32 v97, 0x110, v97
	v_add_u32_e32 v128, 0, v120
	s_waitcnt lgkmcnt(0)
	s_barrier
	v_lshrrev_b32_e32 v121, 4, v143
	v_lshlrev_b32_e32 v122, 2, v142
	v_lshlrev_b32_e32 v130, 1, v142
	v_lshlrev_b32_e32 v119, 2, v121
	v_lshrrev_b32_e32 v116, 6, v198
	v_and_b32_e32 v128, 15, v198
	v_readfirstlane_b32 s4, v116
	v_bfe_u32 v133, v198, 4, 2
	s_and_b32 s5, s4, 3
	s_lshr_b32 s6, s4, 2
	s_movk_i32 s7, 272
	v_lshlrev_b32_e32 v134, 4, v133
	v_mad_u32_u24 v117, v128, s7, v134
	s_mul_i32 s7, s5, 4352
	s_cmp_eq_u32 s6, 0
	s_cselect_b32 s10, 17408, 0
	s_add_u32 s7, s7, s10
	v_add_u32_e32 v116, s7, v117
	v_add_u32_e32 v117, 17408, v117
	ds_read_b128 v[96:99], v116 offset:0
	ds_read_b128 v[100:103], v116 offset:64
	ds_read_b128 v[104:107], v116 offset:128
	ds_read_b128 v[108:111], v116 offset:192
	s_lshl_b32 s7, s5, 6
	v_lshl_add_u32 v134, v133, 4, s7
	v_add_u32_e32 v134, 0x1f700, v134
	ds_read_b128 v[146:149], v134
	ds_read_b128 v[124:127], v134 offset:256
	v_lshlrev_b32_e32 v134, 2, v128
	v_add_u32_e32 v134, 0x1f700, v134
	ds_read_b32 v237, v134 offset:0
	ds_read_b32 v238, v134 offset:64
	ds_read_b32 v239, v134 offset:128
	ds_read_b32 v123, v134 offset:192
	s_lshl_b32 s7, s5, 4
	v_lshl_add_u32 v116, v133, 2, s7
	ds_read_b128 v[112:115], v117 offset:0
	ds_read_b128 v[136:139], v117 offset:64
	s_waitcnt lgkmcnt(1)
	v_mfma_f32_16x16x32_bf16 v[240:243], v[96:99], v[112:115], 0
	ds_read_b128 v[112:115], v117 offset:128
	s_waitcnt lgkmcnt(1)
	v_mfma_f32_16x16x32_bf16 v[240:243], v[100:103], v[136:139], v[240:243]
	ds_read_b128 v[136:139], v117 offset:192
	s_waitcnt lgkmcnt(1)
	v_mfma_f32_16x16x32_bf16 v[240:243], v[104:107], v[112:115], v[240:243]
	s_waitcnt lgkmcnt(0)
	v_mfma_f32_16x16x32_bf16 v[240:243], v[108:111], v[136:139], v[240:243]
	s_cmp_lt_u32 s5, 1
	s_cbranch_scc1 .Ls2_skip1
	ds_read_b128 v[112:115], v117 offset:4352
	ds_read_b128 v[136:139], v117 offset:4416
	s_waitcnt lgkmcnt(1)
	v_mfma_f32_16x16x32_bf16 v[244:247], v[96:99], v[112:115], 0
	ds_read_b128 v[112:115], v117 offset:4480
	s_waitcnt lgkmcnt(1)
	v_mfma_f32_16x16x32_bf16 v[244:247], v[100:103], v[136:139], v[244:247]
	ds_read_b128 v[136:139], v117 offset:4544
	s_waitcnt lgkmcnt(1)
	v_mfma_f32_16x16x32_bf16 v[244:247], v[104:107], v[112:115], v[244:247]
	s_waitcnt lgkmcnt(0)
	v_mfma_f32_16x16x32_bf16 v[244:247], v[108:111], v[136:139], v[244:247]
	s_branch .Ls2_done1
.Ls2_skip1:
	v_mov_b32_e32 v244, 0
	v_mov_b32_e32 v245, 0
	v_mov_b32_e32 v246, 0
	v_mov_b32_e32 v247, 0
.Ls2_done1:
	s_cmp_lt_u32 s5, 2
	s_cbranch_scc1 .Ls2_skip2
	ds_read_b128 v[112:115], v117 offset:8704
	ds_read_b128 v[136:139], v117 offset:8768
	s_waitcnt lgkmcnt(1)
	v_mfma_f32_16x16x32_bf16 v[248:251], v[96:99], v[112:115], 0
	ds_read_b128 v[112:115], v117 offset:8832
	s_waitcnt lgkmcnt(1)
	v_mfma_f32_16x16x32_bf16 v[248:251], v[100:103], v[136:139], v[248:251]
	ds_read_b128 v[136:139], v117 offset:8896
	s_waitcnt lgkmcnt(1)
	v_mfma_f32_16x16x32_bf16 v[248:251], v[104:107], v[112:115], v[248:251]
	s_waitcnt lgkmcnt(0)
	v_mfma_f32_16x16x32_bf16 v[248:251], v[108:111], v[136:139], v[248:251]
	s_branch .Ls2_done2
.Ls2_skip2:
	v_mov_b32_e32 v248, 0
	v_mov_b32_e32 v249, 0
	v_mov_b32_e32 v250, 0
	v_mov_b32_e32 v251, 0
.Ls2_done2:
	s_cmp_lt_u32 s5, 3
	s_cbranch_scc1 .Ls2_skip3
	ds_read_b128 v[112:115], v117 offset:13056
	ds_read_b128 v[136:139], v117 offset:13120
	s_waitcnt lgkmcnt(1)
	v_mfma_f32_16x16x32_bf16 v[252:255], v[96:99], v[112:115], 0
	ds_read_b128 v[112:115], v117 offset:13184
	s_waitcnt lgkmcnt(1)
	v_mfma_f32_16x16x32_bf16 v[252:255], v[100:103], v[136:139], v[252:255]
	ds_read_b128 v[136:139], v117 offset:13248
	s_waitcnt lgkmcnt(1)
	v_mfma_f32_16x16x32_bf16 v[252:255], v[104:107], v[112:115], v[252:255]
	s_waitcnt lgkmcnt(0)
	v_mfma_f32_16x16x32_bf16 v[252:255], v[108:111], v[136:139], v[252:255]
	s_branch .Ls2_done3
.Ls2_skip3:
	v_mov_b32_e32 v252, 0
	v_mov_b32_e32 v253, 0
	v_mov_b32_e32 v254, 0
	v_mov_b32_e32 v255, 0
.Ls2_done3:
	s_waitcnt lgkmcnt(0)
	v_sub_u32_e32 v134, v116, v128
	s_nop 7
	s_cmp_eq_u32 s6, 0
	s_cbranch_scc0 .Ls2_intra
	s_movk_i32 s7, 260
	v_mul_u32_u24_e32 v116, s7, v116
	v_lshl_add_u32 v116, v128, 2, v116
	v_add_u32_e32 v116, 0x11000, v116
	v_sub_f32_e32 v96, v146, v237
	v_sub_f32_e32 v97, v146, v238
	v_sub_f32_e32 v98, v146, v239
	v_sub_f32_e32 v99, v146, v123
	v_mul_f32_e32 v96, 0x3fb8aa3b, v96
	v_mul_f32_e32 v97, 0x3fb8aa3b, v97
	v_mul_f32_e32 v98, 0x3fb8aa3b, v98
	v_mul_f32_e32 v99, 0x3fb8aa3b, v99
	v_exp_f32_e32 v96, v96
	v_exp_f32_e32 v97, v97
	v_exp_f32_e32 v98, v98
	v_exp_f32_e32 v99, v99
	v_mul_f32_e32 v240, v124, v240
	v_mul_f32_e32 v244, v124, v244
	v_mul_f32_e32 v248, v124, v248
	v_mul_f32_e32 v252, v124, v252
	v_cmp_gt_i32_e64 vcc, v134, 0
	v_cmp_gt_i32_e64 s[4:5], v134, 16
	v_cmp_gt_i32_e64 s[6:7], v134, 32
	v_cmp_gt_i32_e64 s[10:11], v134, 48
	v_mul_f32_e32 v96, v240, v96
	v_mul_f32_e32 v97, v244, v97
	v_mul_f32_e32 v98, v248, v98
	v_mul_f32_e32 v99, v252, v99
	v_cndmask_b32_e64 v96, 0, v96, vcc
	v_cndmask_b32_e64 v97, 0, v97, s[4:5]
	v_cndmask_b32_e64 v98, 0, v98, s[6:7]
	v_cndmask_b32_e64 v99, 0, v99, s[10:11]
	ds_write_b32 v116, v96 offset:0
	ds_write_b32 v116, v97 offset:64
	ds_write_b32 v116, v98 offset:128
	ds_write_b32 v116, v99 offset:192
	v_sub_f32_e32 v100, v147, v237
	v_sub_f32_e32 v101, v147, v238
	v_sub_f32_e32 v102, v147, v239
	v_sub_f32_e32 v103, v147, v123
	v_mul_f32_e32 v100, 0x3fb8aa3b, v100
	v_mul_f32_e32 v101, 0x3fb8aa3b, v101
	v_mul_f32_e32 v102, 0x3fb8aa3b, v102
	v_mul_f32_e32 v103, 0x3fb8aa3b, v103
	v_exp_f32_e32 v100, v100
	v_exp_f32_e32 v101, v101
	v_exp_f32_e32 v102, v102
	v_exp_f32_e32 v103, v103
	v_mul_f32_e32 v241, v125, v241
	v_mul_f32_e32 v245, v125, v245
	v_mul_f32_e32 v249, v125, v249
	v_mul_f32_e32 v253, v125, v253
	v_cmp_gt_i32_e64 vcc, v134, -1
	v_cmp_gt_i32_e64 s[4:5], v134, 15
	v_cmp_gt_i32_e64 s[6:7], v134, 31
	v_cmp_gt_i32_e64 s[10:11], v134, 47
	v_mul_f32_e32 v100, v241, v100
	v_mul_f32_e32 v101, v245, v101
	v_mul_f32_e32 v102, v249, v102
	v_mul_f32_e32 v103, v253, v103
	v_cndmask_b32_e64 v100, 0, v100, vcc
	v_cndmask_b32_e64 v101, 0, v101, s[4:5]
	v_cndmask_b32_e64 v102, 0, v102, s[6:7]
	v_cndmask_b32_e64 v103, 0, v103, s[10:11]
	ds_write_b32 v116, v100 offset:260
	ds_write_b32 v116, v101 offset:324
	ds_write_b32 v116, v102 offset:388
	ds_write_b32 v116, v103 offset:452
	v_sub_f32_e32 v104, v148, v237
	v_sub_f32_e32 v105, v148, v238
	v_sub_f32_e32 v106, v148, v239
	v_sub_f32_e32 v107, v148, v123
	v_mul_f32_e32 v104, 0x3fb8aa3b, v104
	v_mul_f32_e32 v105, 0x3fb8aa3b, v105
	v_mul_f32_e32 v106, 0x3fb8aa3b, v106
	v_mul_f32_e32 v107, 0x3fb8aa3b, v107
	v_exp_f32_e32 v104, v104
	v_exp_f32_e32 v105, v105
	v_exp_f32_e32 v106, v106
	v_exp_f32_e32 v107, v107
	v_mul_f32_e32 v242, v126, v242
	v_mul_f32_e32 v246, v126, v246
	v_mul_f32_e32 v250, v126, v250
	v_mul_f32_e32 v254, v126, v254
	v_cmp_gt_i32_e64 vcc, v134, -2
	v_cmp_gt_i32_e64 s[4:5], v134, 14
	v_cmp_gt_i32_e64 s[6:7], v134, 30
	v_cmp_gt_i32_e64 s[10:11], v134, 46
	v_mul_f32_e32 v104, v242, v104
	v_mul_f32_e32 v105, v246, v105
	v_mul_f32_e32 v106, v250, v106
	v_mul_f32_e32 v107, v254, v107
	v_cndmask_b32_e64 v104, 0, v104, vcc
	v_cndmask_b32_e64 v105, 0, v105, s[4:5]
	v_cndmask_b32_e64 v106, 0, v106, s[6:7]
	v_cndmask_b32_e64 v107, 0, v107, s[10:11]
	ds_write_b32 v116, v104 offset:520
	ds_write_b32 v116, v105 offset:584
	ds_write_b32 v116, v106 offset:648
	ds_write_b32 v116, v107 offset:712
	v_sub_f32_e32 v108, v149, v237
	v_sub_f32_e32 v109, v149, v238
	v_sub_f32_e32 v110, v149, v239
	v_sub_f32_e32 v111, v149, v123
	v_mul_f32_e32 v108, 0x3fb8aa3b, v108
	v_mul_f32_e32 v109, 0x3fb8aa3b, v109
	v_mul_f32_e32 v110, 0x3fb8aa3b, v110
	v_mul_f32_e32 v111, 0x3fb8aa3b, v111
	v_exp_f32_e32 v108, v108
	v_exp_f32_e32 v109, v109
	v_exp_f32_e32 v110, v110
	v_exp_f32_e32 v111, v111
	v_mul_f32_e32 v243, v127, v243
	v_mul_f32_e32 v247, v127, v247
	v_mul_f32_e32 v251, v127, v251
	v_mul_f32_e32 v255, v127, v255
	v_cmp_gt_i32_e64 vcc, v134, -3
	v_cmp_gt_i32_e64 s[4:5], v134, 13
	v_cmp_gt_i32_e64 s[6:7], v134, 29
	v_cmp_gt_i32_e64 s[10:11], v134, 45
	v_mul_f32_e32 v108, v243, v108
	v_mul_f32_e32 v109, v247, v109
	v_mul_f32_e32 v110, v251, v110
	v_mul_f32_e32 v111, v255, v111
	v_cndmask_b32_e64 v108, 0, v108, vcc
	v_cndmask_b32_e64 v109, 0, v109, s[4:5]
	v_cndmask_b32_e64 v110, 0, v110, s[6:7]
	v_cndmask_b32_e64 v111, 0, v111, s[10:11]
	ds_write_b32 v116, v108 offset:780
	ds_write_b32 v116, v109 offset:844
	ds_write_b32 v116, v110 offset:908
	ds_write_b32 v116, v111 offset:972
	s_branch .Ls2_end
.Ls2_intra:
	s_ashr_i32 s7, s24, 8
	s_lshl_b32 s7, s7, 11
	s_and_b32 s10, s24, 31
	s_lshl_b32 s10, s10, 6
	s_add_u32 s7, s7, s10
	s_lshl_b32 s7, s7, 12
	s_lshl_b32 s10, s68, 7
	s_add_u32 s7, s7, s10
	s_add_u32 s8, s50, s7
	s_addc_u32 s9, s51, 0
	v_lshlrev_b32_e32 v116, 12, v116
	v_lshl_add_u32 v116, v128, 1, v116
	s_add_u32 s10, s8, 0x0
	s_addc_u32 s11, s9, 0
	v_sub_f32_e32 v96, v146, v237
	v_sub_f32_e32 v97, v146, v238
	v_sub_f32_e32 v98, v146, v239
	v_sub_f32_e32 v99, v146, v123
	v_mul_f32_e32 v96, 0x3fb8aa3b, v96
	v_mul_f32_e32 v97, 0x3fb8aa3b, v97
	v_mul_f32_e32 v98, 0x3fb8aa3b, v98
	v_mul_f32_e32 v99, 0x3fb8aa3b, v99
	v_exp_f32_e32 v96, v96
	v_exp_f32_e32 v97, v97
	v_exp_f32_e32 v98, v98
	v_exp_f32_e32 v99, v99
	v_cmp_ge_i32_e64 vcc, v134, 0
	v_cmp_ge_i32_e64 s[4:5], v134, 16
	v_cmp_ge_i32_e64 s[6:7], v134, 32
	v_mul_f32_e32 v96, v240, v96
	v_mul_f32_e32 v97, v244, v97
	v_mul_f32_e32 v98, v248, v98
	v_mul_f32_e32 v99, v252, v99
	v_cndmask_b32_e64 v96, 0, v96, vcc
	v_cndmask_b32_e64 v97, 0, v97, s[4:5]
	v_cndmask_b32_e64 v98, 0, v98, s[6:7]
	v_cmp_ge_i32_e64 vcc, v134, 48
	v_cvt_pk_bf16_f32 v96, v96, 0
	v_cvt_pk_bf16_f32 v97, v97, 0
	v_cvt_pk_bf16_f32 v98, v98, 0
	v_cndmask_b32_e64 v99, 0, v99, vcc
	v_cvt_pk_bf16_f32 v99, v99, 0
	global_store_short v116, v96, s[10:11] offset:0
	global_store_short v116, v97, s[10:11] offset:32
	global_store_short v116, v98, s[10:11] offset:64
	global_store_short v116, v99, s[10:11] offset:96
	s_add_u32 s10, s8, 0x1000
	s_addc_u32 s11, s9, 0
	v_sub_f32_e32 v100, v147, v237
	v_sub_f32_e32 v101, v147, v238
	v_sub_f32_e32 v102, v147, v239
	v_sub_f32_e32 v103, v147, v123
	v_mul_f32_e32 v100, 0x3fb8aa3b, v100
	v_mul_f32_e32 v101, 0x3fb8aa3b, v101
	v_mul_f32_e32 v102, 0x3fb8aa3b, v102
	v_mul_f32_e32 v103, 0x3fb8aa3b, v103
	v_exp_f32_e32 v100, v100
	v_exp_f32_e32 v101, v101
	v_exp_f32_e32 v102, v102
	v_exp_f32_e32 v103, v103
	v_cmp_ge_i32_e64 vcc, v134, -1
	v_cmp_ge_i32_e64 s[4:5], v134, 15
	v_cmp_ge_i32_e64 s[6:7], v134, 31
	v_mul_f32_e32 v100, v241, v100
	v_mul_f32_e32 v101, v245, v101
	v_mul_f32_e32 v102, v249, v102
	v_mul_f32_e32 v103, v253, v103
	v_cndmask_b32_e64 v100, 0, v100, vcc
	v_cndmask_b32_e64 v101, 0, v101, s[4:5]
	v_cndmask_b32_e64 v102, 0, v102, s[6:7]
	v_cmp_ge_i32_e64 vcc, v134, 47
	v_cvt_pk_bf16_f32 v100, v100, 0
	v_cvt_pk_bf16_f32 v101, v101, 0
	v_cvt_pk_bf16_f32 v102, v102, 0
	v_cndmask_b32_e64 v103, 0, v103, vcc
	v_cvt_pk_bf16_f32 v103, v103, 0
	global_store_short v116, v100, s[10:11] offset:0
	global_store_short v116, v101, s[10:11] offset:32
	global_store_short v116, v102, s[10:11] offset:64
	global_store_short v116, v103, s[10:11] offset:96
	s_add_u32 s10, s8, 0x2000
	s_addc_u32 s11, s9, 0
	v_sub_f32_e32 v104, v148, v237
	v_sub_f32_e32 v105, v148, v238
	v_sub_f32_e32 v106, v148, v239
	v_sub_f32_e32 v107, v148, v123
	v_mul_f32_e32 v104, 0x3fb8aa3b, v104
	v_mul_f32_e32 v105, 0x3fb8aa3b, v105
	v_mul_f32_e32 v106, 0x3fb8aa3b, v106
	v_mul_f32_e32 v107, 0x3fb8aa3b, v107
	v_exp_f32_e32 v104, v104
	v_exp_f32_e32 v105, v105
	v_exp_f32_e32 v106, v106
	v_exp_f32_e32 v107, v107
	v_cmp_ge_i32_e64 vcc, v134, -2
	v_cmp_ge_i32_e64 s[4:5], v134, 14
	v_cmp_ge_i32_e64 s[6:7], v134, 30
	v_mul_f32_e32 v104, v242, v104
	v_mul_f32_e32 v105, v246, v105
	v_mul_f32_e32 v106, v250, v106
	v_mul_f32_e32 v107, v254, v107
	v_cndmask_b32_e64 v104, 0, v104, vcc
	v_cndmask_b32_e64 v105, 0, v105, s[4:5]
	v_cndmask_b32_e64 v106, 0, v106, s[6:7]
	v_cmp_ge_i32_e64 vcc, v134, 46
	v_cvt_pk_bf16_f32 v104, v104, 0
	v_cvt_pk_bf16_f32 v105, v105, 0
	v_cvt_pk_bf16_f32 v106, v106, 0
	v_cndmask_b32_e64 v107, 0, v107, vcc
	v_cvt_pk_bf16_f32 v107, v107, 0
	global_store_short v116, v104, s[10:11] offset:0
	global_store_short v116, v105, s[10:11] offset:32
	global_store_short v116, v106, s[10:11] offset:64
	global_store_short v116, v107, s[10:11] offset:96
	s_add_u32 s10, s8, 0x3000
	s_addc_u32 s11, s9, 0
	v_sub_f32_e32 v108, v149, v237
	v_sub_f32_e32 v109, v149, v238
	v_sub_f32_e32 v110, v149, v239
	v_sub_f32_e32 v111, v149, v123
	v_mul_f32_e32 v108, 0x3fb8aa3b, v108
	v_mul_f32_e32 v109, 0x3fb8aa3b, v109
	v_mul_f32_e32 v110, 0x3fb8aa3b, v110
	v_mul_f32_e32 v111, 0x3fb8aa3b, v111
	v_exp_f32_e32 v108, v108
	v_exp_f32_e32 v109, v109
	v_exp_f32_e32 v110, v110
	v_exp_f32_e32 v111, v111
	v_cmp_ge_i32_e64 vcc, v134, -3
	v_cmp_ge_i32_e64 s[4:5], v134, 13
	v_cmp_ge_i32_e64 s[6:7], v134, 29
	v_mul_f32_e32 v108, v243, v108
	v_mul_f32_e32 v109, v247, v109
	v_mul_f32_e32 v110, v251, v110
	v_mul_f32_e32 v111, v255, v111
	v_cndmask_b32_e64 v108, 0, v108, vcc
	v_cndmask_b32_e64 v109, 0, v109, s[4:5]
	v_cndmask_b32_e64 v110, 0, v110, s[6:7]
	v_cmp_ge_i32_e64 vcc, v134, 45
	v_cvt_pk_bf16_f32 v108, v108, 0
	v_cvt_pk_bf16_f32 v109, v109, 0
	v_cvt_pk_bf16_f32 v110, v110, 0
	v_cndmask_b32_e64 v111, 0, v111, vcc
	v_cvt_pk_bf16_f32 v111, v111, 0
	global_store_short v116, v108, s[10:11] offset:0
	global_store_short v116, v109, s[10:11] offset:32
	global_store_short v116, v110, s[10:11] offset:64
	global_store_short v116, v111, s[10:11] offset:96
.Ls2_end:
	s_waitcnt lgkmcnt(0)
	s_barrier
	s_and_saveexec_b64 s[4:5], s[2:3]
	s_cbranch_execz .LBB0_510
	s_waitcnt lgkmcnt(0)
	v_lshrrev_b32_e32 v252, 4, v198
	s_movk_i32 s8, 0x1080
	v_mul_u32_u24_e32 v252, s8, v252
	v_and_b32_e32 v254, 15, v198
	v_lshl_add_u32 v253, v254, 2, v252
	v_add_u32_e32 v253, 0x15100, v253
	v_add_u32_e32 v252, 0x11000, v252
	ds_read_b32 v237, v252 offset:260
	ds_read_b32 v238, v252 offset:520
	ds_read_b32 v239, v252 offset:780
	ds_read_b32 v240, v252 offset:1040
	ds_read_b32 v241, v252 offset:1300
	ds_read_b32 v242, v252 offset:1560
	ds_read_b32 v243, v252 offset:1820
	ds_read_b32 v244, v252 offset:2080
	ds_read_b32 v245, v252 offset:2340
	ds_read_b32 v246, v252 offset:2600
	ds_read_b32 v247, v252 offset:2860
	ds_read_b32 v248, v252 offset:3120
	ds_read_b32 v249, v252 offset:3380
	ds_read_b32 v250, v252 offset:3640
	ds_read_b32 v251, v252 offset:3900
	v_cmp_eq_u32_e32 vcc, 0, v254
	s_nop 1
	v_cndmask_b32_e64 v96, 0, 1.0, vcc
	v_cmp_eq_u32_e32 vcc, 1, v254
	s_nop 1
	v_cndmask_b32_e64 v97, 0, 1.0, vcc
	v_cmp_eq_u32_e32 vcc, 2, v254
	s_nop 1
	v_cndmask_b32_e64 v98, 0, 1.0, vcc
	v_cmp_eq_u32_e32 vcc, 3, v254
	s_nop 1
	v_cndmask_b32_e64 v99, 0, 1.0, vcc
	v_cmp_eq_u32_e32 vcc, 4, v254
	s_nop 1
	v_cndmask_b32_e64 v100, 0, 1.0, vcc
	v_cmp_eq_u32_e32 vcc, 5, v254
	s_nop 1
	v_cndmask_b32_e64 v101, 0, 1.0, vcc
	v_cmp_eq_u32_e32 vcc, 6, v254
	s_nop 1
	v_cndmask_b32_e64 v102, 0, 1.0, vcc
	v_cmp_eq_u32_e32 vcc, 7, v254
	s_nop 1
	v_cndmask_b32_e64 v103, 0, 1.0, vcc
	v_cmp_eq_u32_e32 vcc, 8, v254
	s_nop 1
	v_cndmask_b32_e64 v104, 0, 1.0, vcc
	v_cmp_eq_u32_e32 vcc, 9, v254
	s_nop 1
	v_cndmask_b32_e64 v105, 0, 1.0, vcc
	v_cmp_eq_u32_e32 vcc, 10, v254
	s_nop 1
	v_cndmask_b32_e64 v106, 0, 1.0, vcc
	v_cmp_eq_u32_e32 vcc, 11, v254
	s_nop 1
	v_cndmask_b32_e64 v107, 0, 1.0, vcc
	v_cmp_eq_u32_e32 vcc, 12, v254
	s_nop 1
	v_cndmask_b32_e64 v108, 0, 1.0, vcc
	v_cmp_eq_u32_e32 vcc, 13, v254
	s_nop 1
	v_cndmask_b32_e64 v109, 0, 1.0, vcc
	v_cmp_eq_u32_e32 vcc, 14, v254
	s_nop 1
	v_cndmask_b32_e64 v110, 0, 1.0, vcc
	v_cmp_eq_u32_e32 vcc, 15, v254
	s_nop 1
	v_cndmask_b32_e64 v111, 0, 1.0, vcc
	s_waitcnt lgkmcnt(0)
	ds_read_b32 v112, v252 offset:524
	ds_read_b32 v113, v252 offset:784
	ds_read_b32 v114, v252 offset:1044
	ds_read_b32 v115, v252 offset:1304
	ds_read_b32 v116, v252 offset:1564
	ds_read_b32 v117, v252 offset:1824
	ds_read_b32 v123, v252 offset:2084
	ds_read_b32 v124, v252 offset:2344
	ds_read_b32 v125, v252 offset:2604
	ds_read_b32 v126, v252 offset:2864
	ds_read_b32 v127, v252 offset:3124
	ds_read_b32 v128, v252 offset:3384
	ds_read_b32 v133, v252 offset:3644
	ds_read_b32 v134, v252 offset:3904
	v_fma_f32 v97, -v96, v237, v97
	v_fma_f32 v98, -v96, v238, v98
	v_fma_f32 v99, -v96, v239, v99
	v_fma_f32 v100, -v96, v240, v100
	v_fma_f32 v101, -v96, v241, v101
	v_fma_f32 v102, -v96, v242, v102
	v_fma_f32 v103, -v96, v243, v103
	v_fma_f32 v104, -v96, v244, v104
	v_fma_f32 v105, -v96, v245, v105
	v_fma_f32 v106, -v96, v246, v106
	v_fma_f32 v107, -v96, v247, v107
	v_fma_f32 v108, -v96, v248, v108
	v_fma_f32 v109, -v96, v249, v109
	v_fma_f32 v110, -v96, v250, v110
	v_fma_f32 v111, -v96, v251, v111
	s_waitcnt lgkmcnt(0)
	ds_read_b32 v237, v252 offset:788
	ds_read_b32 v238, v252 offset:1048
	ds_read_b32 v239, v252 offset:1308
	ds_read_b32 v240, v252 offset:1568
	ds_read_b32 v241, v252 offset:1828
	ds_read_b32 v242, v252 offset:2088
	ds_read_b32 v243, v252 offset:2348
	ds_read_b32 v244, v252 offset:2608
	ds_read_b32 v245, v252 offset:2868
	ds_read_b32 v246, v252 offset:3128
	ds_read_b32 v247, v252 offset:3388
	ds_read_b32 v248, v252 offset:3648
	ds_read_b32 v249, v252 offset:3908
	v_fma_f32 v98, -v97, v112, v98
	v_fma_f32 v99, -v97, v113, v99
	v_fma_f32 v100, -v97, v114, v100
	v_fma_f32 v101, -v97, v115, v101
	v_fma_f32 v102, -v97, v116, v102
	v_fma_f32 v103, -v97, v117, v103
	v_fma_f32 v104, -v97, v123, v104
	v_fma_f32 v105, -v97, v124, v105
	v_fma_f32 v106, -v97, v125, v106
	v_fma_f32 v107, -v97, v126, v107
	v_fma_f32 v108, -v97, v127, v108
	v_fma_f32 v109, -v97, v128, v109
	v_fma_f32 v110, -v97, v133, v110
	v_fma_f32 v111, -v97, v134, v111
	s_waitcnt lgkmcnt(0)
	ds_read_b32 v112, v252 offset:1052
	ds_read_b32 v113, v252 offset:1312
	ds_read_b32 v114, v252 offset:1572
	ds_read_b32 v115, v252 offset:1832
	ds_read_b32 v116, v252 offset:2092
	ds_read_b32 v117, v252 offset:2352
	ds_read_b32 v123, v252 offset:2612
	ds_read_b32 v124, v252 offset:2872
	ds_read_b32 v125, v252 offset:3132
	ds_read_b32 v126, v252 offset:3392
	ds_read_b32 v127, v252 offset:3652
	ds_read_b32 v128, v252 offset:3912
	v_fma_f32 v99, -v98, v237, v99
	v_fma_f32 v100, -v98, v238, v100
	v_fma_f32 v101, -v98, v239, v101
	v_fma_f32 v102, -v98, v240, v102
	v_fma_f32 v103, -v98, v241, v103
	v_fma_f32 v104, -v98, v242, v104
	v_fma_f32 v105, -v98, v243, v105
	v_fma_f32 v106, -v98, v244, v106
	v_fma_f32 v107, -v98, v245, v107
	v_fma_f32 v108, -v98, v246, v108
	v_fma_f32 v109, -v98, v247, v109
	v_fma_f32 v110, -v98, v248, v110
	v_fma_f32 v111, -v98, v249, v111
	s_waitcnt lgkmcnt(0)
	ds_read_b32 v237, v252 offset:1316
	ds_read_b32 v238, v252 offset:1576
	ds_read_b32 v239, v252 offset:1836
	ds_read_b32 v240, v252 offset:2096
	ds_read_b32 v241, v252 offset:2356
	ds_read_b32 v242, v252 offset:2616
	ds_read_b32 v243, v252 offset:2876
	ds_read_b32 v244, v252 offset:3136
	ds_read_b32 v245, v252 offset:3396
	ds_read_b32 v246, v252 offset:3656
	ds_read_b32 v247, v252 offset:3916
	v_fma_f32 v100, -v99, v112, v100
	v_fma_f32 v101, -v99, v113, v101
	v_fma_f32 v102, -v99, v114, v102
	v_fma_f32 v103, -v99, v115, v103
	v_fma_f32 v104, -v99, v116, v104
	v_fma_f32 v105, -v99, v117, v105
	v_fma_f32 v106, -v99, v123, v106
	v_fma_f32 v107, -v99, v124, v107
	v_fma_f32 v108, -v99, v125, v108
	v_fma_f32 v109, -v99, v126, v109
	v_fma_f32 v110, -v99, v127, v110
	v_fma_f32 v111, -v99, v128, v111
	s_waitcnt lgkmcnt(0)
	ds_read_b32 v112, v252 offset:1580
	ds_read_b32 v113, v252 offset:1840
	ds_read_b32 v114, v252 offset:2100
	ds_read_b32 v115, v252 offset:2360
	ds_read_b32 v116, v252 offset:2620
	ds_read_b32 v117, v252 offset:2880
	ds_read_b32 v123, v252 offset:3140
	ds_read_b32 v124, v252 offset:3400
	ds_read_b32 v125, v252 offset:3660
	ds_read_b32 v126, v252 offset:3920
	v_fma_f32 v101, -v100, v237, v101
	v_fma_f32 v102, -v100, v238, v102
	v_fma_f32 v103, -v100, v239, v103
	v_fma_f32 v104, -v100, v240, v104
	v_fma_f32 v105, -v100, v241, v105
	v_fma_f32 v106, -v100, v242, v106
	v_fma_f32 v107, -v100, v243, v107
	v_fma_f32 v108, -v100, v244, v108
	v_fma_f32 v109, -v100, v245, v109
	v_fma_f32 v110, -v100, v246, v110
	v_fma_f32 v111, -v100, v247, v111
	s_waitcnt lgkmcnt(0)
	ds_read_b32 v237, v252 offset:1844
	ds_read_b32 v238, v252 offset:2104
	ds_read_b32 v239, v252 offset:2364
	ds_read_b32 v240, v252 offset:2624
	ds_read_b32 v241, v252 offset:2884
	ds_read_b32 v242, v252 offset:3144
	ds_read_b32 v243, v252 offset:3404
	ds_read_b32 v244, v252 offset:3664
	ds_read_b32 v245, v252 offset:3924
	v_fma_f32 v102, -v101, v112, v102
	v_fma_f32 v103, -v101, v113, v103
	v_fma_f32 v104, -v101, v114, v104
	v_fma_f32 v105, -v101, v115, v105
	v_fma_f32 v106, -v101, v116, v106
	v_fma_f32 v107, -v101, v117, v107
	v_fma_f32 v108, -v101, v123, v108
	v_fma_f32 v109, -v101, v124, v109
	v_fma_f32 v110, -v101, v125, v110
	v_fma_f32 v111, -v101, v126, v111
	s_waitcnt lgkmcnt(0)
	ds_read_b32 v112, v252 offset:2108
	ds_read_b32 v113, v252 offset:2368
	ds_read_b32 v114, v252 offset:2628
	ds_read_b32 v115, v252 offset:2888
	ds_read_b32 v116, v252 offset:3148
	ds_read_b32 v117, v252 offset:3408
	ds_read_b32 v123, v252 offset:3668
	ds_read_b32 v124, v252 offset:3928
	v_fma_f32 v103, -v102, v237, v103
	v_fma_f32 v104, -v102, v238, v104
	v_fma_f32 v105, -v102, v239, v105
	v_fma_f32 v106, -v102, v240, v106
	v_fma_f32 v107, -v102, v241, v107
	v_fma_f32 v108, -v102, v242, v108
	v_fma_f32 v109, -v102, v243, v109
	v_fma_f32 v110, -v102, v244, v110
	v_fma_f32 v111, -v102, v245, v111
	s_waitcnt lgkmcnt(0)
	ds_read_b32 v237, v252 offset:2372
	ds_read_b32 v238, v252 offset:2632
	ds_read_b32 v239, v252 offset:2892
	ds_read_b32 v240, v252 offset:3152
	ds_read_b32 v241, v252 offset:3412
	ds_read_b32 v242, v252 offset:3672
	ds_read_b32 v243, v252 offset:3932
	v_fma_f32 v104, -v103, v112, v104
	v_fma_f32 v105, -v103, v113, v105
	v_fma_f32 v106, -v103, v114, v106
	v_fma_f32 v107, -v103, v115, v107
	v_fma_f32 v108, -v103, v116, v108
	v_fma_f32 v109, -v103, v117, v109
	v_fma_f32 v110, -v103, v123, v110
	v_fma_f32 v111, -v103, v124, v111
	s_waitcnt lgkmcnt(0)
	ds_read_b32 v112, v252 offset:2636
	ds_read_b32 v113, v252 offset:2896
	ds_read_b32 v114, v252 offset:3156
	ds_read_b32 v115, v252 offset:3416
	ds_read_b32 v116, v252 offset:3676
	ds_read_b32 v117, v252 offset:3936
	v_fma_f32 v105, -v104, v237, v105
	v_fma_f32 v106, -v104, v238, v106
	v_fma_f32 v107, -v104, v239, v107
	v_fma_f32 v108, -v104, v240, v108
	v_fma_f32 v109, -v104, v241, v109
	v_fma_f32 v110, -v104, v242, v110
	v_fma_f32 v111, -v104, v243, v111
	s_waitcnt lgkmcnt(0)
	ds_read_b32 v237, v252 offset:2900
	ds_read_b32 v238, v252 offset:3160
	ds_read_b32 v239, v252 offset:3420
	ds_read_b32 v240, v252 offset:3680
	ds_read_b32 v241, v252 offset:3940
	v_fma_f32 v106, -v105, v112, v106
	v_fma_f32 v107, -v105, v113, v107
	v_fma_f32 v108, -v105, v114, v108
	v_fma_f32 v109, -v105, v115, v109
	v_fma_f32 v110, -v105, v116, v110
	v_fma_f32 v111, -v105, v117, v111
	s_waitcnt lgkmcnt(0)
	ds_read_b32 v112, v252 offset:3164
	ds_read_b32 v113, v252 offset:3424
	ds_read_b32 v114, v252 offset:3684
	ds_read_b32 v115, v252 offset:3944
	v_fma_f32 v107, -v106, v237, v107
	v_fma_f32 v108, -v106, v238, v108
	v_fma_f32 v109, -v106, v239, v109
	v_fma_f32 v110, -v106, v240, v110
	v_fma_f32 v111, -v106, v241, v111
	s_waitcnt lgkmcnt(0)
	ds_read_b32 v237, v252 offset:3428
	ds_read_b32 v238, v252 offset:3688
	ds_read_b32 v239, v252 offset:3948
	v_fma_f32 v108, -v107, v112, v108
	v_fma_f32 v109, -v107, v113, v109
	v_fma_f32 v110, -v107, v114, v110
	v_fma_f32 v111, -v107, v115, v111
	s_waitcnt lgkmcnt(0)
	ds_read_b32 v112, v252 offset:3692
	ds_read_b32 v113, v252 offset:3952
	v_fma_f32 v109, -v108, v237, v109
	v_fma_f32 v110, -v108, v238, v110
	v_fma_f32 v111, -v108, v239, v111
	s_waitcnt lgkmcnt(0)
	ds_read_b32 v237, v252 offset:3956
	v_fma_f32 v110, -v109, v112, v110
	v_fma_f32 v111, -v109, v113, v111
	s_waitcnt lgkmcnt(0)
	v_fma_f32 v111, -v110, v237, v111
	ds_write_b32 v253, v96 offset:0
	ds_write_b32 v253, v97 offset:260
	ds_write_b32 v253, v98 offset:520
	ds_write_b32 v253, v99 offset:780
	ds_write_b32 v253, v100 offset:1040
	ds_write_b32 v253, v101 offset:1300
	ds_write_b32 v253, v102 offset:1560
	ds_write_b32 v253, v103 offset:1820
	ds_write_b32 v253, v104 offset:2080
	ds_write_b32 v253, v105 offset:2340
	ds_write_b32 v253, v106 offset:2600
	ds_write_b32 v253, v107 offset:2860
	ds_write_b32 v253, v108 offset:3120
	ds_write_b32 v253, v109 offset:3380
	ds_write_b32 v253, v110 offset:3640
	ds_write_b32 v253, v111 offset:3900

.LBB0_585:
	s_or_b64 exec, exec, s[4:5]
	s_lshr_b32 s1, s96, 5
	s_and_b32 s1, s1, 7
	s_lshl_b32 s1, s1, 7
	s_and_b32 s38, s96, 7
	s_lshl_b32 s38, s38, 25
	s_mov_b32 s39, 0
	v_mbcnt_lo_u32_b32 v165, -1, 0
	v_mbcnt_hi_u32_b32 v165, -1, v165
	v_mov_b32_e32 v167, 64
	v_xor_b32_e32 v199, 1, v165
	v_lshlrev_b32_e32 v199, 2, v199
	v_xor_b32_e32 v200, 2, v165
	v_lshlrev_b32_e32 v200, 2, v200
	v_xor_b32_e32 v201, 16, v165
	v_lshlrev_b32_e32 v201, 2, v201
	v_xor_b32_e32 v202, 32, v165
	v_lshlrev_b32_e32 v202, 2, v202
	v_cmp_gt_u32_e32 vcc, 64, v198
	s_nop 3
	s_and_saveexec_b64 s[2:3], vcc
	v_readlane_b32 s8, v236, 22
	v_readlane_b32 s22, v236, 36
	v_readlane_b32 s23, v236, 37
	v_readlane_b32 s14, v236, 28
	v_readlane_b32 s15, v236, 29
	v_readlane_b32 s20, v236, 34
	v_readlane_b32 s21, v236, 35
	s_mov_b64 s[82:83], s[22:23]
	s_xor_b64 s[2:3], exec, s[2:3]
	s_mov_b64 s[80:81], s[20:21]
	s_mov_b64 s[74:75], s[14:15]
	v_readlane_b32 s9, v236, 23
	v_readlane_b32 s10, v236, 24
	v_readlane_b32 s11, v236, 25
	v_readlane_b32 s12, v236, 26
	v_readlane_b32 s13, v236, 27
	v_readlane_b32 s16, v236, 30
	v_readlane_b32 s17, v236, 31
	v_readlane_b32 s18, v236, 32
	v_readlane_b32 s19, v236, 33
	s_cbranch_execz .LBB0_667
	s_mov_b64 s[4:5], exec
	v_readlane_b32 s6, v236, 19
	v_readlane_b32 s7, v236, 20
	s_and_b64 s[6:7], s[4:5], s[6:7]
	s_mov_b64 exec, s[6:7]
	s_cbranch_execz .LBB0_666
	s_lshl_b32 s6, s0, 1
	s_or_b32 s7, s6, 1
	s_cmp_lt_u32 s0, 4
	s_cselect_b32 s8, s6, s0
	s_cselect_b32 s0, s7, s0
	s_and_b32 s12, s34, 0xffffff8
	s_lshl_b64 s[6:7], s[42:43], 2
	s_add_u32 s6, s80, s6
	s_addc_u32 s7, s81, s7
	s_add_i32 s8, s12, s8
	s_lshl_b32 s10, s8, 6
	s_mov_b32 s11, 0
	s_lshl_b64 s[8:9], s[10:11], 2
	s_add_u32 s8, s80, s8
	s_addc_u32 s9, s81, s9
	s_add_i32 s0, s0, s12
	s_lshl_b32 s10, s0, 6
	s_lshl_b64 s[10:11], s[10:11], 2
	s_add_u32 s10, s80, s10
	s_addc_u32 s11, s81, s11
	s_mov_b32 s0, 0x1000000
	v_mov_b32_e32 v0, 0
	s_branch .LBB0_648
